# GEMM LDS-DMA loads: 49 sites converted to SGPR-base + 32-bit VGPR offset form (drops 64-bit VALU address adds)
# speedup vs baseline: 1.0021x; 1.0021x over previous
; #define PG8_STAGE(bufoff, gbase, voff) do { _Pragma("unroll") for (int _i = 0; _i < 2; ++_i) \
;         __builtin_amdgcn_global_load_lds((const unsigned*)((const char*)(gbase) + (voff)[_i]), (PG8_LAS unsigned*)(lds + (bufoff) + ldsw + _i * 8192), 16, 0, 0); } while (0)
; #define PG8_LDA(dst, b, h) do { _Pragma("unroll") for (int m = 0; m < 4; ++m) _Pragma("unroll") for (int k = 0; k < 2; ++k) dst[m][k] = *(const PG8_LAS bf16x8*)(lds + PG8_SA(b, h) + aoff + m * 2048 + k * 1024); } while (0)
; #define PG8_LDB(dst, b, h) do { _Pragma("unroll") for (int n = 0; n < 2; ++n) _Pragma("unroll") for (int k = 0; k < 2; ++k) dst[n][k] = *(const PG8_LAS bf16x8*)(lds + PG8_SB(b, h) + boff + n * 2048 + k * 1024); } while (0)
; #define PG8_MMA(ai, bj, At, Bt) do { __builtin_amdgcn_s_setprio(1); _Pragma("unroll") for (int m = 0; m < 4; ++m) _Pragma("unroll") for (int n = 0; n < 2; ++n) _Pragma("unroll") for (int k = 0; k < 2; ++k) \
;         acc[ai][bj][m][n] = __builtin_amdgcn_mfma_f32_16x16x32_bf16(Bt[n][k], At[m][k], acc[ai][bj][m][n], 0, 0, 0); __builtin_amdgcn_s_setprio(0); } while (0)
; #define PG8_WAIT_V(n) asm volatile("s_waitcnt vmcnt(" #n ")" ::: "memory")
; #define PG8_BAR __builtin_amdgcn_s_barrier()
; template <class Epi, class Sched, bool ALIGN_EPI = false, bool SP2 = false>
; __device__ __forceinline__ void gemm_phase(PG8_LAS unsigned char* lds, const Gemm g, const Sched& S, const Epi& E, int tid_in) {
;     ...
;         for (int t = 0; t < nt; t += 2) {
;             const bool last = (t == nt - 2);
;             const char* a1 = cA + (size_t)(t + 1) * kstep;
;             const char* a2 = last ? nA : cA + (size_t)(t + 2) * kstep; const char* b2 = last ? nB : cB + (size_t)(t + 2) * kstep;
;             const char* a3 = a2 + kstep; const char* b3 = b2 + kstep;
;             if (last && has_next) S.a_ready(nxt);
;             if constexpr (SP2) {
;             PG8_LDB(B0, 0, 0); PG8_LDB(B1, 0, 1); PG8_SCHED; PG8_LDA(At, 0, 0); PG8_STAGE(PG8_SA(1, 1), a1 + hstepA, voffA);
;             PG8_WAIT_V(8); PG8_WAIT_L(0); PG8_BAR; PG8_MMA(0, 0, At, B0); PG8_MMA(0, 1, At, B1); PG8_BAR; PG8_SCHED;
;             PG8_LDA(At, 0, 1); PG8_STAGE(PG8_SB(0, 0), b2, voffB); PG8_STAGE(PG8_SB(0, 1), b2 + hstepB, voffB); PG8_STAGE(PG8_SA(0, 0), a2, voffA);
;             PG8_WAIT_V(8); PG8_WAIT_L(0); PG8_BAR; PG8_MMA(1, 0, At, B0); PG8_MMA(1, 1, At, B1); PG8_BAR; PG8_SCHED;
.LBB0_287:
	ds_read_b128 v[150:153], v168
	ds_read_b128 v[154:157], v168 offset:1024
	ds_read_b128 v[172:175], v168 offset:2048
	ds_read_b128 v[176:179], v168 offset:3072
	ds_read_b128 v[180:183], v169
	ds_read_b128 v[184:187], v169 offset:1024
	ds_read_b128 v[188:191], v169 offset:2048
	ds_read_b128 v[192:195], v169 offset:3072
	s_add_i32 s10, s3, 2
	s_add_u32 s8, s6, 0x80
	s_addc_u32 s9, s7, 0
	s_cmp_eq_u32 s66, s3
	s_cselect_b32 s9, s43, s9
	s_cselect_b32 s8, s42, s8
	s_cselect_b32 s13, s45, s2
	s_cselect_b32 s12, s44, s1
	s_add_i32 m0, s58, 0xc000
	ds_read_b128 v[196:199], v170
	ds_read_b128 v[200:203], v170 offset:1024
	ds_read_b128 v[208:211], v170 offset:2048
	ds_read_b128 v[212:215], v170 offset:3072
	ds_read_b128 v[216:219], v170 offset:4096
	ds_read_b128 v[220:223], v170 offset:5120
	ds_read_b128 v[224:227], v170 offset:6144
	ds_read_b128 v[228:231], v170 offset:7168
	global_load_lds_dwordx4 v142, s[6:7]
	s_add_i32 m0, s58, 0xe000
	s_nop 0
	global_load_lds_dwordx4 v144, s[6:7]
	s_waitcnt vmcnt(8)
	s_waitcnt lgkmcnt(0)
	s_barrier
	s_setprio 1
	s_waitcnt lgkmcnt(0)
	v_mfma_f32_16x16x32_bf16 v[124:127], v[150:153], v[196:199], v[124:127]
	v_mfma_f32_16x16x32_bf16 v[120:123], v[172:175], v[196:199], v[120:123]
	v_mfma_f32_16x16x32_bf16 v[108:111], v[150:153], v[208:211], v[108:111]
	v_mfma_f32_16x16x32_bf16 v[104:107], v[172:175], v[208:211], v[104:107]
	v_mfma_f32_16x16x32_bf16 v[92:95], v[150:153], v[216:219], v[92:95]
	v_mfma_f32_16x16x32_bf16 v[88:91], v[172:175], v[216:219], v[88:91]
	v_mfma_f32_16x16x32_bf16 v[76:79], v[150:153], v[224:227], v[76:79]
	v_mfma_f32_16x16x32_bf16 v[72:75], v[172:175], v[224:227], v[72:75]
	v_mfma_f32_16x16x32_bf16 v[124:127], v[154:157], v[200:203], v[124:127]
	v_mfma_f32_16x16x32_bf16 v[120:123], v[176:179], v[200:203], v[120:123]
	v_mfma_f32_16x16x32_bf16 v[108:111], v[154:157], v[212:215], v[108:111]
	v_mfma_f32_16x16x32_bf16 v[104:107], v[176:179], v[212:215], v[104:107]
	v_mfma_f32_16x16x32_bf16 v[92:95], v[154:157], v[220:223], v[92:95]
	v_mfma_f32_16x16x32_bf16 v[88:91], v[176:179], v[220:223], v[88:91]
	v_mfma_f32_16x16x32_bf16 v[76:79], v[154:157], v[228:231], v[76:79]
	v_mfma_f32_16x16x32_bf16 v[72:75], v[176:179], v[228:231], v[72:75]
	s_setprio 0
	s_setprio 1
	v_mfma_f32_16x16x32_bf16 v[116:119], v[180:183], v[196:199], v[116:119]
	v_mfma_f32_16x16x32_bf16 v[112:115], v[188:191], v[196:199], v[112:115]
	v_mfma_f32_16x16x32_bf16 v[100:103], v[180:183], v[208:211], v[100:103]
	v_mfma_f32_16x16x32_bf16 v[96:99], v[188:191], v[208:211], v[96:99]
	v_mfma_f32_16x16x32_bf16 v[84:87], v[180:183], v[216:219], v[84:87]
	v_mfma_f32_16x16x32_bf16 v[80:83], v[188:191], v[216:219], v[80:83]
	v_mfma_f32_16x16x32_bf16 v[68:71], v[180:183], v[224:227], v[68:71]
	v_mfma_f32_16x16x32_bf16 v[64:67], v[188:191], v[224:227], v[64:67]
	v_mfma_f32_16x16x32_bf16 v[116:119], v[184:187], v[200:203], v[116:119]
	v_mfma_f32_16x16x32_bf16 v[112:115], v[192:195], v[200:203], v[112:115]
	v_mfma_f32_16x16x32_bf16 v[100:103], v[184:187], v[212:215], v[100:103]
	v_mfma_f32_16x16x32_bf16 v[96:99], v[192:195], v[212:215], v[96:99]
	v_mfma_f32_16x16x32_bf16 v[84:87], v[184:187], v[220:223], v[84:87]
	v_mfma_f32_16x16x32_bf16 v[80:83], v[192:195], v[220:223], v[80:83]
	v_mfma_f32_16x16x32_bf16 v[68:71], v[184:187], v[228:231], v[68:71]
	v_mfma_f32_16x16x32_bf16 v[64:67], v[192:195], v[228:231], v[64:67]
	s_setprio 0
	s_barrier
	s_add_i32 s3, s71, s57
	v_lshl_add_u64 v[204:205], s[12:13], 0, v[130:131]
	s_mov_b32 m0, s3
	ds_read_b128 v[196:199], v170 offset:16384
	ds_read_b128 v[200:203], v170 offset:17408
	ds_read_b128 v[208:211], v170 offset:18432
	ds_read_b128 v[212:215], v170 offset:19456
	ds_read_b128 v[216:219], v170 offset:20480
	ds_read_b128 v[220:223], v170 offset:21504
	ds_read_b128 v[224:227], v170 offset:22528
	ds_read_b128 v[228:231], v170 offset:23552
	global_load_lds_dwordx4 v[204:205], off
	s_add_i32 m0, s3, 0x2000
	v_lshl_add_u64 v[232:233], s[12:13], 0, v[134:135]
	s_add_u32 s12, s12, s20
	s_addc_u32 s13, s13, s21
	s_add_i32 s3, s72, s57
	global_load_lds_dwordx4 v[232:233], off
	v_lshl_add_u64 v[234:235], s[12:13], 0, v[130:131]
	s_mov_b32 m0, s3
	v_lshl_add_u64 v[236:237], s[12:13], 0, v[134:135]
	global_load_lds_dwordx4 v[234:235], off
	s_add_i32 m0, s3, 0x2000
	v_lshl_add_u64 v[238:239], s[8:9], 0, v[128:129]
	global_load_lds_dwordx4 v[236:237], off
	s_mov_b32 m0, s58
	v_lshl_add_u64 v[240:241], s[8:9], 0, v[132:133]
	global_load_lds_dwordx4 v[238:239], off
	s_mov_b32 m0, s59
	s_nop 0
	global_load_lds_dwordx4 v[240:241], off
	s_waitcnt vmcnt(8)
	s_waitcnt lgkmcnt(0)
	s_barrier
; #define PG8_STAGE(bufoff, gbase, voff) do { _Pragma("unroll") for (int _i = 0; _i < 2; ++_i) \
;         __builtin_amdgcn_global_load_lds((const unsigned*)((const char*)(gbase) + (voff)[_i]), (PG8_LAS unsigned*)(lds + (bufoff) + ldsw + _i * 8192), 16, 0, 0); } while (0)
; #define PG8_LDA(dst, b, h) do { _Pragma("unroll") for (int m = 0; m < 4; ++m) _Pragma("unroll") for (int k = 0; k < 2; ++k) dst[m][k] = *(const PG8_LAS bf16x8*)(lds + PG8_SA(b, h) + aoff + m * 2048 + k * 1024); } while (0)
; #define PG8_LDB(dst, b, h) do { _Pragma("unroll") for (int n = 0; n < 2; ++n) _Pragma("unroll") for (int k = 0; k < 2; ++k) dst[n][k] = *(const PG8_LAS bf16x8*)(lds + PG8_SB(b, h) + boff + n * 2048 + k * 1024); } while (0)
; #define PG8_MMA(ai, bj, At, Bt) do { __builtin_amdgcn_s_setprio(1); _Pragma("unroll") for (int m = 0; m < 4; ++m) _Pragma("unroll") for (int n = 0; n < 2; ++n) _Pragma("unroll") for (int k = 0; k < 2; ++k) \
;         acc[ai][bj][m][n] = __builtin_amdgcn_mfma_f32_16x16x32_bf16(Bt[n][k], At[m][k], acc[ai][bj][m][n], 0, 0, 0); __builtin_amdgcn_s_setprio(0); } while (0)
; #define PG8_WAIT_V(n) asm volatile("s_waitcnt vmcnt(" #n ")" ::: "memory")
; #define PG8_WAIT_L(n) asm volatile("s_waitcnt lgkmcnt(" #n ")" ::: "memory")
; #define PG8_BAR __builtin_amdgcn_s_barrier()
; #define PG8_SCHED __builtin_amdgcn_sched_barrier(0)
; template <class Epi, class Sched, bool ALIGN_EPI = false, bool SP2 = false>
; __device__ __forceinline__ void gemm_phase(PG8_LAS unsigned char* lds, const Gemm g, const Sched& S, const Epi& E, int tid_in) {
;     ...
;             PG8_WAIT_V(8); PG8_WAIT_L(0); PG8_BAR; PG8_MMA(1, 0, At, B0); PG8_MMA(1, 1, At, B1); PG8_BAR; PG8_SCHED;
;             PG8_LDB(B0, 1, 0); PG8_LDB(B1, 1, 1); PG8_SCHED; PG8_LDA(At, 1, 0); PG8_STAGE(PG8_SA(0, 1), a2 + hstepA, voffA);
;             PG8_WAIT_V(8); PG8_WAIT_L(0); PG8_BAR; PG8_MMA(0, 0, At, B0); PG8_MMA(0, 1, At, B1); PG8_BAR; PG8_SCHED;
	s_setprio 1
	s_waitcnt lgkmcnt(0)
	v_mfma_f32_16x16x32_bf16 v[60:63], v[150:153], v[196:199], v[60:63]
	v_mfma_f32_16x16x32_bf16 v[56:59], v[172:175], v[196:199], v[56:59]
	v_mfma_f32_16x16x32_bf16 v[44:47], v[150:153], v[208:211], v[44:47]
	v_mfma_f32_16x16x32_bf16 v[40:43], v[172:175], v[208:211], v[40:43]
	v_mfma_f32_16x16x32_bf16 v[28:31], v[150:153], v[216:219], v[28:31]
	v_mfma_f32_16x16x32_bf16 v[24:27], v[172:175], v[216:219], v[24:27]
	v_mfma_f32_16x16x32_bf16 v[12:15], v[150:153], v[224:227], v[12:15]
	v_mfma_f32_16x16x32_bf16 v[8:11], v[172:175], v[224:227], v[8:11]
	v_mfma_f32_16x16x32_bf16 v[60:63], v[154:157], v[200:203], v[60:63]
	v_mfma_f32_16x16x32_bf16 v[56:59], v[176:179], v[200:203], v[56:59]
	v_mfma_f32_16x16x32_bf16 v[44:47], v[154:157], v[212:215], v[44:47]
	v_mfma_f32_16x16x32_bf16 v[40:43], v[176:179], v[212:215], v[40:43]
	v_mfma_f32_16x16x32_bf16 v[28:31], v[154:157], v[220:223], v[28:31]
	v_mfma_f32_16x16x32_bf16 v[24:27], v[176:179], v[220:223], v[24:27]
	v_mfma_f32_16x16x32_bf16 v[12:15], v[154:157], v[228:231], v[12:15]
	v_mfma_f32_16x16x32_bf16 v[8:11], v[176:179], v[228:231], v[8:11]
	s_setprio 0
	s_setprio 1
	v_mfma_f32_16x16x32_bf16 v[52:55], v[180:183], v[196:199], v[52:55]
	v_mfma_f32_16x16x32_bf16 v[48:51], v[188:191], v[196:199], v[48:51]
	v_mfma_f32_16x16x32_bf16 v[36:39], v[180:183], v[208:211], v[36:39]
	v_mfma_f32_16x16x32_bf16 v[32:35], v[188:191], v[208:211], v[32:35]
	v_mfma_f32_16x16x32_bf16 v[20:23], v[180:183], v[216:219], v[20:23]
	v_mfma_f32_16x16x32_bf16 v[16:19], v[188:191], v[216:219], v[16:19]
	v_mfma_f32_16x16x32_bf16 v[4:7], v[180:183], v[224:227], v[4:7]
	v_mfma_f32_16x16x32_bf16 v[0:3], v[188:191], v[224:227], v[0:3]
	v_mfma_f32_16x16x32_bf16 v[52:55], v[184:187], v[200:203], v[52:55]
	v_mfma_f32_16x16x32_bf16 v[48:51], v[192:195], v[200:203], v[48:51]
	v_mfma_f32_16x16x32_bf16 v[36:39], v[184:187], v[212:215], v[36:39]
	v_mfma_f32_16x16x32_bf16 v[32:35], v[192:195], v[212:215], v[32:35]
	v_mfma_f32_16x16x32_bf16 v[20:23], v[184:187], v[220:223], v[20:23]
	v_mfma_f32_16x16x32_bf16 v[16:19], v[192:195], v[220:223], v[16:19]
	v_mfma_f32_16x16x32_bf16 v[4:7], v[184:187], v[228:231], v[4:7]
	v_mfma_f32_16x16x32_bf16 v[0:3], v[192:195], v[228:231], v[0:3]
	s_setprio 0
	s_barrier
	s_add_i32 s3, 0, 0x18000
	s_add_i32 s11, 0, 0x1c000
	v_add_u32_e32 v176, s3, v160
	v_add_u32_e32 v192, s11, v160
	ds_read_b128 v[150:153], v176
	ds_read_b128 v[154:157], v176 offset:1024
	ds_read_b128 v[172:175], v176 offset:2048
	ds_read_b128 v[176:179], v176 offset:3072
	ds_read_b128 v[180:183], v192
	ds_read_b128 v[184:187], v192 offset:1024
	ds_read_b128 v[188:191], v192 offset:2048
	ds_read_b128 v[192:195], v192 offset:3072
	s_add_u32 s8, s8, s20
	s_addc_u32 s9, s9, s21
	s_mov_b32 m0, s60
	ds_read_b128 v[196:199], v170 offset:32768
	ds_read_b128 v[200:203], v170 offset:33792
	ds_read_b128 v[208:211], v170 offset:34816
	ds_read_b128 v[212:215], v170 offset:35840
	ds_read_b128 v[216:219], v170 offset:36864
	ds_read_b128 v[220:223], v170 offset:37888
	ds_read_b128 v[224:227], v170 offset:38912
	ds_read_b128 v[228:231], v170 offset:39936
	global_load_lds_dwordx4 v128, s[8:9]
	s_mov_b32 m0, s61
	s_nop 0
	global_load_lds_dwordx4 v132, s[8:9]
	s_waitcnt vmcnt(8)
	s_waitcnt lgkmcnt(0)
	s_barrier
	s_setprio 1
	s_waitcnt lgkmcnt(0)
	v_mfma_f32_16x16x32_bf16 v[124:127], v[150:153], v[196:199], v[124:127]
	v_mfma_f32_16x16x32_bf16 v[120:123], v[172:175], v[196:199], v[120:123]
	v_mfma_f32_16x16x32_bf16 v[108:111], v[150:153], v[208:211], v[108:111]
	v_mfma_f32_16x16x32_bf16 v[104:107], v[172:175], v[208:211], v[104:107]
	v_mfma_f32_16x16x32_bf16 v[92:95], v[150:153], v[216:219], v[92:95]
	v_mfma_f32_16x16x32_bf16 v[88:91], v[172:175], v[216:219], v[88:91]
	v_mfma_f32_16x16x32_bf16 v[76:79], v[150:153], v[224:227], v[76:79]
	v_mfma_f32_16x16x32_bf16 v[72:75], v[172:175], v[224:227], v[72:75]
	v_mfma_f32_16x16x32_bf16 v[124:127], v[154:157], v[200:203], v[124:127]
	v_mfma_f32_16x16x32_bf16 v[120:123], v[176:179], v[200:203], v[120:123]
	v_mfma_f32_16x16x32_bf16 v[108:111], v[154:157], v[212:215], v[108:111]
	v_mfma_f32_16x16x32_bf16 v[104:107], v[176:179], v[212:215], v[104:107]
	v_mfma_f32_16x16x32_bf16 v[92:95], v[154:157], v[220:223], v[92:95]
	v_mfma_f32_16x16x32_bf16 v[88:91], v[176:179], v[220:223], v[88:91]
	v_mfma_f32_16x16x32_bf16 v[76:79], v[154:157], v[228:231], v[76:79]
	v_mfma_f32_16x16x32_bf16 v[72:75], v[176:179], v[228:231], v[72:75]
	s_setprio 0
	s_setprio 1
	v_mfma_f32_16x16x32_bf16 v[116:119], v[180:183], v[196:199], v[116:119]
	v_mfma_f32_16x16x32_bf16 v[112:115], v[188:191], v[196:199], v[112:115]
	v_mfma_f32_16x16x32_bf16 v[100:103], v[180:183], v[208:211], v[100:103]
	v_mfma_f32_16x16x32_bf16 v[96:99], v[188:191], v[208:211], v[96:99]
	v_mfma_f32_16x16x32_bf16 v[84:87], v[180:183], v[216:219], v[84:87]
	v_mfma_f32_16x16x32_bf16 v[80:83], v[188:191], v[216:219], v[80:83]
	v_mfma_f32_16x16x32_bf16 v[68:71], v[180:183], v[224:227], v[68:71]
	v_mfma_f32_16x16x32_bf16 v[64:67], v[188:191], v[224:227], v[64:67]
	v_mfma_f32_16x16x32_bf16 v[116:119], v[184:187], v[200:203], v[116:119]
	v_mfma_f32_16x16x32_bf16 v[112:115], v[192:195], v[200:203], v[112:115]
	v_mfma_f32_16x16x32_bf16 v[100:103], v[184:187], v[212:215], v[100:103]
	v_mfma_f32_16x16x32_bf16 v[96:99], v[192:195], v[212:215], v[96:99]
	v_mfma_f32_16x16x32_bf16 v[84:87], v[184:187], v[220:223], v[84:87]
	v_mfma_f32_16x16x32_bf16 v[80:83], v[192:195], v[220:223], v[80:83]
	v_mfma_f32_16x16x32_bf16 v[68:71], v[184:187], v[228:231], v[68:71]
	v_mfma_f32_16x16x32_bf16 v[64:67], v[192:195], v[228:231], v[64:67]
	s_setprio 0
	s_barrier
; #define PG8_STAGE(bufoff, gbase, voff) do { _Pragma("unroll") for (int _i = 0; _i < 2; ++_i) \
;         __builtin_amdgcn_global_load_lds((const unsigned*)((const char*)(gbase) + (voff)[_i]), (PG8_LAS unsigned*)(lds + (bufoff) + ldsw + _i * 8192), 16, 0, 0); } while (0)
; #define PG8_LDA(dst, b, h) do { _Pragma("unroll") for (int m = 0; m < 4; ++m) _Pragma("unroll") for (int k = 0; k < 2; ++k) dst[m][k] = *(const PG8_LAS bf16x8*)(lds + PG8_SA(b, h) + aoff + m * 2048 + k * 1024); } while (0)
; #define PG8_MMA(ai, bj, At, Bt) do { __builtin_amdgcn_s_setprio(1); _Pragma("unroll") for (int m = 0; m < 4; ++m) _Pragma("unroll") for (int n = 0; n < 2; ++n) _Pragma("unroll") for (int k = 0; k < 2; ++k) \
;         acc[ai][bj][m][n] = __builtin_amdgcn_mfma_f32_16x16x32_bf16(Bt[n][k], At[m][k], acc[ai][bj][m][n], 0, 0, 0); __builtin_amdgcn_s_setprio(0); } while (0)
; #define PG8_WAIT_V(n) asm volatile("s_waitcnt vmcnt(" #n ")" ::: "memory")
; #define PG8_WAIT_L(n) asm volatile("s_waitcnt lgkmcnt(" #n ")" ::: "memory")
; #define PG8_BAR __builtin_amdgcn_s_barrier()
; #define PG8_SCHED __builtin_amdgcn_sched_barrier(0)
; template <class Epi, class Sched, bool ALIGN_EPI = false, bool SP2 = false>
; __device__ __forceinline__ void gemm_phase(PG8_LAS unsigned char* lds, const Gemm g, const Sched& S, const Epi& E, int tid_in) {
;     ...
;         for (int t = 0; t < nt; t += 2) {
;     ...
;             PG8_LDA(At, 1, 1); PG8_STAGE(PG8_SB(1, 0), b3, voffB); PG8_STAGE(PG8_SB(1, 1), b3 + hstepB, voffB); PG8_STAGE(PG8_SA(1, 0), a3, voffA);
;             PG8_WAIT_V(8); PG8_WAIT_L(0); PG8_BAR; PG8_MMA(1, 0, At, B0); PG8_MMA(1, 1, At, B1); PG8_BAR; PG8_SCHED;
	s_add_i32 s3, s3, s57
	v_lshl_add_u64 v[204:205], v[204:205], 0, s[36:37]
	s_mov_b32 m0, s3
	ds_read_b128 v[196:199], v170 offset:49152
	ds_read_b128 v[200:203], v170 offset:50176
	ds_read_b128 v[208:211], v170 offset:51200
	ds_read_b128 v[212:215], v170 offset:52224
	ds_read_b128 v[216:219], v170 offset:53248
	ds_read_b128 v[220:223], v170 offset:54272
	ds_read_b128 v[224:227], v170 offset:55296
	ds_read_b128 v[228:231], v170 offset:56320
	global_load_lds_dwordx4 v[204:205], off
	v_lshl_add_u64 v[204:205], v[232:233], 0, s[36:37]
	s_add_i32 m0, s3, 0x2000
	s_add_i32 s3, s11, s57
	global_load_lds_dwordx4 v[204:205], off
	v_lshl_add_u64 v[204:205], v[234:235], 0, s[36:37]
	s_mov_b32 m0, s3
	s_nop 0
	global_load_lds_dwordx4 v[204:205], off
	v_lshl_add_u64 v[204:205], v[236:237], 0, s[36:37]
	s_add_i32 m0, s3, 0x2000
	s_nop 0
	global_load_lds_dwordx4 v[204:205], off
	v_lshl_add_u64 v[204:205], v[238:239], 0, s[36:37]
	s_mov_b32 m0, s63
	s_nop 0
	global_load_lds_dwordx4 v[204:205], off
	v_lshl_add_u64 v[204:205], v[240:241], 0, s[36:37]
	s_mov_b32 m0, s64
	s_nop 0
	global_load_lds_dwordx4 v[204:205], off
	s_waitcnt vmcnt(8)
	s_waitcnt lgkmcnt(0)
	s_barrier
	s_setprio 1
	s_waitcnt lgkmcnt(0)
	v_mfma_f32_16x16x32_bf16 v[60:63], v[150:153], v[196:199], v[60:63]
	v_mfma_f32_16x16x32_bf16 v[56:59], v[172:175], v[196:199], v[56:59]
	v_mfma_f32_16x16x32_bf16 v[44:47], v[150:153], v[208:211], v[44:47]
	v_mfma_f32_16x16x32_bf16 v[40:43], v[172:175], v[208:211], v[40:43]
	v_mfma_f32_16x16x32_bf16 v[28:31], v[150:153], v[216:219], v[28:31]
	v_mfma_f32_16x16x32_bf16 v[24:27], v[172:175], v[216:219], v[24:27]
	v_mfma_f32_16x16x32_bf16 v[12:15], v[150:153], v[224:227], v[12:15]
	v_mfma_f32_16x16x32_bf16 v[8:11], v[172:175], v[224:227], v[8:11]
	v_mfma_f32_16x16x32_bf16 v[60:63], v[154:157], v[200:203], v[60:63]
	v_mfma_f32_16x16x32_bf16 v[56:59], v[176:179], v[200:203], v[56:59]
	v_mfma_f32_16x16x32_bf16 v[44:47], v[154:157], v[212:215], v[44:47]
	v_mfma_f32_16x16x32_bf16 v[40:43], v[176:179], v[212:215], v[40:43]
	v_mfma_f32_16x16x32_bf16 v[28:31], v[154:157], v[220:223], v[28:31]
	v_mfma_f32_16x16x32_bf16 v[24:27], v[176:179], v[220:223], v[24:27]
	v_mfma_f32_16x16x32_bf16 v[12:15], v[154:157], v[228:231], v[12:15]
	v_mfma_f32_16x16x32_bf16 v[8:11], v[176:179], v[228:231], v[8:11]
	s_setprio 0
	s_setprio 1
	v_mfma_f32_16x16x32_bf16 v[52:55], v[180:183], v[196:199], v[52:55]
	v_mfma_f32_16x16x32_bf16 v[48:51], v[188:191], v[196:199], v[48:51]
	v_mfma_f32_16x16x32_bf16 v[36:39], v[180:183], v[208:211], v[36:39]
	v_mfma_f32_16x16x32_bf16 v[32:35], v[188:191], v[208:211], v[32:35]
	v_mfma_f32_16x16x32_bf16 v[20:23], v[180:183], v[216:219], v[20:23]
	v_mfma_f32_16x16x32_bf16 v[16:19], v[188:191], v[216:219], v[16:19]
	v_mfma_f32_16x16x32_bf16 v[4:7], v[180:183], v[224:227], v[4:7]
	v_mfma_f32_16x16x32_bf16 v[0:3], v[188:191], v[224:227], v[0:3]
	v_mfma_f32_16x16x32_bf16 v[52:55], v[184:187], v[200:203], v[52:55]
	v_mfma_f32_16x16x32_bf16 v[48:51], v[192:195], v[200:203], v[48:51]
	v_mfma_f32_16x16x32_bf16 v[36:39], v[184:187], v[212:215], v[36:39]
	v_mfma_f32_16x16x32_bf16 v[32:35], v[192:195], v[212:215], v[32:35]
	v_mfma_f32_16x16x32_bf16 v[20:23], v[184:187], v[220:223], v[20:23]
	v_mfma_f32_16x16x32_bf16 v[16:19], v[192:195], v[220:223], v[16:19]
	v_mfma_f32_16x16x32_bf16 v[4:7], v[184:187], v[228:231], v[4:7]
	v_mfma_f32_16x16x32_bf16 v[0:3], v[192:195], v[228:231], v[0:3]
	s_setprio 0
	s_barrier
	s_add_u32 s6, s6, 0x100
	s_addc_u32 s7, s7, 0
	s_add_u32 s1, s1, 0x100
	s_addc_u32 s2, s2, 0
	s_cmp_ge_i32 s10, s65
	s_mov_b32 s3, s10
	s_cbranch_scc0 .LBB0_287

; #define PG8_STAGE(bufoff, gbase, voff) do { _Pragma("unroll") for (int _i = 0; _i < 2; ++_i) \
;         __builtin_amdgcn_global_load_lds((const unsigned*)((const char*)(gbase) + (voff)[_i]), (PG8_LAS unsigned*)(lds + (bufoff) + ldsw + _i * 8192), 16, 0, 0); } while (0)
; #define PG8_LDA(dst, b, h) do { _Pragma("unroll") for (int m = 0; m < 4; ++m) _Pragma("unroll") for (int k = 0; k < 2; ++k) dst[m][k] = *(const PG8_LAS bf16x8*)(lds + PG8_SA(b, h) + aoff + m * 2048 + k * 1024); } while (0)
; #define PG8_LDB(dst, b, h) do { _Pragma("unroll") for (int n = 0; n < 2; ++n) _Pragma("unroll") for (int k = 0; k < 2; ++k) dst[n][k] = *(const PG8_LAS bf16x8*)(lds + PG8_SB(b, h) + boff + n * 2048 + k * 1024); } while (0)
; #define PG8_MMA(ai, bj, At, Bt) do { __builtin_amdgcn_s_setprio(1); _Pragma("unroll") for (int m = 0; m < 4; ++m) _Pragma("unroll") for (int n = 0; n < 2; ++n) _Pragma("unroll") for (int k = 0; k < 2; ++k) \
;         acc[ai][bj][m][n] = __builtin_amdgcn_mfma_f32_16x16x32_bf16(Bt[n][k], At[m][k], acc[ai][bj][m][n], 0, 0, 0); __builtin_amdgcn_s_setprio(0); } while (0)
; #define PG8_WAIT_V(n) asm volatile("s_waitcnt vmcnt(" #n ")" ::: "memory")
; #define PG8_BAR __builtin_amdgcn_s_barrier()
; template <class Epi, class Sched, bool ALIGN_EPI = false, bool SP2 = false>
; __device__ __forceinline__ void gemm_phase(PG8_LAS unsigned char* lds, const Gemm g, const Sched& S, const Epi& E, int tid_in) {
;     ...
;         for (int t = 0; t < nt; t += 2) {
;             const bool last = (t == nt - 2);
;             const char* a1 = cA + (size_t)(t + 1) * kstep;
;             const char* a2 = last ? nA : cA + (size_t)(t + 2) * kstep; const char* b2 = last ? nB : cB + (size_t)(t + 2) * kstep;
;             const char* a3 = a2 + kstep; const char* b3 = b2 + kstep;
;             if (last && has_next) S.a_ready(nxt);
;             if constexpr (SP2) {
;             PG8_LDB(B0, 0, 0); PG8_LDB(B1, 0, 1); PG8_SCHED; PG8_LDA(At, 0, 0); PG8_STAGE(PG8_SA(1, 1), a1 + hstepA, voffA);
;             PG8_WAIT_V(8); PG8_WAIT_L(0); PG8_BAR; PG8_MMA(0, 0, At, B0); PG8_MMA(0, 1, At, B1); PG8_BAR; PG8_SCHED;
;             PG8_LDA(At, 0, 1); PG8_STAGE(PG8_SB(0, 0), b2, voffB); PG8_STAGE(PG8_SB(0, 1), b2 + hstepB, voffB); PG8_STAGE(PG8_SA(0, 0), a2, voffA);
;             PG8_WAIT_V(8); PG8_WAIT_L(0); PG8_BAR; PG8_MMA(1, 0, At, B0); PG8_MMA(1, 1, At, B1); PG8_BAR; PG8_SCHED;
.LBB0_498:
	ds_read_b128 v[152:155], v149
	ds_read_b128 v[156:159], v149 offset:1024
	ds_read_b128 v[160:163], v149 offset:2048
	ds_read_b128 v[164:167], v149 offset:3072
	ds_read_b128 v[168:171], v150
	ds_read_b128 v[172:175], v150 offset:1024
	ds_read_b128 v[176:179], v150 offset:2048
	ds_read_b128 v[180:183], v150 offset:3072
	s_add_i32 s52, s28, 2
	s_add_u32 s53, s26, 0x80
	s_addc_u32 s29, s27, 0
	s_cmp_eq_u32 s40, s28
	s_cselect_b32 s28, s6, s53
	s_cselect_b32 s29, s7, s29
	s_cselect_b32 s59, s25, s51
	s_cselect_b32 s58, s24, s50
	s_add_i32 m0, s31, 0xc000
	ds_read_b128 v[184:187], v151
	ds_read_b128 v[188:191], v151 offset:1024
	ds_read_b128 v[192:195], v151 offset:2048
	ds_read_b128 v[196:199], v151 offset:3072
	ds_read_b128 v[200:203], v151 offset:4096
	ds_read_b128 v[208:211], v151 offset:5120
	ds_read_b128 v[212:215], v151 offset:6144
	ds_read_b128 v[216:219], v151 offset:7168
	global_load_lds_dwordx4 v138, s[26:27]
	s_add_i32 m0, s31, 0xe000
	s_nop 0
	global_load_lds_dwordx4 v140, s[26:27]
	s_waitcnt vmcnt(8)
	s_waitcnt lgkmcnt(0)
	s_barrier
	s_setprio 1
	s_waitcnt lgkmcnt(0)
	v_mfma_f32_16x16x32_bf16 v[124:127], v[152:155], v[184:187], v[124:127]
	v_mfma_f32_16x16x32_bf16 v[120:123], v[160:163], v[184:187], v[120:123]
	v_mfma_f32_16x16x32_bf16 v[116:119], v[152:155], v[192:195], v[116:119]
	v_mfma_f32_16x16x32_bf16 v[112:115], v[160:163], v[192:195], v[112:115]
	v_mfma_f32_16x16x32_bf16 v[108:111], v[152:155], v[200:203], v[108:111]
	v_mfma_f32_16x16x32_bf16 v[104:107], v[160:163], v[200:203], v[104:107]
	v_mfma_f32_16x16x32_bf16 v[100:103], v[152:155], v[212:215], v[100:103]
	v_mfma_f32_16x16x32_bf16 v[96:99], v[160:163], v[212:215], v[96:99]
	v_mfma_f32_16x16x32_bf16 v[124:127], v[156:159], v[188:191], v[124:127]
	v_mfma_f32_16x16x32_bf16 v[120:123], v[164:167], v[188:191], v[120:123]
	v_mfma_f32_16x16x32_bf16 v[116:119], v[156:159], v[196:199], v[116:119]
	v_mfma_f32_16x16x32_bf16 v[112:115], v[164:167], v[196:199], v[112:115]
	v_mfma_f32_16x16x32_bf16 v[108:111], v[156:159], v[208:211], v[108:111]
	v_mfma_f32_16x16x32_bf16 v[104:107], v[164:167], v[208:211], v[104:107]
	v_mfma_f32_16x16x32_bf16 v[100:103], v[156:159], v[216:219], v[100:103]
	v_mfma_f32_16x16x32_bf16 v[96:99], v[164:167], v[216:219], v[96:99]
	s_setprio 0
	s_setprio 1
	v_mfma_f32_16x16x32_bf16 v[60:63], v[168:171], v[184:187], v[60:63]
	v_mfma_f32_16x16x32_bf16 v[56:59], v[176:179], v[184:187], v[56:59]
	v_mfma_f32_16x16x32_bf16 v[52:55], v[168:171], v[192:195], v[52:55]
	v_mfma_f32_16x16x32_bf16 v[48:51], v[176:179], v[192:195], v[48:51]
	v_mfma_f32_16x16x32_bf16 v[44:47], v[168:171], v[200:203], v[44:47]
	v_mfma_f32_16x16x32_bf16 v[40:43], v[176:179], v[200:203], v[40:43]
	v_mfma_f32_16x16x32_bf16 v[36:39], v[168:171], v[212:215], v[36:39]
	v_mfma_f32_16x16x32_bf16 v[32:35], v[176:179], v[212:215], v[32:35]
	v_mfma_f32_16x16x32_bf16 v[60:63], v[172:175], v[188:191], v[60:63]
	v_mfma_f32_16x16x32_bf16 v[56:59], v[180:183], v[188:191], v[56:59]
	v_mfma_f32_16x16x32_bf16 v[52:55], v[172:175], v[196:199], v[52:55]
	v_mfma_f32_16x16x32_bf16 v[48:51], v[180:183], v[196:199], v[48:51]
	v_mfma_f32_16x16x32_bf16 v[44:47], v[172:175], v[208:211], v[44:47]
	v_mfma_f32_16x16x32_bf16 v[40:43], v[180:183], v[208:211], v[40:43]
	v_mfma_f32_16x16x32_bf16 v[36:39], v[172:175], v[216:219], v[36:39]
	v_mfma_f32_16x16x32_bf16 v[32:35], v[180:183], v[216:219], v[32:35]
	s_setprio 0
	s_barrier
	s_add_i32 s53, s43, s2
	v_lshl_add_u64 v[204:205], s[58:59], 0, v[132:133]
	s_mov_b32 m0, s53
	ds_read_b128 v[184:187], v151 offset:16384
	ds_read_b128 v[188:191], v151 offset:17408
	ds_read_b128 v[192:195], v151 offset:18432
	ds_read_b128 v[196:199], v151 offset:19456
	ds_read_b128 v[200:203], v151 offset:20480
	ds_read_b128 v[208:211], v151 offset:21504
	ds_read_b128 v[212:215], v151 offset:22528
	ds_read_b128 v[216:219], v151 offset:23552
	global_load_lds_dwordx4 v[204:205], off
	s_add_i32 m0, s53, 0x2000
	v_lshl_add_u64 v[220:221], s[58:59], 0, v[128:129]
	s_add_u32 s58, s58, s8
	s_addc_u32 s59, s59, s9
	s_add_i32 s53, s44, s2
	global_load_lds_dwordx4 v[220:221], off
	v_lshl_add_u64 v[222:223], s[58:59], 0, v[132:133]
	s_mov_b32 m0, s53
	v_lshl_add_u64 v[224:225], s[58:59], 0, v[128:129]
	global_load_lds_dwordx4 v[222:223], off
	s_add_i32 m0, s53, 0x2000
	v_lshl_add_u64 v[226:227], s[28:29], 0, v[134:135]
	global_load_lds_dwordx4 v[224:225], off
	s_mov_b32 m0, s31
	v_lshl_add_u64 v[228:229], s[28:29], 0, v[130:131]
	global_load_lds_dwordx4 v[226:227], off
	s_mov_b32 m0, s33
	s_nop 0
	global_load_lds_dwordx4 v[228:229], off
	s_waitcnt vmcnt(8)
	s_waitcnt lgkmcnt(0)
	s_barrier
; #define PG8_STAGE(bufoff, gbase, voff) do { _Pragma("unroll") for (int _i = 0; _i < 2; ++_i) \
;         __builtin_amdgcn_global_load_lds((const unsigned*)((const char*)(gbase) + (voff)[_i]), (PG8_LAS unsigned*)(lds + (bufoff) + ldsw + _i * 8192), 16, 0, 0); } while (0)
; #define PG8_LDA(dst, b, h) do { _Pragma("unroll") for (int m = 0; m < 4; ++m) _Pragma("unroll") for (int k = 0; k < 2; ++k) dst[m][k] = *(const PG8_LAS bf16x8*)(lds + PG8_SA(b, h) + aoff + m * 2048 + k * 1024); } while (0)
; #define PG8_LDB(dst, b, h) do { _Pragma("unroll") for (int n = 0; n < 2; ++n) _Pragma("unroll") for (int k = 0; k < 2; ++k) dst[n][k] = *(const PG8_LAS bf16x8*)(lds + PG8_SB(b, h) + boff + n * 2048 + k * 1024); } while (0)
; #define PG8_MMA(ai, bj, At, Bt) do { __builtin_amdgcn_s_setprio(1); _Pragma("unroll") for (int m = 0; m < 4; ++m) _Pragma("unroll") for (int n = 0; n < 2; ++n) _Pragma("unroll") for (int k = 0; k < 2; ++k) \
;         acc[ai][bj][m][n] = __builtin_amdgcn_mfma_f32_16x16x32_bf16(Bt[n][k], At[m][k], acc[ai][bj][m][n], 0, 0, 0); __builtin_amdgcn_s_setprio(0); } while (0)
; #define PG8_WAIT_V(n) asm volatile("s_waitcnt vmcnt(" #n ")" ::: "memory")
; #define PG8_WAIT_L(n) asm volatile("s_waitcnt lgkmcnt(" #n ")" ::: "memory")
; #define PG8_BAR __builtin_amdgcn_s_barrier()
; #define PG8_SCHED __builtin_amdgcn_sched_barrier(0)
; template <class Epi, class Sched, bool ALIGN_EPI = false, bool SP2 = false>
; __device__ __forceinline__ void gemm_phase(PG8_LAS unsigned char* lds, const Gemm g, const Sched& S, const Epi& E, int tid_in) {
;     ...
;             PG8_WAIT_V(8); PG8_WAIT_L(0); PG8_BAR; PG8_MMA(1, 0, At, B0); PG8_MMA(1, 1, At, B1); PG8_BAR; PG8_SCHED;
;             PG8_LDB(B0, 1, 0); PG8_LDB(B1, 1, 1); PG8_SCHED; PG8_LDA(At, 1, 0); PG8_STAGE(PG8_SA(0, 1), a2 + hstepA, voffA);
;             PG8_WAIT_V(8); PG8_WAIT_L(0); PG8_BAR; PG8_MMA(0, 0, At, B0); PG8_MMA(0, 1, At, B1); PG8_BAR; PG8_SCHED;
	s_setprio 1
	s_waitcnt lgkmcnt(0)
	v_mfma_f32_16x16x32_bf16 v[92:95], v[152:155], v[184:187], v[92:95]
	v_mfma_f32_16x16x32_bf16 v[88:91], v[160:163], v[184:187], v[88:91]
	v_mfma_f32_16x16x32_bf16 v[84:87], v[152:155], v[192:195], v[84:87]
	v_mfma_f32_16x16x32_bf16 v[80:83], v[160:163], v[192:195], v[80:83]
	v_mfma_f32_16x16x32_bf16 v[76:79], v[152:155], v[200:203], v[76:79]
	v_mfma_f32_16x16x32_bf16 v[72:75], v[160:163], v[200:203], v[72:75]
	v_mfma_f32_16x16x32_bf16 v[68:71], v[152:155], v[212:215], v[68:71]
	v_mfma_f32_16x16x32_bf16 v[64:67], v[160:163], v[212:215], v[64:67]
	v_mfma_f32_16x16x32_bf16 v[92:95], v[156:159], v[188:191], v[92:95]
	v_mfma_f32_16x16x32_bf16 v[88:91], v[164:167], v[188:191], v[88:91]
	v_mfma_f32_16x16x32_bf16 v[84:87], v[156:159], v[196:199], v[84:87]
	v_mfma_f32_16x16x32_bf16 v[80:83], v[164:167], v[196:199], v[80:83]
	v_mfma_f32_16x16x32_bf16 v[76:79], v[156:159], v[208:211], v[76:79]
	v_mfma_f32_16x16x32_bf16 v[72:75], v[164:167], v[208:211], v[72:75]
	v_mfma_f32_16x16x32_bf16 v[68:71], v[156:159], v[216:219], v[68:71]
	v_mfma_f32_16x16x32_bf16 v[64:67], v[164:167], v[216:219], v[64:67]
	s_setprio 0
	s_setprio 1
	v_mfma_f32_16x16x32_bf16 v[28:31], v[168:171], v[184:187], v[28:31]
	v_mfma_f32_16x16x32_bf16 v[24:27], v[176:179], v[184:187], v[24:27]
	v_mfma_f32_16x16x32_bf16 v[20:23], v[168:171], v[192:195], v[20:23]
	v_mfma_f32_16x16x32_bf16 v[16:19], v[176:179], v[192:195], v[16:19]
	v_mfma_f32_16x16x32_bf16 v[12:15], v[168:171], v[200:203], v[12:15]
	v_mfma_f32_16x16x32_bf16 v[8:11], v[176:179], v[200:203], v[8:11]
	v_mfma_f32_16x16x32_bf16 v[4:7], v[168:171], v[212:215], v[4:7]
	v_mfma_f32_16x16x32_bf16 v[0:3], v[176:179], v[212:215], v[0:3]
	v_mfma_f32_16x16x32_bf16 v[28:31], v[172:175], v[188:191], v[28:31]
	v_mfma_f32_16x16x32_bf16 v[24:27], v[180:183], v[188:191], v[24:27]
	v_mfma_f32_16x16x32_bf16 v[20:23], v[172:175], v[196:199], v[20:23]
	v_mfma_f32_16x16x32_bf16 v[16:19], v[180:183], v[196:199], v[16:19]
	v_mfma_f32_16x16x32_bf16 v[12:15], v[172:175], v[208:211], v[12:15]
	v_mfma_f32_16x16x32_bf16 v[8:11], v[180:183], v[208:211], v[8:11]
	v_mfma_f32_16x16x32_bf16 v[4:7], v[172:175], v[216:219], v[4:7]
	v_mfma_f32_16x16x32_bf16 v[0:3], v[180:183], v[216:219], v[0:3]
	s_setprio 0
	s_barrier
	s_add_i32 s53, 0, 0x18000
	s_add_i32 s57, 0, 0x1c000
	v_add_u32_e32 v164, s53, v147
	v_add_u32_e32 v180, s57, v147
	ds_read_b128 v[152:155], v164
	ds_read_b128 v[156:159], v164 offset:1024
	ds_read_b128 v[160:163], v164 offset:2048
	ds_read_b128 v[164:167], v164 offset:3072
	ds_read_b128 v[168:171], v180
	ds_read_b128 v[172:175], v180 offset:1024
	ds_read_b128 v[176:179], v180 offset:2048
	ds_read_b128 v[180:183], v180 offset:3072
	s_add_u32 s28, s28, s8
	s_addc_u32 s29, s29, s9
	s_mov_b32 m0, s34
	ds_read_b128 v[184:187], v151 offset:32768
	ds_read_b128 v[188:191], v151 offset:33792
	ds_read_b128 v[192:195], v151 offset:34816
	ds_read_b128 v[196:199], v151 offset:35840
	ds_read_b128 v[200:203], v151 offset:36864
	ds_read_b128 v[208:211], v151 offset:37888
	ds_read_b128 v[212:215], v151 offset:38912
	ds_read_b128 v[216:219], v151 offset:39936
	global_load_lds_dwordx4 v134, s[28:29]
	s_mov_b32 m0, s35
	s_nop 0
	global_load_lds_dwordx4 v130, s[28:29]
	s_waitcnt vmcnt(8)
	s_waitcnt lgkmcnt(0)
	s_barrier
	s_setprio 1
	s_waitcnt lgkmcnt(0)
	v_mfma_f32_16x16x32_bf16 v[124:127], v[152:155], v[184:187], v[124:127]
	v_mfma_f32_16x16x32_bf16 v[120:123], v[160:163], v[184:187], v[120:123]
	v_mfma_f32_16x16x32_bf16 v[116:119], v[152:155], v[192:195], v[116:119]
	v_mfma_f32_16x16x32_bf16 v[112:115], v[160:163], v[192:195], v[112:115]
	v_mfma_f32_16x16x32_bf16 v[108:111], v[152:155], v[200:203], v[108:111]
	v_mfma_f32_16x16x32_bf16 v[104:107], v[160:163], v[200:203], v[104:107]
	v_mfma_f32_16x16x32_bf16 v[100:103], v[152:155], v[212:215], v[100:103]
	v_mfma_f32_16x16x32_bf16 v[96:99], v[160:163], v[212:215], v[96:99]
	v_mfma_f32_16x16x32_bf16 v[124:127], v[156:159], v[188:191], v[124:127]
	v_mfma_f32_16x16x32_bf16 v[120:123], v[164:167], v[188:191], v[120:123]
	v_mfma_f32_16x16x32_bf16 v[116:119], v[156:159], v[196:199], v[116:119]
	v_mfma_f32_16x16x32_bf16 v[112:115], v[164:167], v[196:199], v[112:115]
	v_mfma_f32_16x16x32_bf16 v[108:111], v[156:159], v[208:211], v[108:111]
	v_mfma_f32_16x16x32_bf16 v[104:107], v[164:167], v[208:211], v[104:107]
	v_mfma_f32_16x16x32_bf16 v[100:103], v[156:159], v[216:219], v[100:103]
	v_mfma_f32_16x16x32_bf16 v[96:99], v[164:167], v[216:219], v[96:99]
	s_setprio 0
	s_setprio 1
	v_mfma_f32_16x16x32_bf16 v[60:63], v[168:171], v[184:187], v[60:63]
	v_mfma_f32_16x16x32_bf16 v[56:59], v[176:179], v[184:187], v[56:59]
	v_mfma_f32_16x16x32_bf16 v[52:55], v[168:171], v[192:195], v[52:55]
	v_mfma_f32_16x16x32_bf16 v[48:51], v[176:179], v[192:195], v[48:51]
	v_mfma_f32_16x16x32_bf16 v[44:47], v[168:171], v[200:203], v[44:47]
	v_mfma_f32_16x16x32_bf16 v[40:43], v[176:179], v[200:203], v[40:43]
	v_mfma_f32_16x16x32_bf16 v[36:39], v[168:171], v[212:215], v[36:39]
	v_mfma_f32_16x16x32_bf16 v[32:35], v[176:179], v[212:215], v[32:35]
	v_mfma_f32_16x16x32_bf16 v[60:63], v[172:175], v[188:191], v[60:63]
	v_mfma_f32_16x16x32_bf16 v[56:59], v[180:183], v[188:191], v[56:59]
	v_mfma_f32_16x16x32_bf16 v[52:55], v[172:175], v[196:199], v[52:55]
	v_mfma_f32_16x16x32_bf16 v[48:51], v[180:183], v[196:199], v[48:51]
	v_mfma_f32_16x16x32_bf16 v[44:47], v[172:175], v[208:211], v[44:47]
	v_mfma_f32_16x16x32_bf16 v[40:43], v[180:183], v[208:211], v[40:43]
	v_mfma_f32_16x16x32_bf16 v[36:39], v[172:175], v[216:219], v[36:39]
	v_mfma_f32_16x16x32_bf16 v[32:35], v[180:183], v[216:219], v[32:35]
	s_setprio 0
	s_barrier
; #define PG8_STAGE(bufoff, gbase, voff) do { _Pragma("unroll") for (int _i = 0; _i < 2; ++_i) \
;         __builtin_amdgcn_global_load_lds((const unsigned*)((const char*)(gbase) + (voff)[_i]), (PG8_LAS unsigned*)(lds + (bufoff) + ldsw + _i * 8192), 16, 0, 0); } while (0)
; #define PG8_LDA(dst, b, h) do { _Pragma("unroll") for (int m = 0; m < 4; ++m) _Pragma("unroll") for (int k = 0; k < 2; ++k) dst[m][k] = *(const PG8_LAS bf16x8*)(lds + PG8_SA(b, h) + aoff + m * 2048 + k * 1024); } while (0)
; #define PG8_MMA(ai, bj, At, Bt) do { __builtin_amdgcn_s_setprio(1); _Pragma("unroll") for (int m = 0; m < 4; ++m) _Pragma("unroll") for (int n = 0; n < 2; ++n) _Pragma("unroll") for (int k = 0; k < 2; ++k) \
;         acc[ai][bj][m][n] = __builtin_amdgcn_mfma_f32_16x16x32_bf16(Bt[n][k], At[m][k], acc[ai][bj][m][n], 0, 0, 0); __builtin_amdgcn_s_setprio(0); } while (0)
; #define PG8_WAIT_V(n) asm volatile("s_waitcnt vmcnt(" #n ")" ::: "memory")
; #define PG8_WAIT_L(n) asm volatile("s_waitcnt lgkmcnt(" #n ")" ::: "memory")
; #define PG8_BAR __builtin_amdgcn_s_barrier()
; #define PG8_SCHED __builtin_amdgcn_sched_barrier(0)
; template <class Epi, class Sched, bool ALIGN_EPI = false, bool SP2 = false>
; __device__ __forceinline__ void gemm_phase(PG8_LAS unsigned char* lds, const Gemm g, const Sched& S, const Epi& E, int tid_in) {
;     ...
;         for (int t = 0; t < nt; t += 2) {
;     ...
;             PG8_LDA(At, 1, 1); PG8_STAGE(PG8_SB(1, 0), b3, voffB); PG8_STAGE(PG8_SB(1, 1), b3 + hstepB, voffB); PG8_STAGE(PG8_SA(1, 0), a3, voffA);
;             PG8_WAIT_V(8); PG8_WAIT_L(0); PG8_BAR; PG8_MMA(1, 0, At, B0); PG8_MMA(1, 1, At, B1); PG8_BAR; PG8_SCHED;
	s_add_i32 s28, s53, s2
	v_lshl_add_u64 v[204:205], v[204:205], 0, s[18:19]
	s_mov_b32 m0, s28
	ds_read_b128 v[184:187], v151 offset:49152
	ds_read_b128 v[188:191], v151 offset:50176
	ds_read_b128 v[192:195], v151 offset:51200
	ds_read_b128 v[196:199], v151 offset:52224
	ds_read_b128 v[200:203], v151 offset:53248
	ds_read_b128 v[208:211], v151 offset:54272
	ds_read_b128 v[212:215], v151 offset:55296
	ds_read_b128 v[216:219], v151 offset:56320
	global_load_lds_dwordx4 v[204:205], off
	v_lshl_add_u64 v[204:205], v[220:221], 0, s[18:19]
	s_add_i32 m0, s28, 0x2000
	s_add_i32 s28, s57, s2
	global_load_lds_dwordx4 v[204:205], off
	v_lshl_add_u64 v[204:205], v[222:223], 0, s[18:19]
	s_mov_b32 m0, s28
	s_nop 0
	global_load_lds_dwordx4 v[204:205], off
	v_lshl_add_u64 v[204:205], v[224:225], 0, s[18:19]
	s_add_i32 m0, s28, 0x2000
	s_nop 0
	global_load_lds_dwordx4 v[204:205], off
	v_lshl_add_u64 v[204:205], v[226:227], 0, s[18:19]
	s_mov_b32 m0, s37
	s_nop 0
	global_load_lds_dwordx4 v[204:205], off
	v_lshl_add_u64 v[204:205], v[228:229], 0, s[18:19]
	s_mov_b32 m0, s38
	s_nop 0
	global_load_lds_dwordx4 v[204:205], off
	s_waitcnt vmcnt(8)
	s_waitcnt lgkmcnt(0)
	s_barrier
	s_setprio 1
	s_waitcnt lgkmcnt(0)
	v_mfma_f32_16x16x32_bf16 v[92:95], v[152:155], v[184:187], v[92:95]
	v_mfma_f32_16x16x32_bf16 v[88:91], v[160:163], v[184:187], v[88:91]
	v_mfma_f32_16x16x32_bf16 v[84:87], v[152:155], v[192:195], v[84:87]
	v_mfma_f32_16x16x32_bf16 v[80:83], v[160:163], v[192:195], v[80:83]
	v_mfma_f32_16x16x32_bf16 v[76:79], v[152:155], v[200:203], v[76:79]
	v_mfma_f32_16x16x32_bf16 v[72:75], v[160:163], v[200:203], v[72:75]
	v_mfma_f32_16x16x32_bf16 v[68:71], v[152:155], v[212:215], v[68:71]
	v_mfma_f32_16x16x32_bf16 v[64:67], v[160:163], v[212:215], v[64:67]
	v_mfma_f32_16x16x32_bf16 v[92:95], v[156:159], v[188:191], v[92:95]
	v_mfma_f32_16x16x32_bf16 v[88:91], v[164:167], v[188:191], v[88:91]
	v_mfma_f32_16x16x32_bf16 v[84:87], v[156:159], v[196:199], v[84:87]
	v_mfma_f32_16x16x32_bf16 v[80:83], v[164:167], v[196:199], v[80:83]
	v_mfma_f32_16x16x32_bf16 v[76:79], v[156:159], v[208:211], v[76:79]
	v_mfma_f32_16x16x32_bf16 v[72:75], v[164:167], v[208:211], v[72:75]
	v_mfma_f32_16x16x32_bf16 v[68:71], v[156:159], v[216:219], v[68:71]
	v_mfma_f32_16x16x32_bf16 v[64:67], v[164:167], v[216:219], v[64:67]
	s_setprio 0
	s_setprio 1
	v_mfma_f32_16x16x32_bf16 v[28:31], v[168:171], v[184:187], v[28:31]
	v_mfma_f32_16x16x32_bf16 v[24:27], v[176:179], v[184:187], v[24:27]
	v_mfma_f32_16x16x32_bf16 v[20:23], v[168:171], v[192:195], v[20:23]
	v_mfma_f32_16x16x32_bf16 v[16:19], v[176:179], v[192:195], v[16:19]
	v_mfma_f32_16x16x32_bf16 v[12:15], v[168:171], v[200:203], v[12:15]
	v_mfma_f32_16x16x32_bf16 v[8:11], v[176:179], v[200:203], v[8:11]
	v_mfma_f32_16x16x32_bf16 v[4:7], v[168:171], v[212:215], v[4:7]
	v_mfma_f32_16x16x32_bf16 v[0:3], v[176:179], v[212:215], v[0:3]
	v_mfma_f32_16x16x32_bf16 v[28:31], v[172:175], v[188:191], v[28:31]
	v_mfma_f32_16x16x32_bf16 v[24:27], v[180:183], v[188:191], v[24:27]
	v_mfma_f32_16x16x32_bf16 v[20:23], v[172:175], v[196:199], v[20:23]
	v_mfma_f32_16x16x32_bf16 v[16:19], v[180:183], v[196:199], v[16:19]
	v_mfma_f32_16x16x32_bf16 v[12:15], v[172:175], v[208:211], v[12:15]
	v_mfma_f32_16x16x32_bf16 v[8:11], v[180:183], v[208:211], v[8:11]
	v_mfma_f32_16x16x32_bf16 v[4:7], v[172:175], v[216:219], v[4:7]
	v_mfma_f32_16x16x32_bf16 v[0:3], v[180:183], v[216:219], v[0:3]
	s_setprio 0
	s_barrier
	s_add_u32 s26, s26, 0x100
	s_addc_u32 s27, s27, 0
	s_add_u32 s50, s50, 0x100
	s_addc_u32 s51, s51, 0
	s_cmp_ge_i32 s52, s39
	s_mov_b32 s28, s52
	s_cbranch_scc0 .LBB0_498

; #define PG8_STAGE(bufoff, gbase, voff) do { _Pragma("unroll") for (int _i = 0; _i < 2; ++_i) \
;         __builtin_amdgcn_global_load_lds((const unsigned*)((const char*)(gbase) + (voff)[_i]), (PG8_LAS unsigned*)(lds + (bufoff) + ldsw + _i * 8192), 16, 0, 0); } while (0)
; #define PG8_LDA(dst, b, h) do { _Pragma("unroll") for (int m = 0; m < 4; ++m) _Pragma("unroll") for (int k = 0; k < 2; ++k) dst[m][k] = *(const PG8_LAS bf16x8*)(lds + PG8_SA(b, h) + aoff + m * 2048 + k * 1024); } while (0)
; #define PG8_LDB(dst, b, h) do { _Pragma("unroll") for (int n = 0; n < 2; ++n) _Pragma("unroll") for (int k = 0; k < 2; ++k) dst[n][k] = *(const PG8_LAS bf16x8*)(lds + PG8_SB(b, h) + boff + n * 2048 + k * 1024); } while (0)
; #define PG8_MMA(ai, bj, At, Bt) do { __builtin_amdgcn_s_setprio(1); _Pragma("unroll") for (int m = 0; m < 4; ++m) _Pragma("unroll") for (int n = 0; n < 2; ++n) _Pragma("unroll") for (int k = 0; k < 2; ++k) \
;         acc[ai][bj][m][n] = __builtin_amdgcn_mfma_f32_16x16x32_bf16(Bt[n][k], At[m][k], acc[ai][bj][m][n], 0, 0, 0); __builtin_amdgcn_s_setprio(0); } while (0)
; #define PG8_WAIT_V(n) asm volatile("s_waitcnt vmcnt(" #n ")" ::: "memory")
; #define PG8_BAR __builtin_amdgcn_s_barrier()
; template <class Epi, class Sched, bool ALIGN_EPI = false, bool SP2 = false>
; __device__ __forceinline__ void gemm_phase(PG8_LAS unsigned char* lds, const Gemm g, const Sched& S, const Epi& E, int tid_in) {
;     ...
;         for (int t = 0; t < nt; t += 2) {
;             const bool last = (t == nt - 2);
;             const char* a1 = cA + (size_t)(t + 1) * kstep;
;             const char* a2 = last ? nA : cA + (size_t)(t + 2) * kstep; const char* b2 = last ? nB : cB + (size_t)(t + 2) * kstep;
;             const char* a3 = a2 + kstep; const char* b3 = b2 + kstep;
;             if (last && has_next) S.a_ready(nxt);
;             if constexpr (SP2) {
;             PG8_LDB(B0, 0, 0); PG8_LDB(B1, 0, 1); PG8_SCHED; PG8_LDA(At, 0, 0); PG8_STAGE(PG8_SA(1, 1), a1 + hstepA, voffA);
;             PG8_WAIT_V(8); PG8_WAIT_L(0); PG8_BAR; PG8_MMA(0, 0, At, B0); PG8_MMA(0, 1, At, B1); PG8_BAR; PG8_SCHED;
;             PG8_LDA(At, 0, 1); PG8_STAGE(PG8_SB(0, 0), b2, voffB); PG8_STAGE(PG8_SB(0, 1), b2 + hstepB, voffB); PG8_STAGE(PG8_SA(0, 0), a2, voffA);
;             PG8_WAIT_V(8); PG8_WAIT_L(0); PG8_BAR; PG8_MMA(1, 0, At, B0); PG8_MMA(1, 1, At, B1); PG8_BAR; PG8_SCHED;
.LBB0_576:
	ds_read_b128 v[80:83], v197
	ds_read_b128 v[84:87], v197 offset:1024
	ds_read_b128 v[104:107], v197 offset:2048
	ds_read_b128 v[108:111], v197 offset:3072
	ds_read_b128 v[124:127], v198
	ds_read_b128 v[128:131], v198 offset:1024
	ds_read_b128 v[144:147], v198 offset:2048
	ds_read_b128 v[148:151], v198 offset:3072
	s_add_i32 s39, s10, 2
	s_add_u32 s6, s8, 0x100
	s_addc_u32 s7, s9, 0
	s_cmp_eq_u32 s55, s10
	s_cselect_b32 s10, s34, s6
	s_cselect_b32 s11, s35, s7
	s_cselect_b32 s65, s37, s38
	s_cselect_b32 s64, s36, s33
	s_add_i32 m0, s45, 0xc000
	ds_read_b128 v[180:183], v199
	ds_read_b128 v[184:187], v199 offset:1024
	ds_read_b128 v[188:191], v199 offset:2048
	ds_read_b128 v[210:213], v199 offset:3072
	ds_read_b128 v[214:217], v199 offset:4096
	ds_read_b128 v[218:221], v199 offset:5120
	ds_read_b128 v[222:225], v199 offset:6144
	ds_read_b128 v[226:229], v199 offset:7168
	global_load_lds_dwordx4 v172, s[8:9]
	s_add_i32 m0, s45, 0xe000
	s_nop 0
	global_load_lds_dwordx4 v174, s[8:9]
	s_waitcnt vmcnt(8)
	s_waitcnt lgkmcnt(0)
	s_barrier
	s_setprio 1
	s_waitcnt lgkmcnt(0)
	v_mfma_f32_16x16x32_bf16 v[156:159], v[80:83], v[180:183], v[156:159]
	v_mfma_f32_16x16x32_bf16 v[152:155], v[104:107], v[180:183], v[152:155]
	v_mfma_f32_16x16x32_bf16 v[132:135], v[80:83], v[188:191], v[132:135]
	v_mfma_f32_16x16x32_bf16 v[120:123], v[104:107], v[188:191], v[120:123]
	v_mfma_f32_16x16x32_bf16 v[100:103], v[80:83], v[214:217], v[100:103]
	v_mfma_f32_16x16x32_bf16 v[96:99], v[104:107], v[214:217], v[96:99]
	v_mfma_f32_16x16x32_bf16 v[76:79], v[80:83], v[222:225], v[76:79]
	v_mfma_f32_16x16x32_bf16 v[72:75], v[104:107], v[222:225], v[72:75]
	v_mfma_f32_16x16x32_bf16 v[156:159], v[84:87], v[184:187], v[156:159]
	v_mfma_f32_16x16x32_bf16 v[152:155], v[108:111], v[184:187], v[152:155]
	v_mfma_f32_16x16x32_bf16 v[132:135], v[84:87], v[210:213], v[132:135]
	v_mfma_f32_16x16x32_bf16 v[120:123], v[108:111], v[210:213], v[120:123]
	v_mfma_f32_16x16x32_bf16 v[100:103], v[84:87], v[218:221], v[100:103]
	v_mfma_f32_16x16x32_bf16 v[96:99], v[108:111], v[218:221], v[96:99]
	v_mfma_f32_16x16x32_bf16 v[76:79], v[84:87], v[226:229], v[76:79]
	v_mfma_f32_16x16x32_bf16 v[72:75], v[108:111], v[226:229], v[72:75]
	s_setprio 0
	s_setprio 1
	v_mfma_f32_16x16x32_bf16 v[140:143], v[124:127], v[180:183], v[140:143]
	v_mfma_f32_16x16x32_bf16 v[136:139], v[144:147], v[180:183], v[136:139]
	v_mfma_f32_16x16x32_bf16 v[116:119], v[124:127], v[188:191], v[116:119]
	v_mfma_f32_16x16x32_bf16 v[112:115], v[144:147], v[188:191], v[112:115]
	v_mfma_f32_16x16x32_bf16 v[92:95], v[124:127], v[214:217], v[92:95]
	v_mfma_f32_16x16x32_bf16 v[88:91], v[144:147], v[214:217], v[88:91]
	v_mfma_f32_16x16x32_bf16 v[68:71], v[124:127], v[222:225], v[68:71]
	v_mfma_f32_16x16x32_bf16 v[64:67], v[144:147], v[222:225], v[64:67]
	v_mfma_f32_16x16x32_bf16 v[140:143], v[128:131], v[184:187], v[140:143]
	v_mfma_f32_16x16x32_bf16 v[136:139], v[148:151], v[184:187], v[136:139]
	v_mfma_f32_16x16x32_bf16 v[116:119], v[128:131], v[210:213], v[116:119]
	v_mfma_f32_16x16x32_bf16 v[112:115], v[148:151], v[210:213], v[112:115]
	v_mfma_f32_16x16x32_bf16 v[92:95], v[128:131], v[218:221], v[92:95]
	v_mfma_f32_16x16x32_bf16 v[88:91], v[148:151], v[218:221], v[88:91]
	v_mfma_f32_16x16x32_bf16 v[68:71], v[128:131], v[226:229], v[68:71]
	v_mfma_f32_16x16x32_bf16 v[64:67], v[148:151], v[226:229], v[64:67]
	s_setprio 0
	s_barrier
	s_add_i32 s8, s60, s44
	v_lshl_add_u64 v[192:193], s[64:65], 0, v[162:163]
	s_mov_b32 m0, s8
	ds_read_b128 v[180:183], v199 offset:16384
	ds_read_b128 v[184:187], v199 offset:17408
	ds_read_b128 v[188:191], v199 offset:18432
	ds_read_b128 v[210:213], v199 offset:19456
	ds_read_b128 v[214:217], v199 offset:20480
	ds_read_b128 v[218:221], v199 offset:21504
	ds_read_b128 v[222:225], v199 offset:22528
	ds_read_b128 v[226:229], v199 offset:23552
	global_load_lds_dwordx4 v[192:193], off
	s_add_i32 m0, s8, 0x2000
	s_add_u32 s8, s64, s16
	v_lshl_add_u64 v[230:231], s[64:65], 0, v[166:167]
	s_addc_u32 s9, s65, s17
	s_add_i32 s63, s61, s44
	global_load_lds_dwordx4 v[230:231], off
	v_lshl_add_u64 v[232:233], s[8:9], 0, v[162:163]
	s_mov_b32 m0, s63
	v_lshl_add_u64 v[234:235], s[8:9], 0, v[166:167]
	global_load_lds_dwordx4 v[232:233], off
	s_add_i32 m0, s63, 0x2000
	v_lshl_add_u64 v[236:237], s[10:11], 0, v[160:161]
	global_load_lds_dwordx4 v[234:235], off
	s_mov_b32 m0, s45
	v_lshl_add_u64 v[238:239], s[10:11], 0, v[164:165]
	global_load_lds_dwordx4 v[236:237], off
	s_mov_b32 m0, s46
	s_nop 0
	global_load_lds_dwordx4 v[238:239], off
	s_waitcnt vmcnt(8)
	s_waitcnt lgkmcnt(0)
	s_barrier
; #define PG8_STAGE(bufoff, gbase, voff) do { _Pragma("unroll") for (int _i = 0; _i < 2; ++_i) \
;         __builtin_amdgcn_global_load_lds((const unsigned*)((const char*)(gbase) + (voff)[_i]), (PG8_LAS unsigned*)(lds + (bufoff) + ldsw + _i * 8192), 16, 0, 0); } while (0)
; #define PG8_LDA(dst, b, h) do { _Pragma("unroll") for (int m = 0; m < 4; ++m) _Pragma("unroll") for (int k = 0; k < 2; ++k) dst[m][k] = *(const PG8_LAS bf16x8*)(lds + PG8_SA(b, h) + aoff + m * 2048 + k * 1024); } while (0)
; #define PG8_LDB(dst, b, h) do { _Pragma("unroll") for (int n = 0; n < 2; ++n) _Pragma("unroll") for (int k = 0; k < 2; ++k) dst[n][k] = *(const PG8_LAS bf16x8*)(lds + PG8_SB(b, h) + boff + n * 2048 + k * 1024); } while (0)
; #define PG8_MMA(ai, bj, At, Bt) do { __builtin_amdgcn_s_setprio(1); _Pragma("unroll") for (int m = 0; m < 4; ++m) _Pragma("unroll") for (int n = 0; n < 2; ++n) _Pragma("unroll") for (int k = 0; k < 2; ++k) \
;         acc[ai][bj][m][n] = __builtin_amdgcn_mfma_f32_16x16x32_bf16(Bt[n][k], At[m][k], acc[ai][bj][m][n], 0, 0, 0); __builtin_amdgcn_s_setprio(0); } while (0)
; #define PG8_WAIT_V(n) asm volatile("s_waitcnt vmcnt(" #n ")" ::: "memory")
; #define PG8_WAIT_L(n) asm volatile("s_waitcnt lgkmcnt(" #n ")" ::: "memory")
; #define PG8_BAR __builtin_amdgcn_s_barrier()
; #define PG8_SCHED __builtin_amdgcn_sched_barrier(0)
; template <class Epi, class Sched, bool ALIGN_EPI = false, bool SP2 = false>
; __device__ __forceinline__ void gemm_phase(PG8_LAS unsigned char* lds, const Gemm g, const Sched& S, const Epi& E, int tid_in) {
;     ...
;             PG8_WAIT_V(8); PG8_WAIT_L(0); PG8_BAR; PG8_MMA(1, 0, At, B0); PG8_MMA(1, 1, At, B1); PG8_BAR; PG8_SCHED;
;             PG8_LDB(B0, 1, 0); PG8_LDB(B1, 1, 1); PG8_SCHED; PG8_LDA(At, 1, 0); PG8_STAGE(PG8_SA(0, 1), a2 + hstepA, voffA);
;             PG8_WAIT_V(8); PG8_WAIT_L(0); PG8_BAR; PG8_MMA(0, 0, At, B0); PG8_MMA(0, 1, At, B1); PG8_BAR; PG8_SCHED;
	s_setprio 1
	s_waitcnt lgkmcnt(0)
	v_mfma_f32_16x16x32_bf16 v[60:63], v[80:83], v[180:183], v[60:63]
	v_mfma_f32_16x16x32_bf16 v[56:59], v[104:107], v[180:183], v[56:59]
	v_mfma_f32_16x16x32_bf16 v[44:47], v[80:83], v[188:191], v[44:47]
	v_mfma_f32_16x16x32_bf16 v[40:43], v[104:107], v[188:191], v[40:43]
	v_mfma_f32_16x16x32_bf16 v[28:31], v[80:83], v[214:217], v[28:31]
	v_mfma_f32_16x16x32_bf16 v[24:27], v[104:107], v[214:217], v[24:27]
	v_mfma_f32_16x16x32_bf16 v[12:15], v[80:83], v[222:225], v[12:15]
	v_mfma_f32_16x16x32_bf16 v[8:11], v[104:107], v[222:225], v[8:11]
	v_mfma_f32_16x16x32_bf16 v[60:63], v[84:87], v[184:187], v[60:63]
	v_mfma_f32_16x16x32_bf16 v[56:59], v[108:111], v[184:187], v[56:59]
	v_mfma_f32_16x16x32_bf16 v[44:47], v[84:87], v[210:213], v[44:47]
	v_mfma_f32_16x16x32_bf16 v[40:43], v[108:111], v[210:213], v[40:43]
	v_mfma_f32_16x16x32_bf16 v[28:31], v[84:87], v[218:221], v[28:31]
	v_mfma_f32_16x16x32_bf16 v[24:27], v[108:111], v[218:221], v[24:27]
	v_mfma_f32_16x16x32_bf16 v[12:15], v[84:87], v[226:229], v[12:15]
	v_mfma_f32_16x16x32_bf16 v[8:11], v[108:111], v[226:229], v[8:11]
	s_setprio 0
	s_setprio 1
	v_mfma_f32_16x16x32_bf16 v[52:55], v[124:127], v[180:183], v[52:55]
	v_mfma_f32_16x16x32_bf16 v[48:51], v[144:147], v[180:183], v[48:51]
	v_mfma_f32_16x16x32_bf16 v[36:39], v[124:127], v[188:191], v[36:39]
	v_mfma_f32_16x16x32_bf16 v[32:35], v[144:147], v[188:191], v[32:35]
	v_mfma_f32_16x16x32_bf16 v[20:23], v[124:127], v[214:217], v[20:23]
	v_mfma_f32_16x16x32_bf16 v[16:19], v[144:147], v[214:217], v[16:19]
	v_mfma_f32_16x16x32_bf16 v[4:7], v[124:127], v[222:225], v[4:7]
	v_mfma_f32_16x16x32_bf16 v[0:3], v[144:147], v[222:225], v[0:3]
	v_mfma_f32_16x16x32_bf16 v[52:55], v[128:131], v[184:187], v[52:55]
	v_mfma_f32_16x16x32_bf16 v[48:51], v[148:151], v[184:187], v[48:51]
	v_mfma_f32_16x16x32_bf16 v[36:39], v[128:131], v[210:213], v[36:39]
	v_mfma_f32_16x16x32_bf16 v[32:35], v[148:151], v[210:213], v[32:35]
	v_mfma_f32_16x16x32_bf16 v[20:23], v[128:131], v[218:221], v[20:23]
	v_mfma_f32_16x16x32_bf16 v[16:19], v[148:151], v[218:221], v[16:19]
	v_mfma_f32_16x16x32_bf16 v[4:7], v[128:131], v[226:229], v[4:7]
	v_mfma_f32_16x16x32_bf16 v[0:3], v[148:151], v[226:229], v[0:3]
	s_setprio 0
	s_barrier
	s_add_i32 s63, 0, 0x18000
	s_add_i32 s64, 0, 0x1c000
	v_add_u32_e32 v108, s63, v195
	v_add_u32_e32 v148, s64, v195
	ds_read_b128 v[80:83], v108
	ds_read_b128 v[84:87], v108 offset:1024
	ds_read_b128 v[104:107], v108 offset:2048
	ds_read_b128 v[108:111], v108 offset:3072
	ds_read_b128 v[124:127], v148
	ds_read_b128 v[128:131], v148 offset:1024
	ds_read_b128 v[144:147], v148 offset:2048
	ds_read_b128 v[148:151], v148 offset:3072
	s_add_u32 s8, s10, 0x30000
	s_addc_u32 s9, s11, 0
	s_mov_b32 m0, s47
	ds_read_b128 v[180:183], v199 offset:32768
	ds_read_b128 v[184:187], v199 offset:33792
	ds_read_b128 v[188:191], v199 offset:34816
	ds_read_b128 v[210:213], v199 offset:35840
	ds_read_b128 v[214:217], v199 offset:36864
	ds_read_b128 v[218:221], v199 offset:37888
	ds_read_b128 v[222:225], v199 offset:38912
	ds_read_b128 v[226:229], v199 offset:39936
	global_load_lds_dwordx4 v160, s[8:9]
	s_mov_b32 m0, s48
	s_nop 0
	global_load_lds_dwordx4 v164, s[8:9]
	s_waitcnt vmcnt(8)
	s_waitcnt lgkmcnt(0)
	s_barrier
	s_setprio 1
	s_waitcnt lgkmcnt(0)
	v_mfma_f32_16x16x32_bf16 v[156:159], v[80:83], v[180:183], v[156:159]
	v_mfma_f32_16x16x32_bf16 v[152:155], v[104:107], v[180:183], v[152:155]
	v_mfma_f32_16x16x32_bf16 v[132:135], v[80:83], v[188:191], v[132:135]
	v_mfma_f32_16x16x32_bf16 v[120:123], v[104:107], v[188:191], v[120:123]
	v_mfma_f32_16x16x32_bf16 v[100:103], v[80:83], v[214:217], v[100:103]
	v_mfma_f32_16x16x32_bf16 v[96:99], v[104:107], v[214:217], v[96:99]
	v_mfma_f32_16x16x32_bf16 v[76:79], v[80:83], v[222:225], v[76:79]
	v_mfma_f32_16x16x32_bf16 v[72:75], v[104:107], v[222:225], v[72:75]
	v_mfma_f32_16x16x32_bf16 v[156:159], v[84:87], v[184:187], v[156:159]
	v_mfma_f32_16x16x32_bf16 v[152:155], v[108:111], v[184:187], v[152:155]
	v_mfma_f32_16x16x32_bf16 v[132:135], v[84:87], v[210:213], v[132:135]
	v_mfma_f32_16x16x32_bf16 v[120:123], v[108:111], v[210:213], v[120:123]
	v_mfma_f32_16x16x32_bf16 v[100:103], v[84:87], v[218:221], v[100:103]
	v_mfma_f32_16x16x32_bf16 v[96:99], v[108:111], v[218:221], v[96:99]
	v_mfma_f32_16x16x32_bf16 v[76:79], v[84:87], v[226:229], v[76:79]
	v_mfma_f32_16x16x32_bf16 v[72:75], v[108:111], v[226:229], v[72:75]
	s_setprio 0
	s_setprio 1
	v_mfma_f32_16x16x32_bf16 v[140:143], v[124:127], v[180:183], v[140:143]
	v_mfma_f32_16x16x32_bf16 v[136:139], v[144:147], v[180:183], v[136:139]
	v_mfma_f32_16x16x32_bf16 v[116:119], v[124:127], v[188:191], v[116:119]
	v_mfma_f32_16x16x32_bf16 v[112:115], v[144:147], v[188:191], v[112:115]
	v_mfma_f32_16x16x32_bf16 v[92:95], v[124:127], v[214:217], v[92:95]
	v_mfma_f32_16x16x32_bf16 v[88:91], v[144:147], v[214:217], v[88:91]
	v_mfma_f32_16x16x32_bf16 v[68:71], v[124:127], v[222:225], v[68:71]
	v_mfma_f32_16x16x32_bf16 v[64:67], v[144:147], v[222:225], v[64:67]
	v_mfma_f32_16x16x32_bf16 v[140:143], v[128:131], v[184:187], v[140:143]
	v_mfma_f32_16x16x32_bf16 v[136:139], v[148:151], v[184:187], v[136:139]
	v_mfma_f32_16x16x32_bf16 v[116:119], v[128:131], v[210:213], v[116:119]
	v_mfma_f32_16x16x32_bf16 v[112:115], v[148:151], v[210:213], v[112:115]
	v_mfma_f32_16x16x32_bf16 v[92:95], v[128:131], v[218:221], v[92:95]
	v_mfma_f32_16x16x32_bf16 v[88:91], v[148:151], v[218:221], v[88:91]
	v_mfma_f32_16x16x32_bf16 v[68:71], v[128:131], v[226:229], v[68:71]
	v_mfma_f32_16x16x32_bf16 v[64:67], v[148:151], v[226:229], v[64:67]
	s_setprio 0
	s_barrier
; #define PG8_STAGE(bufoff, gbase, voff) do { _Pragma("unroll") for (int _i = 0; _i < 2; ++_i) \
;         __builtin_amdgcn_global_load_lds((const unsigned*)((const char*)(gbase) + (voff)[_i]), (PG8_LAS unsigned*)(lds + (bufoff) + ldsw + _i * 8192), 16, 0, 0); } while (0)
; #define PG8_LDA(dst, b, h) do { _Pragma("unroll") for (int m = 0; m < 4; ++m) _Pragma("unroll") for (int k = 0; k < 2; ++k) dst[m][k] = *(const PG8_LAS bf16x8*)(lds + PG8_SA(b, h) + aoff + m * 2048 + k * 1024); } while (0)
; #define PG8_MMA(ai, bj, At, Bt) do { __builtin_amdgcn_s_setprio(1); _Pragma("unroll") for (int m = 0; m < 4; ++m) _Pragma("unroll") for (int n = 0; n < 2; ++n) _Pragma("unroll") for (int k = 0; k < 2; ++k) \
;         acc[ai][bj][m][n] = __builtin_amdgcn_mfma_f32_16x16x32_bf16(Bt[n][k], At[m][k], acc[ai][bj][m][n], 0, 0, 0); __builtin_amdgcn_s_setprio(0); } while (0)
; #define PG8_WAIT_V(n) asm volatile("s_waitcnt vmcnt(" #n ")" ::: "memory")
; #define PG8_WAIT_L(n) asm volatile("s_waitcnt lgkmcnt(" #n ")" ::: "memory")
; #define PG8_BAR __builtin_amdgcn_s_barrier()
; #define PG8_SCHED __builtin_amdgcn_sched_barrier(0)
; template <class Epi, class Sched, bool ALIGN_EPI = false, bool SP2 = false>
; __device__ __forceinline__ void gemm_phase(PG8_LAS unsigned char* lds, const Gemm g, const Sched& S, const Epi& E, int tid_in) {
;     ...
;         for (int t = 0; t < nt; t += 2) {
;     ...
;             PG8_LDA(At, 1, 1); PG8_STAGE(PG8_SB(1, 0), b3, voffB); PG8_STAGE(PG8_SB(1, 1), b3 + hstepB, voffB); PG8_STAGE(PG8_SA(1, 0), a3, voffA);
;             PG8_WAIT_V(8); PG8_WAIT_L(0); PG8_BAR; PG8_MMA(1, 0, At, B0); PG8_MMA(1, 1, At, B1); PG8_BAR; PG8_SCHED;
	s_add_i32 s8, s63, s44
	v_lshl_add_u64 v[192:193], v[192:193], 0, s[26:27]
	s_mov_b32 m0, s8
	ds_read_b128 v[180:183], v199 offset:49152
	ds_read_b128 v[184:187], v199 offset:50176
	ds_read_b128 v[188:191], v199 offset:51200
	ds_read_b128 v[210:213], v199 offset:52224
	ds_read_b128 v[214:217], v199 offset:53248
	ds_read_b128 v[218:221], v199 offset:54272
	ds_read_b128 v[222:225], v199 offset:55296
	ds_read_b128 v[226:229], v199 offset:56320
	global_load_lds_dwordx4 v[192:193], off
	v_lshl_add_u64 v[192:193], v[230:231], 0, s[26:27]
	s_add_i32 m0, s8, 0x2000
	s_add_i32 s8, s64, s44
	global_load_lds_dwordx4 v[192:193], off
	v_lshl_add_u64 v[192:193], v[232:233], 0, s[26:27]
	s_mov_b32 m0, s8
	s_nop 0
	global_load_lds_dwordx4 v[192:193], off
	v_lshl_add_u64 v[192:193], v[234:235], 0, s[26:27]
	s_add_i32 m0, s8, 0x2000
	s_nop 0
	global_load_lds_dwordx4 v[192:193], off
	v_lshl_add_u64 v[192:193], v[236:237], 0, s[26:27]
	s_mov_b32 m0, s51
	s_nop 0
	global_load_lds_dwordx4 v[192:193], off
	v_lshl_add_u64 v[192:193], v[238:239], 0, s[26:27]
	s_mov_b32 m0, s52
	s_nop 0
	global_load_lds_dwordx4 v[192:193], off
	s_waitcnt vmcnt(8)
	s_waitcnt lgkmcnt(0)
	s_barrier
	s_setprio 1
	s_waitcnt lgkmcnt(0)
	v_mfma_f32_16x16x32_bf16 v[60:63], v[80:83], v[180:183], v[60:63]
	v_mfma_f32_16x16x32_bf16 v[56:59], v[104:107], v[180:183], v[56:59]
	v_mfma_f32_16x16x32_bf16 v[44:47], v[80:83], v[188:191], v[44:47]
	v_mfma_f32_16x16x32_bf16 v[40:43], v[104:107], v[188:191], v[40:43]
	v_mfma_f32_16x16x32_bf16 v[28:31], v[80:83], v[214:217], v[28:31]
	v_mfma_f32_16x16x32_bf16 v[24:27], v[104:107], v[214:217], v[24:27]
	v_mfma_f32_16x16x32_bf16 v[12:15], v[80:83], v[222:225], v[12:15]
	v_mfma_f32_16x16x32_bf16 v[8:11], v[104:107], v[222:225], v[8:11]
	v_mfma_f32_16x16x32_bf16 v[60:63], v[84:87], v[184:187], v[60:63]
	v_mfma_f32_16x16x32_bf16 v[56:59], v[108:111], v[184:187], v[56:59]
	v_mfma_f32_16x16x32_bf16 v[44:47], v[84:87], v[210:213], v[44:47]
	v_mfma_f32_16x16x32_bf16 v[40:43], v[108:111], v[210:213], v[40:43]
	v_mfma_f32_16x16x32_bf16 v[28:31], v[84:87], v[218:221], v[28:31]
	v_mfma_f32_16x16x32_bf16 v[24:27], v[108:111], v[218:221], v[24:27]
	v_mfma_f32_16x16x32_bf16 v[12:15], v[84:87], v[226:229], v[12:15]
	v_mfma_f32_16x16x32_bf16 v[8:11], v[108:111], v[226:229], v[8:11]
	s_setprio 0
	s_setprio 1
	v_mfma_f32_16x16x32_bf16 v[52:55], v[124:127], v[180:183], v[52:55]
	v_mfma_f32_16x16x32_bf16 v[48:51], v[144:147], v[180:183], v[48:51]
	v_mfma_f32_16x16x32_bf16 v[36:39], v[124:127], v[188:191], v[36:39]
	v_mfma_f32_16x16x32_bf16 v[32:35], v[144:147], v[188:191], v[32:35]
	v_mfma_f32_16x16x32_bf16 v[20:23], v[124:127], v[214:217], v[20:23]
	v_mfma_f32_16x16x32_bf16 v[16:19], v[144:147], v[214:217], v[16:19]
	v_mfma_f32_16x16x32_bf16 v[4:7], v[124:127], v[222:225], v[4:7]
	v_mfma_f32_16x16x32_bf16 v[0:3], v[144:147], v[222:225], v[0:3]
	v_mfma_f32_16x16x32_bf16 v[52:55], v[128:131], v[184:187], v[52:55]
	v_mfma_f32_16x16x32_bf16 v[48:51], v[148:151], v[184:187], v[48:51]
	v_mfma_f32_16x16x32_bf16 v[36:39], v[128:131], v[210:213], v[36:39]
	v_mfma_f32_16x16x32_bf16 v[32:35], v[148:151], v[210:213], v[32:35]
	v_mfma_f32_16x16x32_bf16 v[20:23], v[128:131], v[218:221], v[20:23]
	v_mfma_f32_16x16x32_bf16 v[16:19], v[148:151], v[218:221], v[16:19]
	v_mfma_f32_16x16x32_bf16 v[4:7], v[128:131], v[226:229], v[4:7]
	v_mfma_f32_16x16x32_bf16 v[0:3], v[148:151], v[226:229], v[0:3]
	s_setprio 0
	s_barrier
	s_add_u32 s33, s33, 0x100
	s_addc_u32 s38, s38, 0
	s_cmp_ge_i32 s39, s54
	s_mov_b64 s[8:9], s[6:7]
	s_mov_b32 s10, s39
	s_cbranch_scc0 .LBB0_576

; #define PG8_STAGE(bufoff, gbase, voff) do { _Pragma("unroll") for (int _i = 0; _i < 2; ++_i) \
;         __builtin_amdgcn_global_load_lds((const unsigned*)((const char*)(gbase) + (voff)[_i]), (PG8_LAS unsigned*)(lds + (bufoff) + ldsw + _i * 8192), 16, 0, 0); } while (0)
; #define PG8_LDA(dst, b, h) do { _Pragma("unroll") for (int m = 0; m < 4; ++m) _Pragma("unroll") for (int k = 0; k < 2; ++k) dst[m][k] = *(const PG8_LAS bf16x8*)(lds + PG8_SA(b, h) + aoff + m * 2048 + k * 1024); } while (0)
; #define PG8_LDB(dst, b, h) do { _Pragma("unroll") for (int n = 0; n < 2; ++n) _Pragma("unroll") for (int k = 0; k < 2; ++k) dst[n][k] = *(const PG8_LAS bf16x8*)(lds + PG8_SB(b, h) + boff + n * 2048 + k * 1024); } while (0)
; #define PG8_MMA(ai, bj, At, Bt) do { __builtin_amdgcn_s_setprio(1); _Pragma("unroll") for (int m = 0; m < 4; ++m) _Pragma("unroll") for (int n = 0; n < 2; ++n) _Pragma("unroll") for (int k = 0; k < 2; ++k) \
;         acc[ai][bj][m][n] = __builtin_amdgcn_mfma_f32_16x16x32_bf16(Bt[n][k], At[m][k], acc[ai][bj][m][n], 0, 0, 0); __builtin_amdgcn_s_setprio(0); } while (0)
; #define PG8_WAIT_V(n) asm volatile("s_waitcnt vmcnt(" #n ")" ::: "memory")
; #define PG8_BAR __builtin_amdgcn_s_barrier()
; template <class Epi, class Sched, bool ALIGN_EPI = false, bool SP2 = false>
; __device__ __forceinline__ void gemm_phase(PG8_LAS unsigned char* lds, const Gemm g, const Sched& S, const Epi& E, int tid_in) {
;     ...
;         for (int t = 0; t < nt; t += 2) {
;             const bool last = (t == nt - 2);
;             const char* a1 = cA + (size_t)(t + 1) * kstep;
;             const char* a2 = last ? nA : cA + (size_t)(t + 2) * kstep; const char* b2 = last ? nB : cB + (size_t)(t + 2) * kstep;
;             const char* a3 = a2 + kstep; const char* b3 = b2 + kstep;
;             if (last && has_next) S.a_ready(nxt);
;             if constexpr (SP2) {
;             PG8_LDB(B0, 0, 0); PG8_LDB(B1, 0, 1); PG8_SCHED; PG8_LDA(At, 0, 0); PG8_STAGE(PG8_SA(1, 1), a1 + hstepA, voffA);
;             PG8_WAIT_V(8); PG8_WAIT_L(0); PG8_BAR; PG8_MMA(0, 0, At, B0); PG8_MMA(0, 1, At, B1); PG8_BAR; PG8_SCHED;
;             PG8_LDA(At, 0, 1); PG8_STAGE(PG8_SB(0, 0), b2, voffB); PG8_STAGE(PG8_SB(0, 1), b2 + hstepB, voffB); PG8_STAGE(PG8_SA(0, 0), a2, voffA);
;             PG8_WAIT_V(8); PG8_WAIT_L(0); PG8_BAR; PG8_MMA(1, 0, At, B0); PG8_MMA(1, 1, At, B1); PG8_BAR; PG8_SCHED;
.LBB0_633:
	ds_read_b128 v[144:147], v159
	ds_read_b128 v[148:151], v159 offset:1024
	ds_read_b128 v[152:155], v159 offset:2048
	ds_read_b128 v[164:167], v159 offset:3072
	ds_read_b128 v[168:171], v160
	ds_read_b128 v[172:175], v160 offset:1024
	ds_read_b128 v[176:179], v160 offset:2048
	ds_read_b128 v[180:183], v160 offset:3072
	s_add_i32 s60, s38, 2
	s_add_u32 s36, s34, 0x100
	s_addc_u32 s37, s35, 0
	s_cmp_eq_u32 s49, s38
	s_cselect_b32 s38, s8, s36
	s_cselect_b32 s39, s9, s37
	s_cselect_b32 s63, s31, s59
	s_cselect_b32 s62, s30, s58
	s_add_i32 m0, s33, 0xc000
	ds_read_b128 v[184:187], v161
	ds_read_b128 v[188:191], v161 offset:1024
	ds_read_b128 v[192:195], v161 offset:2048
	ds_read_b128 v[196:199], v161 offset:3072
	ds_read_b128 v[200:203], v161 offset:4096
	ds_read_b128 v[208:211], v161 offset:5120
	ds_read_b128 v[212:215], v161 offset:6144
	ds_read_b128 v[216:219], v161 offset:7168
	global_load_lds_dwordx4 v136, s[34:35]
	s_add_i32 m0, s33, 0xe000
	s_nop 0
	global_load_lds_dwordx4 v138, s[34:35]
	s_waitcnt vmcnt(8)
	s_waitcnt lgkmcnt(0)
	s_barrier
	s_setprio 1
	s_waitcnt lgkmcnt(0)
	v_mfma_f32_16x16x32_bf16 v[120:123], v[144:147], v[184:187], v[120:123]
	v_mfma_f32_16x16x32_bf16 v[124:127], v[152:155], v[184:187], v[124:127]
	v_mfma_f32_16x16x32_bf16 v[108:111], v[144:147], v[192:195], v[108:111]
	v_mfma_f32_16x16x32_bf16 v[104:107], v[152:155], v[192:195], v[104:107]
	v_mfma_f32_16x16x32_bf16 v[92:95], v[144:147], v[200:203], v[92:95]
	v_mfma_f32_16x16x32_bf16 v[88:91], v[152:155], v[200:203], v[88:91]
	v_mfma_f32_16x16x32_bf16 v[76:79], v[144:147], v[212:215], v[76:79]
	v_mfma_f32_16x16x32_bf16 v[72:75], v[152:155], v[212:215], v[72:75]
	v_mfma_f32_16x16x32_bf16 v[120:123], v[148:151], v[188:191], v[120:123]
	v_mfma_f32_16x16x32_bf16 v[124:127], v[164:167], v[188:191], v[124:127]
	v_mfma_f32_16x16x32_bf16 v[108:111], v[148:151], v[196:199], v[108:111]
	v_mfma_f32_16x16x32_bf16 v[104:107], v[164:167], v[196:199], v[104:107]
	v_mfma_f32_16x16x32_bf16 v[92:95], v[148:151], v[208:211], v[92:95]
	v_mfma_f32_16x16x32_bf16 v[88:91], v[164:167], v[208:211], v[88:91]
	v_mfma_f32_16x16x32_bf16 v[76:79], v[148:151], v[216:219], v[76:79]
	v_mfma_f32_16x16x32_bf16 v[72:75], v[164:167], v[216:219], v[72:75]
	s_setprio 0
	s_setprio 1
	v_mfma_f32_16x16x32_bf16 v[116:119], v[168:171], v[184:187], v[116:119]
	v_mfma_f32_16x16x32_bf16 v[112:115], v[176:179], v[184:187], v[112:115]
	v_mfma_f32_16x16x32_bf16 v[100:103], v[168:171], v[192:195], v[100:103]
	v_mfma_f32_16x16x32_bf16 v[96:99], v[176:179], v[192:195], v[96:99]
	v_mfma_f32_16x16x32_bf16 v[84:87], v[168:171], v[200:203], v[84:87]
	v_mfma_f32_16x16x32_bf16 v[80:83], v[176:179], v[200:203], v[80:83]
	v_mfma_f32_16x16x32_bf16 v[68:71], v[168:171], v[212:215], v[68:71]
	v_mfma_f32_16x16x32_bf16 v[64:67], v[176:179], v[212:215], v[64:67]
	v_mfma_f32_16x16x32_bf16 v[116:119], v[172:175], v[188:191], v[116:119]
	v_mfma_f32_16x16x32_bf16 v[112:115], v[180:183], v[188:191], v[112:115]
	v_mfma_f32_16x16x32_bf16 v[100:103], v[172:175], v[196:199], v[100:103]
	v_mfma_f32_16x16x32_bf16 v[96:99], v[180:183], v[196:199], v[96:99]
	v_mfma_f32_16x16x32_bf16 v[84:87], v[172:175], v[208:211], v[84:87]
	v_mfma_f32_16x16x32_bf16 v[80:83], v[180:183], v[208:211], v[80:83]
	v_mfma_f32_16x16x32_bf16 v[68:71], v[172:175], v[216:219], v[68:71]
	v_mfma_f32_16x16x32_bf16 v[64:67], v[180:183], v[216:219], v[64:67]
	s_setprio 0
	s_barrier
	s_add_i32 s34, s52, s2
	v_lshl_add_u64 v[204:205], s[62:63], 0, v[132:133]
	s_mov_b32 m0, s34
	ds_read_b128 v[184:187], v161 offset:16384
	ds_read_b128 v[188:191], v161 offset:17408
	ds_read_b128 v[192:195], v161 offset:18432
	ds_read_b128 v[196:199], v161 offset:19456
	ds_read_b128 v[200:203], v161 offset:20480
	ds_read_b128 v[208:211], v161 offset:21504
	ds_read_b128 v[212:215], v161 offset:22528
	ds_read_b128 v[216:219], v161 offset:23552
	global_load_lds_dwordx4 v[204:205], off
	s_add_i32 m0, s34, 0x2000
	s_add_u32 s34, s62, s12
	v_lshl_add_u64 v[220:221], s[62:63], 0, v[128:129]
	s_addc_u32 s35, s63, s13
	s_add_i32 s61, s53, s2
	global_load_lds_dwordx4 v[220:221], off
	v_lshl_add_u64 v[222:223], s[34:35], 0, v[132:133]
	s_mov_b32 m0, s61
	v_lshl_add_u64 v[224:225], s[34:35], 0, v[128:129]
	global_load_lds_dwordx4 v[222:223], off
	s_add_i32 m0, s61, 0x2000
	v_lshl_add_u64 v[226:227], s[38:39], 0, v[134:135]
	global_load_lds_dwordx4 v[224:225], off
	s_mov_b32 m0, s33
	v_lshl_add_u64 v[228:229], s[38:39], 0, v[130:131]
	global_load_lds_dwordx4 v[226:227], off
	s_mov_b32 m0, s42
	s_nop 0
	global_load_lds_dwordx4 v[228:229], off
	s_waitcnt vmcnt(8)
	s_waitcnt lgkmcnt(0)
	s_barrier
; #define PG8_STAGE(bufoff, gbase, voff) do { _Pragma("unroll") for (int _i = 0; _i < 2; ++_i) \
;         __builtin_amdgcn_global_load_lds((const unsigned*)((const char*)(gbase) + (voff)[_i]), (PG8_LAS unsigned*)(lds + (bufoff) + ldsw + _i * 8192), 16, 0, 0); } while (0)
; #define PG8_LDA(dst, b, h) do { _Pragma("unroll") for (int m = 0; m < 4; ++m) _Pragma("unroll") for (int k = 0; k < 2; ++k) dst[m][k] = *(const PG8_LAS bf16x8*)(lds + PG8_SA(b, h) + aoff + m * 2048 + k * 1024); } while (0)
; #define PG8_LDB(dst, b, h) do { _Pragma("unroll") for (int n = 0; n < 2; ++n) _Pragma("unroll") for (int k = 0; k < 2; ++k) dst[n][k] = *(const PG8_LAS bf16x8*)(lds + PG8_SB(b, h) + boff + n * 2048 + k * 1024); } while (0)
; #define PG8_MMA(ai, bj, At, Bt) do { __builtin_amdgcn_s_setprio(1); _Pragma("unroll") for (int m = 0; m < 4; ++m) _Pragma("unroll") for (int n = 0; n < 2; ++n) _Pragma("unroll") for (int k = 0; k < 2; ++k) \
;         acc[ai][bj][m][n] = __builtin_amdgcn_mfma_f32_16x16x32_bf16(Bt[n][k], At[m][k], acc[ai][bj][m][n], 0, 0, 0); __builtin_amdgcn_s_setprio(0); } while (0)
; #define PG8_WAIT_V(n) asm volatile("s_waitcnt vmcnt(" #n ")" ::: "memory")
; #define PG8_WAIT_L(n) asm volatile("s_waitcnt lgkmcnt(" #n ")" ::: "memory")
; #define PG8_BAR __builtin_amdgcn_s_barrier()
; #define PG8_SCHED __builtin_amdgcn_sched_barrier(0)
; template <class Epi, class Sched, bool ALIGN_EPI = false, bool SP2 = false>
; __device__ __forceinline__ void gemm_phase(PG8_LAS unsigned char* lds, const Gemm g, const Sched& S, const Epi& E, int tid_in) {
;     ...
;             PG8_WAIT_V(8); PG8_WAIT_L(0); PG8_BAR; PG8_MMA(1, 0, At, B0); PG8_MMA(1, 1, At, B1); PG8_BAR; PG8_SCHED;
;             PG8_LDB(B0, 1, 0); PG8_LDB(B1, 1, 1); PG8_SCHED; PG8_LDA(At, 1, 0); PG8_STAGE(PG8_SA(0, 1), a2 + hstepA, voffA);
;             PG8_WAIT_V(8); PG8_WAIT_L(0); PG8_BAR; PG8_MMA(0, 0, At, B0); PG8_MMA(0, 1, At, B1); PG8_BAR; PG8_SCHED;
	s_setprio 1
	s_waitcnt lgkmcnt(0)
	v_mfma_f32_16x16x32_bf16 v[60:63], v[144:147], v[184:187], v[60:63]
	v_mfma_f32_16x16x32_bf16 v[56:59], v[152:155], v[184:187], v[56:59]
	v_mfma_f32_16x16x32_bf16 v[44:47], v[144:147], v[192:195], v[44:47]
	v_mfma_f32_16x16x32_bf16 v[40:43], v[152:155], v[192:195], v[40:43]
	v_mfma_f32_16x16x32_bf16 v[28:31], v[144:147], v[200:203], v[28:31]
	v_mfma_f32_16x16x32_bf16 v[24:27], v[152:155], v[200:203], v[24:27]
	v_mfma_f32_16x16x32_bf16 v[12:15], v[144:147], v[212:215], v[12:15]
	v_mfma_f32_16x16x32_bf16 v[8:11], v[152:155], v[212:215], v[8:11]
	v_mfma_f32_16x16x32_bf16 v[60:63], v[148:151], v[188:191], v[60:63]
	v_mfma_f32_16x16x32_bf16 v[56:59], v[164:167], v[188:191], v[56:59]
	v_mfma_f32_16x16x32_bf16 v[44:47], v[148:151], v[196:199], v[44:47]
	v_mfma_f32_16x16x32_bf16 v[40:43], v[164:167], v[196:199], v[40:43]
	v_mfma_f32_16x16x32_bf16 v[28:31], v[148:151], v[208:211], v[28:31]
	v_mfma_f32_16x16x32_bf16 v[24:27], v[164:167], v[208:211], v[24:27]
	v_mfma_f32_16x16x32_bf16 v[12:15], v[148:151], v[216:219], v[12:15]
	v_mfma_f32_16x16x32_bf16 v[8:11], v[164:167], v[216:219], v[8:11]
	s_setprio 0
	s_setprio 1
	v_mfma_f32_16x16x32_bf16 v[52:55], v[168:171], v[184:187], v[52:55]
	v_mfma_f32_16x16x32_bf16 v[48:51], v[176:179], v[184:187], v[48:51]
	v_mfma_f32_16x16x32_bf16 v[36:39], v[168:171], v[192:195], v[36:39]
	v_mfma_f32_16x16x32_bf16 v[32:35], v[176:179], v[192:195], v[32:35]
	v_mfma_f32_16x16x32_bf16 v[20:23], v[168:171], v[200:203], v[20:23]
	v_mfma_f32_16x16x32_bf16 v[16:19], v[176:179], v[200:203], v[16:19]
	v_mfma_f32_16x16x32_bf16 v[4:7], v[168:171], v[212:215], v[4:7]
	v_mfma_f32_16x16x32_bf16 v[0:3], v[176:179], v[212:215], v[0:3]
	v_mfma_f32_16x16x32_bf16 v[52:55], v[172:175], v[188:191], v[52:55]
	v_mfma_f32_16x16x32_bf16 v[48:51], v[180:183], v[188:191], v[48:51]
	v_mfma_f32_16x16x32_bf16 v[36:39], v[172:175], v[196:199], v[36:39]
	v_mfma_f32_16x16x32_bf16 v[32:35], v[180:183], v[196:199], v[32:35]
	v_mfma_f32_16x16x32_bf16 v[20:23], v[172:175], v[208:211], v[20:23]
	v_mfma_f32_16x16x32_bf16 v[16:19], v[180:183], v[208:211], v[16:19]
	v_mfma_f32_16x16x32_bf16 v[4:7], v[172:175], v[216:219], v[4:7]
	v_mfma_f32_16x16x32_bf16 v[0:3], v[180:183], v[216:219], v[0:3]
	s_setprio 0
	s_barrier
	s_add_i32 s61, 0, 0x18000
	v_add_u32_e32 v163, s61, v157
	s_add_i32 s62, 0, 0x1c000
	ds_read_b128 v[144:147], v163
	ds_read_b128 v[148:151], v163 offset:1024
	ds_read_b128 v[152:155], v163 offset:2048
	ds_read_b128 v[164:167], v163 offset:3072
	v_add_u32_e32 v163, s62, v157
	ds_read_b128 v[168:171], v163
	ds_read_b128 v[172:175], v163 offset:1024
	ds_read_b128 v[176:179], v163 offset:2048
	ds_read_b128 v[180:183], v163 offset:3072
	s_add_u32 s34, s38, 0x30000
	s_addc_u32 s35, s39, 0
	s_mov_b32 m0, s43
	ds_read_b128 v[184:187], v161 offset:32768
	ds_read_b128 v[188:191], v161 offset:33792
	ds_read_b128 v[192:195], v161 offset:34816
	ds_read_b128 v[196:199], v161 offset:35840
	ds_read_b128 v[200:203], v161 offset:36864
	ds_read_b128 v[208:211], v161 offset:37888
	ds_read_b128 v[212:215], v161 offset:38912
	ds_read_b128 v[216:219], v161 offset:39936
	global_load_lds_dwordx4 v134, s[34:35]
	s_mov_b32 m0, s44
	s_nop 0
	global_load_lds_dwordx4 v130, s[34:35]
	s_waitcnt vmcnt(8)
	s_waitcnt lgkmcnt(0)
	s_barrier
	s_setprio 1
	s_waitcnt lgkmcnt(0)
	v_mfma_f32_16x16x32_bf16 v[120:123], v[144:147], v[184:187], v[120:123]
	v_mfma_f32_16x16x32_bf16 v[124:127], v[152:155], v[184:187], v[124:127]
	v_mfma_f32_16x16x32_bf16 v[108:111], v[144:147], v[192:195], v[108:111]
	v_mfma_f32_16x16x32_bf16 v[104:107], v[152:155], v[192:195], v[104:107]
	v_mfma_f32_16x16x32_bf16 v[92:95], v[144:147], v[200:203], v[92:95]
	v_mfma_f32_16x16x32_bf16 v[88:91], v[152:155], v[200:203], v[88:91]
	v_mfma_f32_16x16x32_bf16 v[76:79], v[144:147], v[212:215], v[76:79]
	v_mfma_f32_16x16x32_bf16 v[72:75], v[152:155], v[212:215], v[72:75]
	v_mfma_f32_16x16x32_bf16 v[120:123], v[148:151], v[188:191], v[120:123]
	v_mfma_f32_16x16x32_bf16 v[124:127], v[164:167], v[188:191], v[124:127]
	v_mfma_f32_16x16x32_bf16 v[108:111], v[148:151], v[196:199], v[108:111]
	v_mfma_f32_16x16x32_bf16 v[104:107], v[164:167], v[196:199], v[104:107]
	v_mfma_f32_16x16x32_bf16 v[92:95], v[148:151], v[208:211], v[92:95]
	v_mfma_f32_16x16x32_bf16 v[88:91], v[164:167], v[208:211], v[88:91]
	v_mfma_f32_16x16x32_bf16 v[76:79], v[148:151], v[216:219], v[76:79]
	v_mfma_f32_16x16x32_bf16 v[72:75], v[164:167], v[216:219], v[72:75]
	s_setprio 0
	s_setprio 1
	v_mfma_f32_16x16x32_bf16 v[116:119], v[168:171], v[184:187], v[116:119]
	v_mfma_f32_16x16x32_bf16 v[112:115], v[176:179], v[184:187], v[112:115]
	v_mfma_f32_16x16x32_bf16 v[100:103], v[168:171], v[192:195], v[100:103]
	v_mfma_f32_16x16x32_bf16 v[96:99], v[176:179], v[192:195], v[96:99]
	v_mfma_f32_16x16x32_bf16 v[84:87], v[168:171], v[200:203], v[84:87]
	v_mfma_f32_16x16x32_bf16 v[80:83], v[176:179], v[200:203], v[80:83]
	v_mfma_f32_16x16x32_bf16 v[68:71], v[168:171], v[212:215], v[68:71]
	v_mfma_f32_16x16x32_bf16 v[64:67], v[176:179], v[212:215], v[64:67]
	v_mfma_f32_16x16x32_bf16 v[116:119], v[172:175], v[188:191], v[116:119]
	v_mfma_f32_16x16x32_bf16 v[112:115], v[180:183], v[188:191], v[112:115]
	v_mfma_f32_16x16x32_bf16 v[100:103], v[172:175], v[196:199], v[100:103]
	v_mfma_f32_16x16x32_bf16 v[96:99], v[180:183], v[196:199], v[96:99]
	v_mfma_f32_16x16x32_bf16 v[84:87], v[172:175], v[208:211], v[84:87]
	v_mfma_f32_16x16x32_bf16 v[80:83], v[180:183], v[208:211], v[80:83]
	v_mfma_f32_16x16x32_bf16 v[68:71], v[172:175], v[216:219], v[68:71]
	v_mfma_f32_16x16x32_bf16 v[64:67], v[180:183], v[216:219], v[64:67]
	s_setprio 0
	s_barrier
; #define PG8_STAGE(bufoff, gbase, voff) do { _Pragma("unroll") for (int _i = 0; _i < 2; ++_i) \
;         __builtin_amdgcn_global_load_lds((const unsigned*)((const char*)(gbase) + (voff)[_i]), (PG8_LAS unsigned*)(lds + (bufoff) + ldsw + _i * 8192), 16, 0, 0); } while (0)
; #define PG8_LDA(dst, b, h) do { _Pragma("unroll") for (int m = 0; m < 4; ++m) _Pragma("unroll") for (int k = 0; k < 2; ++k) dst[m][k] = *(const PG8_LAS bf16x8*)(lds + PG8_SA(b, h) + aoff + m * 2048 + k * 1024); } while (0)
; #define PG8_MMA(ai, bj, At, Bt) do { __builtin_amdgcn_s_setprio(1); _Pragma("unroll") for (int m = 0; m < 4; ++m) _Pragma("unroll") for (int n = 0; n < 2; ++n) _Pragma("unroll") for (int k = 0; k < 2; ++k) \
;         acc[ai][bj][m][n] = __builtin_amdgcn_mfma_f32_16x16x32_bf16(Bt[n][k], At[m][k], acc[ai][bj][m][n], 0, 0, 0); __builtin_amdgcn_s_setprio(0); } while (0)
; #define PG8_WAIT_V(n) asm volatile("s_waitcnt vmcnt(" #n ")" ::: "memory")
; #define PG8_WAIT_L(n) asm volatile("s_waitcnt lgkmcnt(" #n ")" ::: "memory")
; #define PG8_BAR __builtin_amdgcn_s_barrier()
; #define PG8_SCHED __builtin_amdgcn_sched_barrier(0)
; template <class Epi, class Sched, bool ALIGN_EPI = false, bool SP2 = false>
; __device__ __forceinline__ void gemm_phase(PG8_LAS unsigned char* lds, const Gemm g, const Sched& S, const Epi& E, int tid_in) {
;     ...
;         for (int t = 0; t < nt; t += 2) {
;     ...
;             PG8_LDA(At, 1, 1); PG8_STAGE(PG8_SB(1, 0), b3, voffB); PG8_STAGE(PG8_SB(1, 1), b3 + hstepB, voffB); PG8_STAGE(PG8_SA(1, 0), a3, voffA);
;             PG8_WAIT_V(8); PG8_WAIT_L(0); PG8_BAR; PG8_MMA(1, 0, At, B0); PG8_MMA(1, 1, At, B1); PG8_BAR; PG8_SCHED;
	s_add_i32 s34, s61, s2
	v_lshl_add_u64 v[204:205], v[204:205], 0, s[24:25]
	s_mov_b32 m0, s34
	ds_read_b128 v[184:187], v161 offset:49152
	ds_read_b128 v[188:191], v161 offset:50176
	ds_read_b128 v[192:195], v161 offset:51200
	ds_read_b128 v[196:199], v161 offset:52224
	ds_read_b128 v[200:203], v161 offset:53248
	ds_read_b128 v[208:211], v161 offset:54272
	ds_read_b128 v[212:215], v161 offset:55296
	ds_read_b128 v[216:219], v161 offset:56320
	global_load_lds_dwordx4 v[204:205], off
	v_lshl_add_u64 v[204:205], v[220:221], 0, s[24:25]
	s_add_i32 m0, s34, 0x2000
	s_add_i32 s34, s62, s2
	global_load_lds_dwordx4 v[204:205], off
	v_lshl_add_u64 v[204:205], v[222:223], 0, s[24:25]
	s_mov_b32 m0, s34
	s_nop 0
	global_load_lds_dwordx4 v[204:205], off
	v_lshl_add_u64 v[204:205], v[224:225], 0, s[24:25]
	s_add_i32 m0, s34, 0x2000
	s_nop 0
	global_load_lds_dwordx4 v[204:205], off
	v_lshl_add_u64 v[204:205], v[226:227], 0, s[24:25]
	s_mov_b32 m0, s46
	s_nop 0
	global_load_lds_dwordx4 v[204:205], off
	v_lshl_add_u64 v[204:205], v[228:229], 0, s[24:25]
	s_mov_b32 m0, s47
	s_nop 0
	global_load_lds_dwordx4 v[204:205], off
	s_waitcnt vmcnt(8)
	s_waitcnt lgkmcnt(0)
	s_barrier
	s_setprio 1
	s_waitcnt lgkmcnt(0)
	v_mfma_f32_16x16x32_bf16 v[60:63], v[144:147], v[184:187], v[60:63]
	v_mfma_f32_16x16x32_bf16 v[56:59], v[152:155], v[184:187], v[56:59]
	v_mfma_f32_16x16x32_bf16 v[44:47], v[144:147], v[192:195], v[44:47]
	v_mfma_f32_16x16x32_bf16 v[40:43], v[152:155], v[192:195], v[40:43]
	v_mfma_f32_16x16x32_bf16 v[28:31], v[144:147], v[200:203], v[28:31]
	v_mfma_f32_16x16x32_bf16 v[24:27], v[152:155], v[200:203], v[24:27]
	v_mfma_f32_16x16x32_bf16 v[12:15], v[144:147], v[212:215], v[12:15]
	v_mfma_f32_16x16x32_bf16 v[8:11], v[152:155], v[212:215], v[8:11]
	v_mfma_f32_16x16x32_bf16 v[60:63], v[148:151], v[188:191], v[60:63]
	v_mfma_f32_16x16x32_bf16 v[56:59], v[164:167], v[188:191], v[56:59]
	v_mfma_f32_16x16x32_bf16 v[44:47], v[148:151], v[196:199], v[44:47]
	v_mfma_f32_16x16x32_bf16 v[40:43], v[164:167], v[196:199], v[40:43]
	v_mfma_f32_16x16x32_bf16 v[28:31], v[148:151], v[208:211], v[28:31]
	v_mfma_f32_16x16x32_bf16 v[24:27], v[164:167], v[208:211], v[24:27]
	v_mfma_f32_16x16x32_bf16 v[12:15], v[148:151], v[216:219], v[12:15]
	v_mfma_f32_16x16x32_bf16 v[8:11], v[164:167], v[216:219], v[8:11]
	s_setprio 0
	s_setprio 1
	v_mfma_f32_16x16x32_bf16 v[52:55], v[168:171], v[184:187], v[52:55]
	v_mfma_f32_16x16x32_bf16 v[48:51], v[176:179], v[184:187], v[48:51]
	v_mfma_f32_16x16x32_bf16 v[36:39], v[168:171], v[192:195], v[36:39]
	v_mfma_f32_16x16x32_bf16 v[32:35], v[176:179], v[192:195], v[32:35]
	v_mfma_f32_16x16x32_bf16 v[20:23], v[168:171], v[200:203], v[20:23]
	v_mfma_f32_16x16x32_bf16 v[16:19], v[176:179], v[200:203], v[16:19]
	v_mfma_f32_16x16x32_bf16 v[4:7], v[168:171], v[212:215], v[4:7]
	v_mfma_f32_16x16x32_bf16 v[0:3], v[176:179], v[212:215], v[0:3]
	v_mfma_f32_16x16x32_bf16 v[52:55], v[172:175], v[188:191], v[52:55]
	v_mfma_f32_16x16x32_bf16 v[48:51], v[180:183], v[188:191], v[48:51]
	v_mfma_f32_16x16x32_bf16 v[36:39], v[172:175], v[196:199], v[36:39]
	v_mfma_f32_16x16x32_bf16 v[32:35], v[180:183], v[196:199], v[32:35]
	v_mfma_f32_16x16x32_bf16 v[20:23], v[172:175], v[208:211], v[20:23]
	v_mfma_f32_16x16x32_bf16 v[16:19], v[180:183], v[208:211], v[16:19]
	v_mfma_f32_16x16x32_bf16 v[4:7], v[172:175], v[216:219], v[4:7]
	v_mfma_f32_16x16x32_bf16 v[0:3], v[180:183], v[216:219], v[0:3]
	s_setprio 0
	s_barrier
	s_add_u32 s58, s58, 0x100
	s_addc_u32 s59, s59, 0
	s_cmp_ge_i32 s60, s48
	s_mov_b64 s[34:35], s[36:37]
	s_mov_b32 s38, s60
	s_cbranch_scc0 .LBB0_633

; #define PG8_STAGE(bufoff, gbase, voff) do { _Pragma("unroll") for (int _i = 0; _i < 2; ++_i) \
;         __builtin_amdgcn_global_load_lds((const unsigned*)((const char*)(gbase) + (voff)[_i]), (PG8_LAS unsigned*)(lds + (bufoff) + ldsw + _i * 8192), 16, 0, 0); } while (0)
; #define PG8_WAIT_V(n) asm volatile("s_waitcnt vmcnt(" #n ")" ::: "memory")
; #define PG8_BAR __builtin_amdgcn_s_barrier()
; template <class Epi, class Sched, bool ALIGN_EPI = false, bool SP2 = false>
; __device__ __forceinline__ void gemm_phase(PG8_LAS unsigned char* lds, const Gemm g, const Sched& S, const Epi& E, int tid_in) {
;     ...
;     for (int i = 0; i < 2; ++i) { int R, C; stage_rc(tid * 16 + i * 8192, R, C); const int Rb = Epi::PERM ? ((R & ~31) + perm32(R & 31)) : R;
;         voffA[i] = (unsigned)(R * lda + C) * 2u; voffB[i] = (unsigned)(Rb * ldb + C) * 2u; }
;     const size_t kstep = (size_t)(BK * 2);
;     const size_t hstepA = (size_t)HALF * lda * 2, hstepB = (size_t)HALF * ldb * 2;
;     const size_t tstepA = 2 * hstepA, tstepB = 2 * hstepB;
;     const unsigned ldsw = (unsigned)wid * 1024u;
;     const int aoff = lds_byte(wr * 64 + fr, fq * 8), boff = lds_byte(wc * 32 + fr, fq * 8);
;     ...
;         PG8_STAGE(PG8_SB(0, 0), cB, voffB); PG8_STAGE(PG8_SB(0, 1), cB + hstepB, voffB); PG8_STAGE(PG8_SA(0, 0), cA, voffA); PG8_STAGE(PG8_SA(0, 1), cA + hstepA, voffA);
;         if (wr == 1) PG8_BAR;
;         PG8_WAIT_V(2); PG8_BAR;
;         PG8_STAGE(PG8_SB(1, 0), cB + kstep, voffB); PG8_STAGE(PG8_SA(1, 0), cA + kstep, voffA); PG8_STAGE(PG8_SB(1, 1), cB + hstepB + kstep, voffB);
;         PG8_WAIT_V(6); PG8_BAR;
.LBB0_643:
	s_add_u32 s14, s14, 0x34400000
	s_addc_u32 s15, s15, 0
	s_lshr_b32 s17, s17, 26
	s_lshl_b32 s7, s7, 5
	s_mov_b64 s[20:21], 0x80
	s_add_i32 s17, s16, s17
	s_and_b32 s7, s7, 0x60
	s_add_i32 m0, s34, 0x18000
	v_lshl_add_u64 v[6:7], v[6:7], 0, s[20:21]
	s_ashr_i32 s39, s17, 6
	s_lshl_b32 s17, s6, 13
	s_lshl_b32 s24, s7, 7
	s_waitcnt vmcnt(2)
	s_barrier
	global_load_lds_dwordx4 v[6:7], off
	v_lshl_add_u64 v[4:5], v[4:5], 0, s[20:21]
	s_add_i32 m0, s34, 0x1a000
	s_add_i32 s42, s34, 0x8000
	s_add_i32 s43, s34, 0xa000
	global_load_lds_dwordx4 v[4:5], off
	v_lshl_add_u64 v[0:1], v[0:1], 0, s[20:21]
	s_mov_b32 m0, s42
	s_add_u32 s22, s28, 0x30080
	global_load_lds_dwordx4 v[0:1], off
	v_lshl_add_u64 v[0:1], v[2:3], 0, s[20:21]
	s_mov_b32 m0, s43
	s_addc_u32 s23, s29, 0
	global_load_lds_dwordx4 v[0:1], off
	s_add_i32 m0, s34, 0x1c000
	s_nop 0
	global_load_lds_dwordx4 v132, s[22:23]
	s_add_i32 m0, s34, 0x1e000
	s_cmp_gt_i32 s16, 63
	global_load_lds_dwordx4 v128, s[22:23]
	v_bfe_u32 v1, v8, 4, 2
	v_and_b32_e32 v0, 15, v8
	v_lshlrev_b32_e32 v2, 4, v1
	v_lshl_or_b32 v160, s6, 6, v0
	v_lshl_or_b32 v0, v0, 6, v2
	v_lshlrev_b32_e32 v2, 2, v8
	v_and_b32_e32 v2, 32, v2
	v_bitop3_b32 v3, v0, s17, v2 bitop3:0xde
	s_cselect_b64 s[16:17], -1, 0
	s_add_i32 s44, s39, -2
	v_lshl_or_b32 v162, v1, 3, s7
	v_add_u32_e32 v1, v14, v12
	v_bitop3_b32 v161, v0, s24, v2 bitop3:0xde
	s_waitcnt vmcnt(6)
	s_cmpk_lt_u32 s5, 0x100
	v_lshrrev_b32_e32 v0, 2, v8
	v_add_lshl_u32 v136, v1, v13, 1
	v_add_u32_e32 v1, v11, v9
	s_cselect_b64 s[22:23], -1, 0
	v_and_b32_e32 v0, 4, v0
	v_lshl_add_u64 v[138:139], s[8:9], 0, v[136:137]
	v_add_lshl_u32 v136, v1, v10, 1
	s_add_i32 s47, 0, 0x10000
	s_add_i32 s48, 0, 0x14000
	s_sext_i32_i16 s53, s4
	s_ashr_i32 s45, s82, 31
	s_mov_b32 s46, s82
	v_lshl_add_u64 v[140:141], s[8:9], 0, v[136:137]
	v_mov_b64_e32 v[142:143], 0x300
	v_mov_b64_e32 v[144:145], 0x2ff
	v_add_u32_e32 v163, s47, v161
	v_add_u32_e32 v164, s48, v161
	v_add_u32_e32 v165, 0, v3
	v_mov_b32_e32 v166, 0x358637bd
	s_mov_b32 s49, 0x30000
	v_lshlrev_b32_e32 v136, 1, v0
	v_mov_b32_e32 v167, 0xffffff70
	v_mov_b32_e32 v168, 0x80
	s_barrier
	s_branch .LBB0_646

; #define PG8_STAGE(bufoff, gbase, voff) do { _Pragma("unroll") for (int _i = 0; _i < 2; ++_i) \
;         __builtin_amdgcn_global_load_lds((const unsigned*)((const char*)(gbase) + (voff)[_i]), (PG8_LAS unsigned*)(lds + (bufoff) + ldsw + _i * 8192), 16, 0, 0); } while (0)
; #define PG8_LDA(dst, b, h) do { _Pragma("unroll") for (int m = 0; m < 4; ++m) _Pragma("unroll") for (int k = 0; k < 2; ++k) dst[m][k] = *(const PG8_LAS bf16x8*)(lds + PG8_SA(b, h) + aoff + m * 2048 + k * 1024); } while (0)
; #define PG8_LDB(dst, b, h) do { _Pragma("unroll") for (int n = 0; n < 2; ++n) _Pragma("unroll") for (int k = 0; k < 2; ++k) dst[n][k] = *(const PG8_LAS bf16x8*)(lds + PG8_SB(b, h) + boff + n * 2048 + k * 1024); } while (0)
; #define PG8_MMA(ai, bj, At, Bt) do { __builtin_amdgcn_s_setprio(1); _Pragma("unroll") for (int m = 0; m < 4; ++m) _Pragma("unroll") for (int n = 0; n < 2; ++n) _Pragma("unroll") for (int k = 0; k < 2; ++k) \
;         acc[ai][bj][m][n] = __builtin_amdgcn_mfma_f32_16x16x32_bf16(Bt[n][k], At[m][k], acc[ai][bj][m][n], 0, 0, 0); __builtin_amdgcn_s_setprio(0); } while (0)
; #define PG8_WAIT_V(n) asm volatile("s_waitcnt vmcnt(" #n ")" ::: "memory")
; #define PG8_WAIT_L(n) asm volatile("s_waitcnt lgkmcnt(" #n ")" ::: "memory")
; #define PG8_BAR __builtin_amdgcn_s_barrier()
; #define PG8_SCHED __builtin_amdgcn_sched_barrier(0)
; template <class Epi, class Sched, bool ALIGN_EPI = false, bool SP2 = false>
; __device__ __forceinline__ void gemm_phase(PG8_LAS unsigned char* lds, const Gemm g, const Sched& S, const Epi& E, int tid_in) {
;     ...
;             if constexpr (SP2) {
;             PG8_LDB(B0, 0, 0); PG8_LDB(B1, 0, 1); PG8_SCHED; PG8_LDA(At, 0, 0); PG8_STAGE(PG8_SA(1, 1), a1 + hstepA, voffA);
;             PG8_WAIT_V(8); PG8_WAIT_L(0); PG8_BAR; PG8_MMA(0, 0, At, B0); PG8_MMA(0, 1, At, B1); PG8_BAR; PG8_SCHED;
;             PG8_LDA(At, 0, 1); PG8_STAGE(PG8_SB(0, 0), b2, voffB); PG8_STAGE(PG8_SB(0, 1), b2 + hstepB, voffB); PG8_STAGE(PG8_SA(0, 0), a2, voffA);
;             PG8_WAIT_V(8); PG8_WAIT_L(0); PG8_BAR; PG8_MMA(1, 0, At, B0); PG8_MMA(1, 1, At, B1); PG8_BAR; PG8_SCHED;
.LBB0_654:
	ds_read_b128 v[146:149], v163
	ds_read_b128 v[150:153], v163 offset:1024
	ds_read_b128 v[154:157], v163 offset:2048
	ds_read_b128 v[170:173], v163 offset:3072
	ds_read_b128 v[174:177], v164
	ds_read_b128 v[178:181], v164 offset:1024
	ds_read_b128 v[182:185], v164 offset:2048
	ds_read_b128 v[186:189], v164 offset:3072
	s_add_i32 s56, s28, 2
	s_add_u32 s29, s26, 0x80
	s_addc_u32 s30, s27, 0
	s_cmp_eq_u32 s44, s28
	s_cselect_b32 s28, s24, s54
	s_cselect_b32 s31, s7, s30
	s_cselect_b32 s30, s6, s29
	s_cselect_b32 s29, s25, s55
	s_add_i32 m0, s34, 0xc000
	ds_read_b128 v[190:193], v165
	ds_read_b128 v[194:197], v165 offset:1024
	ds_read_b128 v[198:201], v165 offset:2048
	ds_read_b128 v[202:205], v165 offset:3072
	ds_read_b128 v[208:211], v165 offset:4096
	ds_read_b128 v[212:215], v165 offset:5120
	ds_read_b128 v[216:219], v165 offset:6144
	ds_read_b128 v[220:223], v165 offset:7168
	global_load_lds_dwordx4 v138, s[26:27]
	s_add_i32 m0, s34, 0xe000
	s_nop 0
	global_load_lds_dwordx4 v140, s[26:27]
	s_waitcnt vmcnt(8)
	s_waitcnt lgkmcnt(0)
	s_barrier
	s_setprio 1
	s_waitcnt lgkmcnt(0)
	v_mfma_f32_16x16x32_bf16 v[120:123], v[146:149], v[190:193], v[120:123]
	v_mfma_f32_16x16x32_bf16 v[124:127], v[154:157], v[190:193], v[124:127]
	v_mfma_f32_16x16x32_bf16 v[116:119], v[146:149], v[198:201], v[116:119]
	v_mfma_f32_16x16x32_bf16 v[112:115], v[154:157], v[198:201], v[112:115]
	v_mfma_f32_16x16x32_bf16 v[108:111], v[146:149], v[208:211], v[108:111]
	v_mfma_f32_16x16x32_bf16 v[104:107], v[154:157], v[208:211], v[104:107]
	v_mfma_f32_16x16x32_bf16 v[100:103], v[146:149], v[216:219], v[100:103]
	v_mfma_f32_16x16x32_bf16 v[96:99], v[154:157], v[216:219], v[96:99]
	v_mfma_f32_16x16x32_bf16 v[120:123], v[150:153], v[194:197], v[120:123]
	v_mfma_f32_16x16x32_bf16 v[124:127], v[170:173], v[194:197], v[124:127]
	v_mfma_f32_16x16x32_bf16 v[116:119], v[150:153], v[202:205], v[116:119]
	v_mfma_f32_16x16x32_bf16 v[112:115], v[170:173], v[202:205], v[112:115]
	v_mfma_f32_16x16x32_bf16 v[108:111], v[150:153], v[212:215], v[108:111]
	v_mfma_f32_16x16x32_bf16 v[104:107], v[170:173], v[212:215], v[104:107]
	v_mfma_f32_16x16x32_bf16 v[100:103], v[150:153], v[220:223], v[100:103]
	v_mfma_f32_16x16x32_bf16 v[96:99], v[170:173], v[220:223], v[96:99]
	s_setprio 0
	s_setprio 1
	v_mfma_f32_16x16x32_bf16 v[60:63], v[174:177], v[190:193], v[60:63]
	v_mfma_f32_16x16x32_bf16 v[56:59], v[182:185], v[190:193], v[56:59]
	v_mfma_f32_16x16x32_bf16 v[52:55], v[174:177], v[198:201], v[52:55]
	v_mfma_f32_16x16x32_bf16 v[48:51], v[182:185], v[198:201], v[48:51]
	v_mfma_f32_16x16x32_bf16 v[44:47], v[174:177], v[208:211], v[44:47]
	v_mfma_f32_16x16x32_bf16 v[40:43], v[182:185], v[208:211], v[40:43]
	v_mfma_f32_16x16x32_bf16 v[36:39], v[174:177], v[216:219], v[36:39]
	v_mfma_f32_16x16x32_bf16 v[32:35], v[182:185], v[216:219], v[32:35]
	v_mfma_f32_16x16x32_bf16 v[60:63], v[178:181], v[194:197], v[60:63]
	v_mfma_f32_16x16x32_bf16 v[56:59], v[186:189], v[194:197], v[56:59]
	v_mfma_f32_16x16x32_bf16 v[52:55], v[178:181], v[202:205], v[52:55]
	v_mfma_f32_16x16x32_bf16 v[48:51], v[186:189], v[202:205], v[48:51]
	v_mfma_f32_16x16x32_bf16 v[44:47], v[178:181], v[212:215], v[44:47]
	v_mfma_f32_16x16x32_bf16 v[40:43], v[186:189], v[212:215], v[40:43]
	v_mfma_f32_16x16x32_bf16 v[36:39], v[178:181], v[220:223], v[36:39]
	v_mfma_f32_16x16x32_bf16 v[32:35], v[186:189], v[220:223], v[32:35]
	s_setprio 0
	s_barrier
	s_add_i32 s57, s47, s2
	v_lshl_add_u64 v[158:159], s[28:29], 0, v[132:133]
	s_mov_b32 m0, s57
	ds_read_b128 v[190:193], v165 offset:16384
	ds_read_b128 v[194:197], v165 offset:17408
	ds_read_b128 v[198:201], v165 offset:18432
	ds_read_b128 v[202:205], v165 offset:19456
	ds_read_b128 v[208:211], v165 offset:20480
	ds_read_b128 v[212:215], v165 offset:21504
	ds_read_b128 v[216:219], v165 offset:22528
	ds_read_b128 v[220:223], v165 offset:23552
	global_load_lds_dwordx4 v[158:159], off
	s_add_i32 m0, s57, 0x2000
	s_add_u32 s58, s28, 0x30000
	v_lshl_add_u64 v[224:225], s[28:29], 0, v[128:129]
	s_addc_u32 s59, s29, 0
	s_add_i32 s57, s48, s2
	global_load_lds_dwordx4 v[224:225], off
	s_mov_b32 m0, s57
	v_lshl_add_u64 v[228:229], s[30:31], 0, v[130:131]
	global_load_lds_dwordx4 v132, s[58:59]
	s_add_i32 m0, s57, 0x2000
	s_nop 0
	global_load_lds_dwordx4 v128, s[58:59]
	v_lshl_add_u64 v[226:227], s[30:31], 0, v[134:135]
	s_mov_b32 m0, s34
	s_nop 0
	global_load_lds_dwordx4 v[226:227], off
	s_mov_b32 m0, s35
	s_nop 0
	global_load_lds_dwordx4 v[228:229], off
	s_waitcnt vmcnt(8)
	s_waitcnt lgkmcnt(0)
	s_barrier
; #define PG8_STAGE(bufoff, gbase, voff) do { _Pragma("unroll") for (int _i = 0; _i < 2; ++_i) \
;         __builtin_amdgcn_global_load_lds((const unsigned*)((const char*)(gbase) + (voff)[_i]), (PG8_LAS unsigned*)(lds + (bufoff) + ldsw + _i * 8192), 16, 0, 0); } while (0)
; #define PG8_LDA(dst, b, h) do { _Pragma("unroll") for (int m = 0; m < 4; ++m) _Pragma("unroll") for (int k = 0; k < 2; ++k) dst[m][k] = *(const PG8_LAS bf16x8*)(lds + PG8_SA(b, h) + aoff + m * 2048 + k * 1024); } while (0)
; #define PG8_LDB(dst, b, h) do { _Pragma("unroll") for (int n = 0; n < 2; ++n) _Pragma("unroll") for (int k = 0; k < 2; ++k) dst[n][k] = *(const PG8_LAS bf16x8*)(lds + PG8_SB(b, h) + boff + n * 2048 + k * 1024); } while (0)
; #define PG8_MMA(ai, bj, At, Bt) do { __builtin_amdgcn_s_setprio(1); _Pragma("unroll") for (int m = 0; m < 4; ++m) _Pragma("unroll") for (int n = 0; n < 2; ++n) _Pragma("unroll") for (int k = 0; k < 2; ++k) \
;         acc[ai][bj][m][n] = __builtin_amdgcn_mfma_f32_16x16x32_bf16(Bt[n][k], At[m][k], acc[ai][bj][m][n], 0, 0, 0); __builtin_amdgcn_s_setprio(0); } while (0)
; #define PG8_WAIT_V(n) asm volatile("s_waitcnt vmcnt(" #n ")" ::: "memory")
; #define PG8_WAIT_L(n) asm volatile("s_waitcnt lgkmcnt(" #n ")" ::: "memory")
; #define PG8_BAR __builtin_amdgcn_s_barrier()
; #define PG8_SCHED __builtin_amdgcn_sched_barrier(0)
; template <class Epi, class Sched, bool ALIGN_EPI = false, bool SP2 = false>
; __device__ __forceinline__ void gemm_phase(PG8_LAS unsigned char* lds, const Gemm g, const Sched& S, const Epi& E, int tid_in) {
;     ...
;             PG8_WAIT_V(8); PG8_WAIT_L(0); PG8_BAR; PG8_MMA(1, 0, At, B0); PG8_MMA(1, 1, At, B1); PG8_BAR; PG8_SCHED;
;             PG8_LDB(B0, 1, 0); PG8_LDB(B1, 1, 1); PG8_SCHED; PG8_LDA(At, 1, 0); PG8_STAGE(PG8_SA(0, 1), a2 + hstepA, voffA);
;             PG8_WAIT_V(8); PG8_WAIT_L(0); PG8_BAR; PG8_MMA(0, 0, At, B0); PG8_MMA(0, 1, At, B1); PG8_BAR; PG8_SCHED;
	s_setprio 1
	s_waitcnt lgkmcnt(0)
	v_mfma_f32_16x16x32_bf16 v[92:95], v[146:149], v[190:193], v[92:95]
	v_mfma_f32_16x16x32_bf16 v[88:91], v[154:157], v[190:193], v[88:91]
	v_mfma_f32_16x16x32_bf16 v[84:87], v[146:149], v[198:201], v[84:87]
	v_mfma_f32_16x16x32_bf16 v[80:83], v[154:157], v[198:201], v[80:83]
	v_mfma_f32_16x16x32_bf16 v[76:79], v[146:149], v[208:211], v[76:79]
	v_mfma_f32_16x16x32_bf16 v[72:75], v[154:157], v[208:211], v[72:75]
	v_mfma_f32_16x16x32_bf16 v[68:71], v[146:149], v[216:219], v[68:71]
	v_mfma_f32_16x16x32_bf16 v[64:67], v[154:157], v[216:219], v[64:67]
	v_mfma_f32_16x16x32_bf16 v[92:95], v[150:153], v[194:197], v[92:95]
	v_mfma_f32_16x16x32_bf16 v[88:91], v[170:173], v[194:197], v[88:91]
	v_mfma_f32_16x16x32_bf16 v[84:87], v[150:153], v[202:205], v[84:87]
	v_mfma_f32_16x16x32_bf16 v[80:83], v[170:173], v[202:205], v[80:83]
	v_mfma_f32_16x16x32_bf16 v[76:79], v[150:153], v[212:215], v[76:79]
	v_mfma_f32_16x16x32_bf16 v[72:75], v[170:173], v[212:215], v[72:75]
	v_mfma_f32_16x16x32_bf16 v[68:71], v[150:153], v[220:223], v[68:71]
	v_mfma_f32_16x16x32_bf16 v[64:67], v[170:173], v[220:223], v[64:67]
	s_setprio 0
	s_setprio 1
	v_mfma_f32_16x16x32_bf16 v[28:31], v[174:177], v[190:193], v[28:31]
	v_mfma_f32_16x16x32_bf16 v[24:27], v[182:185], v[190:193], v[24:27]
	v_mfma_f32_16x16x32_bf16 v[20:23], v[174:177], v[198:201], v[20:23]
	v_mfma_f32_16x16x32_bf16 v[16:19], v[182:185], v[198:201], v[16:19]
	v_mfma_f32_16x16x32_bf16 v[12:15], v[174:177], v[208:211], v[12:15]
	v_mfma_f32_16x16x32_bf16 v[8:11], v[182:185], v[208:211], v[8:11]
	v_mfma_f32_16x16x32_bf16 v[4:7], v[174:177], v[216:219], v[4:7]
	v_mfma_f32_16x16x32_bf16 v[0:3], v[182:185], v[216:219], v[0:3]
	v_mfma_f32_16x16x32_bf16 v[28:31], v[178:181], v[194:197], v[28:31]
	v_mfma_f32_16x16x32_bf16 v[24:27], v[186:189], v[194:197], v[24:27]
	v_mfma_f32_16x16x32_bf16 v[20:23], v[178:181], v[202:205], v[20:23]
	v_mfma_f32_16x16x32_bf16 v[16:19], v[186:189], v[202:205], v[16:19]
	v_mfma_f32_16x16x32_bf16 v[12:15], v[178:181], v[212:215], v[12:15]
	v_mfma_f32_16x16x32_bf16 v[8:11], v[186:189], v[212:215], v[8:11]
	v_mfma_f32_16x16x32_bf16 v[4:7], v[178:181], v[220:223], v[4:7]
	v_mfma_f32_16x16x32_bf16 v[0:3], v[186:189], v[220:223], v[0:3]
	s_setprio 0
	s_barrier
	s_add_i32 s57, 0, 0x18000
	v_add_u32_e32 v169, s57, v161
	s_add_i32 s58, 0, 0x1c000
	ds_read_b128 v[146:149], v169
	ds_read_b128 v[150:153], v169 offset:1024
	ds_read_b128 v[154:157], v169 offset:2048
	ds_read_b128 v[170:173], v169 offset:3072
	v_add_u32_e32 v169, s58, v161
	ds_read_b128 v[174:177], v169
	ds_read_b128 v[178:181], v169 offset:1024
	ds_read_b128 v[182:185], v169 offset:2048
	ds_read_b128 v[186:189], v169 offset:3072
	s_add_u32 s30, s30, s8
	s_addc_u32 s31, s31, s9
	s_mov_b32 m0, s36
	ds_read_b128 v[190:193], v165 offset:32768
	ds_read_b128 v[194:197], v165 offset:33792
	ds_read_b128 v[198:201], v165 offset:34816
	ds_read_b128 v[202:205], v165 offset:35840
	ds_read_b128 v[208:211], v165 offset:36864
	ds_read_b128 v[212:215], v165 offset:37888
	ds_read_b128 v[216:219], v165 offset:38912
	ds_read_b128 v[220:223], v165 offset:39936
	global_load_lds_dwordx4 v134, s[30:31]
	s_mov_b32 m0, s37
	s_nop 0
	global_load_lds_dwordx4 v130, s[30:31]
	s_waitcnt vmcnt(8)
	s_waitcnt lgkmcnt(0)
	s_barrier
	s_setprio 1
	s_waitcnt lgkmcnt(0)
	v_mfma_f32_16x16x32_bf16 v[120:123], v[146:149], v[190:193], v[120:123]
	v_mfma_f32_16x16x32_bf16 v[124:127], v[154:157], v[190:193], v[124:127]
	v_mfma_f32_16x16x32_bf16 v[116:119], v[146:149], v[198:201], v[116:119]
	v_mfma_f32_16x16x32_bf16 v[112:115], v[154:157], v[198:201], v[112:115]
	v_mfma_f32_16x16x32_bf16 v[108:111], v[146:149], v[208:211], v[108:111]
	v_mfma_f32_16x16x32_bf16 v[104:107], v[154:157], v[208:211], v[104:107]
	v_mfma_f32_16x16x32_bf16 v[100:103], v[146:149], v[216:219], v[100:103]
	v_mfma_f32_16x16x32_bf16 v[96:99], v[154:157], v[216:219], v[96:99]
	v_mfma_f32_16x16x32_bf16 v[120:123], v[150:153], v[194:197], v[120:123]
	v_mfma_f32_16x16x32_bf16 v[124:127], v[170:173], v[194:197], v[124:127]
	v_mfma_f32_16x16x32_bf16 v[116:119], v[150:153], v[202:205], v[116:119]
	v_mfma_f32_16x16x32_bf16 v[112:115], v[170:173], v[202:205], v[112:115]
	v_mfma_f32_16x16x32_bf16 v[108:111], v[150:153], v[212:215], v[108:111]
	v_mfma_f32_16x16x32_bf16 v[104:107], v[170:173], v[212:215], v[104:107]
	v_mfma_f32_16x16x32_bf16 v[100:103], v[150:153], v[220:223], v[100:103]
	v_mfma_f32_16x16x32_bf16 v[96:99], v[170:173], v[220:223], v[96:99]
	s_setprio 0
	s_setprio 1
	v_mfma_f32_16x16x32_bf16 v[60:63], v[174:177], v[190:193], v[60:63]
	v_mfma_f32_16x16x32_bf16 v[56:59], v[182:185], v[190:193], v[56:59]
	v_mfma_f32_16x16x32_bf16 v[52:55], v[174:177], v[198:201], v[52:55]
	v_mfma_f32_16x16x32_bf16 v[48:51], v[182:185], v[198:201], v[48:51]
	v_mfma_f32_16x16x32_bf16 v[44:47], v[174:177], v[208:211], v[44:47]
	v_mfma_f32_16x16x32_bf16 v[40:43], v[182:185], v[208:211], v[40:43]
	v_mfma_f32_16x16x32_bf16 v[36:39], v[174:177], v[216:219], v[36:39]
	v_mfma_f32_16x16x32_bf16 v[32:35], v[182:185], v[216:219], v[32:35]
	v_mfma_f32_16x16x32_bf16 v[60:63], v[178:181], v[194:197], v[60:63]
	v_mfma_f32_16x16x32_bf16 v[56:59], v[186:189], v[194:197], v[56:59]
	v_mfma_f32_16x16x32_bf16 v[52:55], v[178:181], v[202:205], v[52:55]
	v_mfma_f32_16x16x32_bf16 v[48:51], v[186:189], v[202:205], v[48:51]
	v_mfma_f32_16x16x32_bf16 v[44:47], v[178:181], v[212:215], v[44:47]
	v_mfma_f32_16x16x32_bf16 v[40:43], v[186:189], v[212:215], v[40:43]
	v_mfma_f32_16x16x32_bf16 v[36:39], v[178:181], v[220:223], v[36:39]
	v_mfma_f32_16x16x32_bf16 v[32:35], v[186:189], v[220:223], v[32:35]
	s_setprio 0
	s_barrier
; #define PG8_STAGE(bufoff, gbase, voff) do { _Pragma("unroll") for (int _i = 0; _i < 2; ++_i) \
;         __builtin_amdgcn_global_load_lds((const unsigned*)((const char*)(gbase) + (voff)[_i]), (PG8_LAS unsigned*)(lds + (bufoff) + ldsw + _i * 8192), 16, 0, 0); } while (0)
; #define PG8_LDA(dst, b, h) do { _Pragma("unroll") for (int m = 0; m < 4; ++m) _Pragma("unroll") for (int k = 0; k < 2; ++k) dst[m][k] = *(const PG8_LAS bf16x8*)(lds + PG8_SA(b, h) + aoff + m * 2048 + k * 1024); } while (0)
; #define PG8_MMA(ai, bj, At, Bt) do { __builtin_amdgcn_s_setprio(1); _Pragma("unroll") for (int m = 0; m < 4; ++m) _Pragma("unroll") for (int n = 0; n < 2; ++n) _Pragma("unroll") for (int k = 0; k < 2; ++k) \
;         acc[ai][bj][m][n] = __builtin_amdgcn_mfma_f32_16x16x32_bf16(Bt[n][k], At[m][k], acc[ai][bj][m][n], 0, 0, 0); __builtin_amdgcn_s_setprio(0); } while (0)
; #define PG8_WAIT_V(n) asm volatile("s_waitcnt vmcnt(" #n ")" ::: "memory")
; #define PG8_WAIT_L(n) asm volatile("s_waitcnt lgkmcnt(" #n ")" ::: "memory")
; #define PG8_BAR __builtin_amdgcn_s_barrier()
; #define PG8_SCHED __builtin_amdgcn_sched_barrier(0)
; template <class Epi, class Sched, bool ALIGN_EPI = false, bool SP2 = false>
; __device__ __forceinline__ void gemm_phase(PG8_LAS unsigned char* lds, const Gemm g, const Sched& S, const Epi& E, int tid_in) {
;     ...
;         for (int t = 0; t < nt; t += 2) {
;     ...
;             PG8_WAIT_V(8); PG8_WAIT_L(0); PG8_BAR; PG8_MMA(0, 0, At, B0); PG8_MMA(0, 1, At, B1); PG8_BAR; PG8_SCHED;
;             PG8_LDA(At, 1, 1); PG8_STAGE(PG8_SB(1, 0), b3, voffB); PG8_STAGE(PG8_SB(1, 1), b3 + hstepB, voffB); PG8_STAGE(PG8_SA(1, 0), a3, voffA);
;             PG8_WAIT_V(8); PG8_WAIT_L(0); PG8_BAR; PG8_MMA(1, 0, At, B0); PG8_MMA(1, 1, At, B1); PG8_BAR; PG8_SCHED;
	s_add_i32 s30, s57, s2
	v_lshl_add_u64 v[158:159], v[158:159], 0, s[20:21]
	s_mov_b32 m0, s30
	ds_read_b128 v[190:193], v165 offset:49152
	ds_read_b128 v[194:197], v165 offset:50176
	ds_read_b128 v[198:201], v165 offset:51200
	ds_read_b128 v[202:205], v165 offset:52224
	ds_read_b128 v[208:211], v165 offset:53248
	ds_read_b128 v[212:215], v165 offset:54272
	ds_read_b128 v[216:219], v165 offset:55296
	ds_read_b128 v[220:223], v165 offset:56320
	global_load_lds_dwordx4 v[158:159], off
	s_add_i32 m0, s30, 0x2000
	s_add_u32 s28, s28, 0x30080
	v_lshl_add_u64 v[158:159], v[224:225], 0, s[20:21]
	s_addc_u32 s29, s29, 0
	s_add_i32 s30, s58, s2
	global_load_lds_dwordx4 v[158:159], off
	s_mov_b32 m0, s30
	s_nop 0
	global_load_lds_dwordx4 v132, s[28:29]
	s_add_i32 m0, s30, 0x2000
	s_nop 0
	global_load_lds_dwordx4 v128, s[28:29]
	v_lshl_add_u64 v[158:159], v[226:227], 0, s[20:21]
	s_mov_b32 m0, s42
	s_nop 0
	global_load_lds_dwordx4 v[158:159], off
	v_lshl_add_u64 v[158:159], v[228:229], 0, s[20:21]
	s_mov_b32 m0, s43
	s_nop 0
	global_load_lds_dwordx4 v[158:159], off
	s_waitcnt vmcnt(8)
	s_waitcnt lgkmcnt(0)
	s_barrier
	s_setprio 1
	s_waitcnt lgkmcnt(0)
	v_mfma_f32_16x16x32_bf16 v[92:95], v[146:149], v[190:193], v[92:95]
	v_mfma_f32_16x16x32_bf16 v[88:91], v[154:157], v[190:193], v[88:91]
	v_mfma_f32_16x16x32_bf16 v[84:87], v[146:149], v[198:201], v[84:87]
	v_mfma_f32_16x16x32_bf16 v[80:83], v[154:157], v[198:201], v[80:83]
	v_mfma_f32_16x16x32_bf16 v[76:79], v[146:149], v[208:211], v[76:79]
	v_mfma_f32_16x16x32_bf16 v[72:75], v[154:157], v[208:211], v[72:75]
	v_mfma_f32_16x16x32_bf16 v[68:71], v[146:149], v[216:219], v[68:71]
	v_mfma_f32_16x16x32_bf16 v[64:67], v[154:157], v[216:219], v[64:67]
	v_mfma_f32_16x16x32_bf16 v[92:95], v[150:153], v[194:197], v[92:95]
	v_mfma_f32_16x16x32_bf16 v[88:91], v[170:173], v[194:197], v[88:91]
	v_mfma_f32_16x16x32_bf16 v[84:87], v[150:153], v[202:205], v[84:87]
	v_mfma_f32_16x16x32_bf16 v[80:83], v[170:173], v[202:205], v[80:83]
	v_mfma_f32_16x16x32_bf16 v[76:79], v[150:153], v[212:215], v[76:79]
	v_mfma_f32_16x16x32_bf16 v[72:75], v[170:173], v[212:215], v[72:75]
	v_mfma_f32_16x16x32_bf16 v[68:71], v[150:153], v[220:223], v[68:71]
	v_mfma_f32_16x16x32_bf16 v[64:67], v[170:173], v[220:223], v[64:67]
	s_setprio 0
	s_setprio 1
	v_mfma_f32_16x16x32_bf16 v[28:31], v[174:177], v[190:193], v[28:31]
	v_mfma_f32_16x16x32_bf16 v[24:27], v[182:185], v[190:193], v[24:27]
	v_mfma_f32_16x16x32_bf16 v[20:23], v[174:177], v[198:201], v[20:23]
	v_mfma_f32_16x16x32_bf16 v[16:19], v[182:185], v[198:201], v[16:19]
	v_mfma_f32_16x16x32_bf16 v[12:15], v[174:177], v[208:211], v[12:15]
	v_mfma_f32_16x16x32_bf16 v[8:11], v[182:185], v[208:211], v[8:11]
	v_mfma_f32_16x16x32_bf16 v[4:7], v[174:177], v[216:219], v[4:7]
	v_mfma_f32_16x16x32_bf16 v[0:3], v[182:185], v[216:219], v[0:3]
	v_mfma_f32_16x16x32_bf16 v[28:31], v[178:181], v[194:197], v[28:31]
	v_mfma_f32_16x16x32_bf16 v[24:27], v[186:189], v[194:197], v[24:27]
	v_mfma_f32_16x16x32_bf16 v[20:23], v[178:181], v[202:205], v[20:23]
	v_mfma_f32_16x16x32_bf16 v[16:19], v[186:189], v[202:205], v[16:19]
	v_mfma_f32_16x16x32_bf16 v[12:15], v[178:181], v[212:215], v[12:15]
	v_mfma_f32_16x16x32_bf16 v[8:11], v[186:189], v[212:215], v[8:11]
	v_mfma_f32_16x16x32_bf16 v[4:7], v[178:181], v[220:223], v[4:7]
	v_mfma_f32_16x16x32_bf16 v[0:3], v[186:189], v[220:223], v[0:3]
	s_setprio 0
	s_barrier
	s_add_u32 s26, s26, 0x100
	s_addc_u32 s27, s27, 0
	s_add_u32 s54, s54, 0x100
	s_addc_u32 s55, s55, 0
	s_cmp_ge_i32 s56, s39
	s_mov_b32 s28, s56
	s_cbranch_scc0 .LBB0_654

; #define PG8_STAGE(bufoff, gbase, voff) do { _Pragma("unroll") for (int _i = 0; _i < 2; ++_i) \
;         __builtin_amdgcn_global_load_lds((const unsigned*)((const char*)(gbase) + (voff)[_i]), (PG8_LAS unsigned*)(lds + (bufoff) + ldsw + _i * 8192), 16, 0, 0); } while (0)
; #define PG8_LDA(dst, b, h) do { _Pragma("unroll") for (int m = 0; m < 4; ++m) _Pragma("unroll") for (int k = 0; k < 2; ++k) dst[m][k] = *(const PG8_LAS bf16x8*)(lds + PG8_SA(b, h) + aoff + m * 2048 + k * 1024); } while (0)
; #define PG8_LDB(dst, b, h) do { _Pragma("unroll") for (int n = 0; n < 2; ++n) _Pragma("unroll") for (int k = 0; k < 2; ++k) dst[n][k] = *(const PG8_LAS bf16x8*)(lds + PG8_SB(b, h) + boff + n * 2048 + k * 1024); } while (0)
; #define PG8_MMA(ai, bj, At, Bt) do { __builtin_amdgcn_s_setprio(1); _Pragma("unroll") for (int m = 0; m < 4; ++m) _Pragma("unroll") for (int n = 0; n < 2; ++n) _Pragma("unroll") for (int k = 0; k < 2; ++k) \
;         acc[ai][bj][m][n] = __builtin_amdgcn_mfma_f32_16x16x32_bf16(Bt[n][k], At[m][k], acc[ai][bj][m][n], 0, 0, 0); __builtin_amdgcn_s_setprio(0); } while (0)
; #define PG8_WAIT_V(n) asm volatile("s_waitcnt vmcnt(" #n ")" ::: "memory")
; #define PG8_WAIT_L(n) asm volatile("s_waitcnt lgkmcnt(" #n ")" ::: "memory")
; #define PG8_BAR __builtin_amdgcn_s_barrier()
; #define PG8_SCHED __builtin_amdgcn_sched_barrier(0)
; template <class Epi, class Sched, bool ALIGN_EPI = false, bool SP2 = false>
; __device__ __forceinline__ void gemm_phase(PG8_LAS unsigned char* lds, const Gemm g, const Sched& S, const Epi& E, int tid_in) {
;     ...
;             if constexpr (SP2) {
;             PG8_LDB(B0, 0, 0); PG8_LDB(B1, 0, 1); PG8_SCHED; PG8_LDA(At, 0, 0); PG8_STAGE(PG8_SA(1, 1), a1 + hstepA, voffA);
;             PG8_WAIT_V(8); PG8_WAIT_L(0); PG8_BAR; PG8_MMA(0, 0, At, B0); PG8_MMA(0, 1, At, B1); PG8_BAR; PG8_SCHED;
;             PG8_LDA(At, 0, 1); PG8_STAGE(PG8_SB(0, 0), b2, voffB); PG8_STAGE(PG8_SB(0, 1), b2 + hstepB, voffB); PG8_STAGE(PG8_SA(0, 0), a2, voffA);
;             PG8_WAIT_V(8); PG8_WAIT_L(0); PG8_BAR; PG8_MMA(1, 0, At, B0); PG8_MMA(1, 1, At, B1); PG8_BAR; PG8_SCHED;
.LBB0_1091:
	v_add_u32_e32 v1, s49, v173
	ds_read_b128 v[132:135], v1
	ds_read_b128 v[136:139], v1 offset:1024
	ds_read_b128 v[140:143], v1 offset:2048
	ds_read_b128 v[144:147], v1 offset:3072
	v_add_u32_e32 v1, s50, v173
	ds_read_b128 v[164:167], v1
	ds_read_b128 v[168:171], v1 offset:1024
	ds_read_b128 v[184:187], v1 offset:2048
	ds_read_b128 v[188:191], v1 offset:3072
	s_add_i32 s59, s30, 2
	s_add_u32 s60, s28, 0x80
	s_addc_u32 s31, s29, 0
	s_cmp_eq_u32 s48, s30
	s_cselect_b32 s30, s6, s60
	s_cselect_b32 s31, s7, s31
	s_cselect_b32 s61, s27, s58
	s_cselect_b32 s60, s26, s57
	s_add_i32 m0, s3, 0xc000
	ds_read_b128 v[192:195], v182
	ds_read_b128 v[196:199], v182 offset:1024
	ds_read_b128 v[200:203], v182 offset:2048
	ds_read_b128 v[208:211], v182 offset:3072
	ds_read_b128 v[212:215], v182 offset:4096
	ds_read_b128 v[216:219], v182 offset:5120
	ds_read_b128 v[220:223], v182 offset:6144
	ds_read_b128 v[224:227], v182 offset:7168
	global_load_lds_dwordx4 v156, s[28:29]
	v_lshl_add_u64 v[2:3], s[28:29], 0, v[158:159]
	s_add_i32 m0, s3, 0xe000
	s_nop 0
	global_load_lds_dwordx4 v[2:3], off
	s_waitcnt vmcnt(8)
	s_waitcnt lgkmcnt(0)
	s_barrier
	s_setprio 1
	s_waitcnt lgkmcnt(0)
	v_mfma_f32_16x16x32_bf16 v[128:131], v[132:135], v[192:195], v[128:131]
	v_mfma_f32_16x16x32_bf16 v[124:127], v[140:143], v[192:195], v[124:127]
	v_mfma_f32_16x16x32_bf16 v[120:123], v[132:135], v[200:203], v[120:123]
	v_mfma_f32_16x16x32_bf16 v[116:119], v[140:143], v[200:203], v[116:119]
	v_mfma_f32_16x16x32_bf16 v[112:115], v[132:135], v[212:215], v[112:115]
	v_mfma_f32_16x16x32_bf16 v[108:111], v[140:143], v[212:215], v[108:111]
	v_mfma_f32_16x16x32_bf16 v[104:107], v[132:135], v[220:223], v[104:107]
	v_mfma_f32_16x16x32_bf16 v[100:103], v[140:143], v[220:223], v[100:103]
	v_mfma_f32_16x16x32_bf16 v[128:131], v[136:139], v[196:199], v[128:131]
	v_mfma_f32_16x16x32_bf16 v[124:127], v[144:147], v[196:199], v[124:127]
	v_mfma_f32_16x16x32_bf16 v[120:123], v[136:139], v[208:211], v[120:123]
	v_mfma_f32_16x16x32_bf16 v[116:119], v[144:147], v[208:211], v[116:119]
	v_mfma_f32_16x16x32_bf16 v[112:115], v[136:139], v[216:219], v[112:115]
	v_mfma_f32_16x16x32_bf16 v[108:111], v[144:147], v[216:219], v[108:111]
	v_mfma_f32_16x16x32_bf16 v[104:107], v[136:139], v[224:227], v[104:107]
	v_mfma_f32_16x16x32_bf16 v[100:103], v[144:147], v[224:227], v[100:103]
	s_setprio 0
	s_setprio 1
	v_mfma_f32_16x16x32_bf16 v[96:99], v[164:167], v[192:195], v[96:99]
	v_mfma_f32_16x16x32_bf16 v[92:95], v[184:187], v[192:195], v[92:95]
	v_mfma_f32_16x16x32_bf16 v[88:91], v[164:167], v[200:203], v[88:91]
	v_mfma_f32_16x16x32_bf16 v[84:87], v[184:187], v[200:203], v[84:87]
	v_mfma_f32_16x16x32_bf16 v[80:83], v[164:167], v[212:215], v[80:83]
	v_mfma_f32_16x16x32_bf16 v[76:79], v[184:187], v[212:215], v[76:79]
	v_mfma_f32_16x16x32_bf16 v[72:75], v[164:167], v[220:223], v[72:75]
	v_mfma_f32_16x16x32_bf16 v[68:71], v[184:187], v[220:223], v[68:71]
	v_mfma_f32_16x16x32_bf16 v[96:99], v[168:171], v[196:199], v[96:99]
	v_mfma_f32_16x16x32_bf16 v[92:95], v[188:191], v[196:199], v[92:95]
	v_mfma_f32_16x16x32_bf16 v[88:91], v[168:171], v[208:211], v[88:91]
	v_mfma_f32_16x16x32_bf16 v[84:87], v[188:191], v[208:211], v[84:87]
	v_mfma_f32_16x16x32_bf16 v[80:83], v[168:171], v[216:219], v[80:83]
	v_mfma_f32_16x16x32_bf16 v[76:79], v[188:191], v[216:219], v[76:79]
	v_mfma_f32_16x16x32_bf16 v[72:75], v[168:171], v[224:227], v[72:75]
	v_mfma_f32_16x16x32_bf16 v[68:71], v[188:191], v[224:227], v[68:71]
	s_setprio 0
	s_barrier
	s_add_i32 s62, s49, s37
	v_lshl_add_u64 v[204:205], s[60:61], 0, v[152:153]
	s_mov_b32 m0, s62
	ds_read_b128 v[192:195], v182 offset:16384
	ds_read_b128 v[196:199], v182 offset:17408
	ds_read_b128 v[200:203], v182 offset:18432
	ds_read_b128 v[208:211], v182 offset:19456
	ds_read_b128 v[212:215], v182 offset:20480
	ds_read_b128 v[216:219], v182 offset:21504
	ds_read_b128 v[220:223], v182 offset:22528
	ds_read_b128 v[224:227], v182 offset:23552
	global_load_lds_dwordx4 v[204:205], off
	s_add_i32 m0, s62, 0x2000
	v_lshl_add_u64 v[228:229], s[60:61], 0, v[148:149]
	s_add_u32 s60, s60, s14
	s_addc_u32 s61, s61, s15
	s_add_i32 s62, s50, s37
	global_load_lds_dwordx4 v[228:229], off
	v_lshl_add_u64 v[230:231], s[60:61], 0, v[152:153]
	s_mov_b32 m0, s62
	v_lshl_add_u64 v[232:233], s[60:61], 0, v[148:149]
	global_load_lds_dwordx4 v[230:231], off
	s_add_i32 m0, s62, 0x2000
	v_lshl_add_u64 v[234:235], s[30:31], 0, v[154:155]
	global_load_lds_dwordx4 v[232:233], off
	s_mov_b32 m0, s3
	v_lshl_add_u64 v[236:237], s[30:31], 0, v[150:151]
	global_load_lds_dwordx4 v[234:235], off
	s_mov_b32 m0, s38
	s_nop 0
	global_load_lds_dwordx4 v[236:237], off
	s_waitcnt vmcnt(8)
	s_waitcnt lgkmcnt(0)
	s_barrier
; #define PG8_STAGE(bufoff, gbase, voff) do { _Pragma("unroll") for (int _i = 0; _i < 2; ++_i) \
;         __builtin_amdgcn_global_load_lds((const unsigned*)((const char*)(gbase) + (voff)[_i]), (PG8_LAS unsigned*)(lds + (bufoff) + ldsw + _i * 8192), 16, 0, 0); } while (0)
; #define PG8_LDA(dst, b, h) do { _Pragma("unroll") for (int m = 0; m < 4; ++m) _Pragma("unroll") for (int k = 0; k < 2; ++k) dst[m][k] = *(const PG8_LAS bf16x8*)(lds + PG8_SA(b, h) + aoff + m * 2048 + k * 1024); } while (0)
; #define PG8_LDB(dst, b, h) do { _Pragma("unroll") for (int n = 0; n < 2; ++n) _Pragma("unroll") for (int k = 0; k < 2; ++k) dst[n][k] = *(const PG8_LAS bf16x8*)(lds + PG8_SB(b, h) + boff + n * 2048 + k * 1024); } while (0)
; #define PG8_MMA(ai, bj, At, Bt) do { __builtin_amdgcn_s_setprio(1); _Pragma("unroll") for (int m = 0; m < 4; ++m) _Pragma("unroll") for (int n = 0; n < 2; ++n) _Pragma("unroll") for (int k = 0; k < 2; ++k) \
;         acc[ai][bj][m][n] = __builtin_amdgcn_mfma_f32_16x16x32_bf16(Bt[n][k], At[m][k], acc[ai][bj][m][n], 0, 0, 0); __builtin_amdgcn_s_setprio(0); } while (0)
; #define PG8_WAIT_V(n) asm volatile("s_waitcnt vmcnt(" #n ")" ::: "memory")
; #define PG8_WAIT_L(n) asm volatile("s_waitcnt lgkmcnt(" #n ")" ::: "memory")
; #define PG8_BAR __builtin_amdgcn_s_barrier()
; #define PG8_SCHED __builtin_amdgcn_sched_barrier(0)
; template <class Epi, class Sched, bool ALIGN_EPI = false, bool SP2 = false>
; __device__ __forceinline__ void gemm_phase(PG8_LAS unsigned char* lds, const Gemm g, const Sched& S, const Epi& E, int tid_in) {
;     ...
;             PG8_WAIT_V(8); PG8_WAIT_L(0); PG8_BAR; PG8_MMA(1, 0, At, B0); PG8_MMA(1, 1, At, B1); PG8_BAR; PG8_SCHED;
;             PG8_LDB(B0, 1, 0); PG8_LDB(B1, 1, 1); PG8_SCHED; PG8_LDA(At, 1, 0); PG8_STAGE(PG8_SA(0, 1), a2 + hstepA, voffA);
;             PG8_WAIT_V(8); PG8_WAIT_L(0); PG8_BAR; PG8_MMA(0, 0, At, B0); PG8_MMA(0, 1, At, B1); PG8_BAR; PG8_SCHED;
	s_setprio 1
	s_waitcnt lgkmcnt(0)
	v_mfma_f32_16x16x32_bf16 v[64:67], v[132:135], v[192:195], v[64:67]
	v_mfma_f32_16x16x32_bf16 v[60:63], v[140:143], v[192:195], v[60:63]
	v_mfma_f32_16x16x32_bf16 v[56:59], v[132:135], v[200:203], v[56:59]
	v_mfma_f32_16x16x32_bf16 v[52:55], v[140:143], v[200:203], v[52:55]
	v_mfma_f32_16x16x32_bf16 v[48:51], v[132:135], v[212:215], v[48:51]
	v_mfma_f32_16x16x32_bf16 v[44:47], v[140:143], v[212:215], v[44:47]
	v_mfma_f32_16x16x32_bf16 v[40:43], v[132:135], v[220:223], v[40:43]
	v_mfma_f32_16x16x32_bf16 v[36:39], v[140:143], v[220:223], v[36:39]
	v_mfma_f32_16x16x32_bf16 v[64:67], v[136:139], v[196:199], v[64:67]
	v_mfma_f32_16x16x32_bf16 v[60:63], v[144:147], v[196:199], v[60:63]
	v_mfma_f32_16x16x32_bf16 v[56:59], v[136:139], v[208:211], v[56:59]
	v_mfma_f32_16x16x32_bf16 v[52:55], v[144:147], v[208:211], v[52:55]
	v_mfma_f32_16x16x32_bf16 v[48:51], v[136:139], v[216:219], v[48:51]
	v_mfma_f32_16x16x32_bf16 v[44:47], v[144:147], v[216:219], v[44:47]
	v_mfma_f32_16x16x32_bf16 v[40:43], v[136:139], v[224:227], v[40:43]
	v_mfma_f32_16x16x32_bf16 v[36:39], v[144:147], v[224:227], v[36:39]
	s_setprio 0
	s_setprio 1
	v_mfma_f32_16x16x32_bf16 v[32:35], v[164:167], v[192:195], v[32:35]
	v_mfma_f32_16x16x32_bf16 v[28:31], v[184:187], v[192:195], v[28:31]
	v_mfma_f32_16x16x32_bf16 v[24:27], v[164:167], v[200:203], v[24:27]
	v_mfma_f32_16x16x32_bf16 v[20:23], v[184:187], v[200:203], v[20:23]
	v_mfma_f32_16x16x32_bf16 v[16:19], v[164:167], v[212:215], v[16:19]
	v_mfma_f32_16x16x32_bf16 v[12:15], v[184:187], v[212:215], v[12:15]
	v_mfma_f32_16x16x32_bf16 v[8:11], v[164:167], v[220:223], v[8:11]
	v_mfma_f32_16x16x32_bf16 v[2:5], v[184:187], v[220:223], v[4:7]
	v_mfma_f32_16x16x32_bf16 v[32:35], v[168:171], v[196:199], v[32:35]
	v_mfma_f32_16x16x32_bf16 v[28:31], v[188:191], v[196:199], v[28:31]
	v_mfma_f32_16x16x32_bf16 v[24:27], v[168:171], v[208:211], v[24:27]
	v_mfma_f32_16x16x32_bf16 v[20:23], v[188:191], v[208:211], v[20:23]
	v_mfma_f32_16x16x32_bf16 v[16:19], v[168:171], v[216:219], v[16:19]
	v_mfma_f32_16x16x32_bf16 v[12:15], v[188:191], v[216:219], v[12:15]
	v_mfma_f32_16x16x32_bf16 v[8:11], v[168:171], v[224:227], v[8:11]
	v_mfma_f32_16x16x32_bf16 v[2:5], v[188:191], v[224:227], v[2:5]
	s_setprio 0
	s_barrier
	s_add_i32 s60, 0, 0x18000
	v_add_u32_e32 v1, s60, v173
	s_add_i32 s61, 0, 0x1c000
	ds_read_b128 v[132:135], v1
	ds_read_b128 v[136:139], v1 offset:1024
	ds_read_b128 v[140:143], v1 offset:2048
	ds_read_b128 v[144:147], v1 offset:3072
	v_add_u32_e32 v1, s61, v173
	ds_read_b128 v[164:167], v1
	ds_read_b128 v[168:171], v1 offset:1024
	ds_read_b128 v[184:187], v1 offset:2048
	ds_read_b128 v[188:191], v1 offset:3072
	s_add_u32 s30, s30, s14
	s_addc_u32 s31, s31, s15
	s_mov_b32 m0, s39
	ds_read_b128 v[192:195], v182 offset:32768
	ds_read_b128 v[196:199], v182 offset:33792
	ds_read_b128 v[200:203], v182 offset:34816
	ds_read_b128 v[208:211], v182 offset:35840
	ds_read_b128 v[212:215], v182 offset:36864
	ds_read_b128 v[216:219], v182 offset:37888
	ds_read_b128 v[220:223], v182 offset:38912
	ds_read_b128 v[224:227], v182 offset:39936
	global_load_lds_dwordx4 v154, s[30:31]
	s_mov_b32 m0, s40
	s_nop 0
	global_load_lds_dwordx4 v150, s[30:31]
	s_waitcnt vmcnt(8)
	s_waitcnt lgkmcnt(0)
	s_barrier
	s_setprio 1
	s_waitcnt lgkmcnt(0)
	v_mfma_f32_16x16x32_bf16 v[128:131], v[132:135], v[192:195], v[128:131]
	v_mfma_f32_16x16x32_bf16 v[124:127], v[140:143], v[192:195], v[124:127]
	v_mfma_f32_16x16x32_bf16 v[120:123], v[132:135], v[200:203], v[120:123]
	v_mfma_f32_16x16x32_bf16 v[116:119], v[140:143], v[200:203], v[116:119]
	v_mfma_f32_16x16x32_bf16 v[112:115], v[132:135], v[212:215], v[112:115]
	v_mfma_f32_16x16x32_bf16 v[108:111], v[140:143], v[212:215], v[108:111]
	v_mfma_f32_16x16x32_bf16 v[104:107], v[132:135], v[220:223], v[104:107]
	v_mfma_f32_16x16x32_bf16 v[100:103], v[140:143], v[220:223], v[100:103]
	v_mfma_f32_16x16x32_bf16 v[128:131], v[136:139], v[196:199], v[128:131]
	v_mfma_f32_16x16x32_bf16 v[124:127], v[144:147], v[196:199], v[124:127]
	v_mfma_f32_16x16x32_bf16 v[120:123], v[136:139], v[208:211], v[120:123]
	v_mfma_f32_16x16x32_bf16 v[116:119], v[144:147], v[208:211], v[116:119]
	v_mfma_f32_16x16x32_bf16 v[112:115], v[136:139], v[216:219], v[112:115]
	v_mfma_f32_16x16x32_bf16 v[108:111], v[144:147], v[216:219], v[108:111]
	v_mfma_f32_16x16x32_bf16 v[104:107], v[136:139], v[224:227], v[104:107]
	v_mfma_f32_16x16x32_bf16 v[100:103], v[144:147], v[224:227], v[100:103]
	s_setprio 0
	s_setprio 1
	v_mfma_f32_16x16x32_bf16 v[96:99], v[164:167], v[192:195], v[96:99]
	v_mfma_f32_16x16x32_bf16 v[92:95], v[184:187], v[192:195], v[92:95]
	v_mfma_f32_16x16x32_bf16 v[88:91], v[164:167], v[200:203], v[88:91]
	v_mfma_f32_16x16x32_bf16 v[84:87], v[184:187], v[200:203], v[84:87]
	v_mfma_f32_16x16x32_bf16 v[80:83], v[164:167], v[212:215], v[80:83]
	v_mfma_f32_16x16x32_bf16 v[76:79], v[184:187], v[212:215], v[76:79]
	v_mfma_f32_16x16x32_bf16 v[72:75], v[164:167], v[220:223], v[72:75]
	v_mfma_f32_16x16x32_bf16 v[68:71], v[184:187], v[220:223], v[68:71]
	v_mfma_f32_16x16x32_bf16 v[96:99], v[168:171], v[196:199], v[96:99]
	v_mfma_f32_16x16x32_bf16 v[92:95], v[188:191], v[196:199], v[92:95]
	v_mfma_f32_16x16x32_bf16 v[88:91], v[168:171], v[208:211], v[88:91]
	v_mfma_f32_16x16x32_bf16 v[84:87], v[188:191], v[208:211], v[84:87]
	v_mfma_f32_16x16x32_bf16 v[80:83], v[168:171], v[216:219], v[80:83]
	v_mfma_f32_16x16x32_bf16 v[76:79], v[188:191], v[216:219], v[76:79]
	v_mfma_f32_16x16x32_bf16 v[72:75], v[168:171], v[224:227], v[72:75]
	v_mfma_f32_16x16x32_bf16 v[68:71], v[188:191], v[224:227], v[68:71]
	s_setprio 0
	s_barrier
; #define PG8_STAGE(bufoff, gbase, voff) do { _Pragma("unroll") for (int _i = 0; _i < 2; ++_i) \
;         __builtin_amdgcn_global_load_lds((const unsigned*)((const char*)(gbase) + (voff)[_i]), (PG8_LAS unsigned*)(lds + (bufoff) + ldsw + _i * 8192), 16, 0, 0); } while (0)
; #define PG8_LDA(dst, b, h) do { _Pragma("unroll") for (int m = 0; m < 4; ++m) _Pragma("unroll") for (int k = 0; k < 2; ++k) dst[m][k] = *(const PG8_LAS bf16x8*)(lds + PG8_SA(b, h) + aoff + m * 2048 + k * 1024); } while (0)
; #define PG8_MMA(ai, bj, At, Bt) do { __builtin_amdgcn_s_setprio(1); _Pragma("unroll") for (int m = 0; m < 4; ++m) _Pragma("unroll") for (int n = 0; n < 2; ++n) _Pragma("unroll") for (int k = 0; k < 2; ++k) \
;         acc[ai][bj][m][n] = __builtin_amdgcn_mfma_f32_16x16x32_bf16(Bt[n][k], At[m][k], acc[ai][bj][m][n], 0, 0, 0); __builtin_amdgcn_s_setprio(0); } while (0)
; #define PG8_WAIT_V(n) asm volatile("s_waitcnt vmcnt(" #n ")" ::: "memory")
; #define PG8_WAIT_L(n) asm volatile("s_waitcnt lgkmcnt(" #n ")" ::: "memory")
; #define PG8_BAR __builtin_amdgcn_s_barrier()
; #define PG8_SCHED __builtin_amdgcn_sched_barrier(0)
; template <class Epi, class Sched, bool ALIGN_EPI = false, bool SP2 = false>
; __device__ __forceinline__ void gemm_phase(PG8_LAS unsigned char* lds, const Gemm g, const Sched& S, const Epi& E, int tid_in) {
;     ...
;             PG8_WAIT_V(8); PG8_WAIT_L(0); PG8_BAR; PG8_MMA(0, 0, At, B0); PG8_MMA(0, 1, At, B1); PG8_BAR; PG8_SCHED;
;             PG8_LDA(At, 1, 1); PG8_STAGE(PG8_SB(1, 0), b3, voffB); PG8_STAGE(PG8_SB(1, 1), b3 + hstepB, voffB); PG8_STAGE(PG8_SA(1, 0), a3, voffA);
;             PG8_WAIT_V(8); PG8_WAIT_L(0); PG8_BAR; PG8_MMA(1, 0, At, B0); PG8_MMA(1, 1, At, B1); PG8_BAR; PG8_SCHED;
	s_add_i32 s30, s60, s37
	v_lshl_add_u64 v[6:7], v[204:205], 0, s[20:21]
	s_mov_b32 m0, s30
	ds_read_b128 v[192:195], v182 offset:49152
	ds_read_b128 v[196:199], v182 offset:50176
	ds_read_b128 v[200:203], v182 offset:51200
	ds_read_b128 v[208:211], v182 offset:52224
	ds_read_b128 v[212:215], v182 offset:53248
	ds_read_b128 v[216:219], v182 offset:54272
	ds_read_b128 v[220:223], v182 offset:55296
	ds_read_b128 v[224:227], v182 offset:56320
	global_load_lds_dwordx4 v[6:7], off
	v_lshl_add_u64 v[6:7], v[228:229], 0, s[20:21]
	s_add_i32 m0, s30, 0x2000
	s_add_i32 s30, s61, s37
	global_load_lds_dwordx4 v[6:7], off
	v_lshl_add_u64 v[6:7], v[230:231], 0, s[20:21]
	s_mov_b32 m0, s30
	s_nop 0
	global_load_lds_dwordx4 v[6:7], off
	v_lshl_add_u64 v[6:7], v[232:233], 0, s[20:21]
	s_add_i32 m0, s30, 0x2000
	s_nop 0
	global_load_lds_dwordx4 v[6:7], off
	v_lshl_add_u64 v[6:7], v[234:235], 0, s[20:21]
	s_mov_b32 m0, s45
	s_nop 0
	global_load_lds_dwordx4 v[6:7], off
	v_lshl_add_u64 v[6:7], v[236:237], 0, s[20:21]
	s_mov_b32 m0, s46
	s_nop 0
	global_load_lds_dwordx4 v[6:7], off
	s_waitcnt vmcnt(8)
	s_waitcnt lgkmcnt(0)
	s_barrier
	s_setprio 1
	s_waitcnt lgkmcnt(0)
	v_mfma_f32_16x16x32_bf16 v[64:67], v[132:135], v[192:195], v[64:67]
	v_mfma_f32_16x16x32_bf16 v[60:63], v[140:143], v[192:195], v[60:63]
	v_mfma_f32_16x16x32_bf16 v[56:59], v[132:135], v[200:203], v[56:59]
	v_mfma_f32_16x16x32_bf16 v[52:55], v[140:143], v[200:203], v[52:55]
	v_mfma_f32_16x16x32_bf16 v[48:51], v[132:135], v[212:215], v[48:51]
	v_mfma_f32_16x16x32_bf16 v[44:47], v[140:143], v[212:215], v[44:47]
	v_mfma_f32_16x16x32_bf16 v[40:43], v[132:135], v[220:223], v[40:43]
	v_mfma_f32_16x16x32_bf16 v[36:39], v[140:143], v[220:223], v[36:39]
	v_mfma_f32_16x16x32_bf16 v[64:67], v[136:139], v[196:199], v[64:67]
	v_mfma_f32_16x16x32_bf16 v[60:63], v[144:147], v[196:199], v[60:63]
	v_mfma_f32_16x16x32_bf16 v[56:59], v[136:139], v[208:211], v[56:59]
	v_mfma_f32_16x16x32_bf16 v[52:55], v[144:147], v[208:211], v[52:55]
	v_mfma_f32_16x16x32_bf16 v[48:51], v[136:139], v[216:219], v[48:51]
	v_mfma_f32_16x16x32_bf16 v[44:47], v[144:147], v[216:219], v[44:47]
	v_mfma_f32_16x16x32_bf16 v[40:43], v[136:139], v[224:227], v[40:43]
	v_mfma_f32_16x16x32_bf16 v[36:39], v[144:147], v[224:227], v[36:39]
	s_setprio 0
	s_setprio 1
	v_mfma_f32_16x16x32_bf16 v[32:35], v[164:167], v[192:195], v[32:35]
	v_mfma_f32_16x16x32_bf16 v[28:31], v[184:187], v[192:195], v[28:31]
	v_mfma_f32_16x16x32_bf16 v[24:27], v[164:167], v[200:203], v[24:27]
	v_mfma_f32_16x16x32_bf16 v[20:23], v[184:187], v[200:203], v[20:23]
	v_mfma_f32_16x16x32_bf16 v[16:19], v[164:167], v[212:215], v[16:19]
	v_mfma_f32_16x16x32_bf16 v[12:15], v[184:187], v[212:215], v[12:15]
	v_mfma_f32_16x16x32_bf16 v[6:9], v[164:167], v[220:223], v[8:11]
	v_mfma_f32_16x16x32_bf16 v[2:5], v[184:187], v[220:223], v[2:5]
	v_mfma_f32_16x16x32_bf16 v[32:35], v[168:171], v[196:199], v[32:35]
	v_mfma_f32_16x16x32_bf16 v[28:31], v[188:191], v[196:199], v[28:31]
	v_mfma_f32_16x16x32_bf16 v[24:27], v[168:171], v[208:211], v[24:27]
	v_mfma_f32_16x16x32_bf16 v[20:23], v[188:191], v[208:211], v[20:23]
	v_mfma_f32_16x16x32_bf16 v[16:19], v[168:171], v[216:219], v[16:19]
	v_mfma_f32_16x16x32_bf16 v[12:15], v[188:191], v[216:219], v[12:15]
	v_mfma_f32_16x16x32_bf16 v[8:11], v[168:171], v[224:227], v[6:9]
	v_mfma_f32_16x16x32_bf16 v[4:7], v[188:191], v[224:227], v[2:5]
	s_setprio 0
	s_barrier
	s_add_u32 s28, s28, 0x100
	s_addc_u32 s29, s29, 0
	s_add_u32 s57, s57, 0x100
	s_addc_u32 s58, s58, 0
	s_cmp_ge_i32 s59, s47
	s_mov_b32 s30, s59
	s_cbranch_scc0 .LBB0_1091

; #define PG8_STAGE(bufoff, gbase, voff) do { _Pragma("unroll") for (int _i = 0; _i < 2; ++_i) \
;         __builtin_amdgcn_global_load_lds((const unsigned*)((const char*)(gbase) + (voff)[_i]), (PG8_LAS unsigned*)(lds + (bufoff) + ldsw + _i * 8192), 16, 0, 0); } while (0)
; #define PG8_LDA(dst, b, h) do { _Pragma("unroll") for (int m = 0; m < 4; ++m) _Pragma("unroll") for (int k = 0; k < 2; ++k) dst[m][k] = *(const PG8_LAS bf16x8*)(lds + PG8_SA(b, h) + aoff + m * 2048 + k * 1024); } while (0)
; #define PG8_LDB(dst, b, h) do { _Pragma("unroll") for (int n = 0; n < 2; ++n) _Pragma("unroll") for (int k = 0; k < 2; ++k) dst[n][k] = *(const PG8_LAS bf16x8*)(lds + PG8_SB(b, h) + boff + n * 2048 + k * 1024); } while (0)
; #define PG8_MMA(ai, bj, At, Bt) do { __builtin_amdgcn_s_setprio(1); _Pragma("unroll") for (int m = 0; m < 4; ++m) _Pragma("unroll") for (int n = 0; n < 2; ++n) _Pragma("unroll") for (int k = 0; k < 2; ++k) \
;         acc[ai][bj][m][n] = __builtin_amdgcn_mfma_f32_16x16x32_bf16(Bt[n][k], At[m][k], acc[ai][bj][m][n], 0, 0, 0); __builtin_amdgcn_s_setprio(0); } while (0)
; #define PG8_WAIT_V(n) asm volatile("s_waitcnt vmcnt(" #n ")" ::: "memory")
; #define PG8_WAIT_L(n) asm volatile("s_waitcnt lgkmcnt(" #n ")" ::: "memory")
; #define PG8_BAR __builtin_amdgcn_s_barrier()
; #define PG8_SCHED __builtin_amdgcn_sched_barrier(0)
; template <class Epi, class Sched, bool ALIGN_EPI = false, bool SP2 = false>
; __device__ __forceinline__ void gemm_phase(PG8_LAS unsigned char* lds, const Gemm g, const Sched& S, const Epi& E, int tid_in) {
;     ...
;             if constexpr (SP2) {
;             PG8_LDB(B0, 0, 0); PG8_LDB(B1, 0, 1); PG8_SCHED; PG8_LDA(At, 0, 0); PG8_STAGE(PG8_SA(1, 1), a1 + hstepA, voffA);
;             PG8_WAIT_V(8); PG8_WAIT_L(0); PG8_BAR; PG8_MMA(0, 0, At, B0); PG8_MMA(0, 1, At, B1); PG8_BAR; PG8_SCHED;
;             PG8_LDA(At, 0, 1); PG8_STAGE(PG8_SB(0, 0), b2, voffB); PG8_STAGE(PG8_SB(0, 1), b2 + hstepB, voffB); PG8_STAGE(PG8_SA(0, 0), a2, voffA);
;             PG8_WAIT_V(8); PG8_WAIT_L(0); PG8_BAR; PG8_MMA(1, 0, At, B0); PG8_MMA(1, 1, At, B1); PG8_BAR; PG8_SCHED;
.LBB0_1172:
	ds_read_b128 v[128:131], v192
	ds_read_b128 v[132:135], v192 offset:1024
	ds_read_b128 v[136:139], v192 offset:2048
	ds_read_b128 v[140:143], v192 offset:3072
	ds_read_b128 v[144:147], v193
	ds_read_b128 v[148:151], v193 offset:1024
	ds_read_b128 v[152:155], v193 offset:2048
	ds_read_b128 v[156:159], v193 offset:3072
	s_add_i32 s59, s34, 2
	s_add_u32 s60, s30, 0x80
	s_addc_u32 s35, s31, 0
	s_cmp_eq_u32 s46, s34
	s_cselect_b32 s34, s8, s60
	s_cselect_b32 s35, s9, s35
	s_cselect_b32 s61, s29, s58
	s_cselect_b32 s60, s28, s57
	s_add_i32 m0, s37, 0xc000
	ds_read_b128 v[180:183], v194
	ds_read_b128 v[184:187], v194 offset:1024
	ds_read_b128 v[196:199], v194 offset:2048
	ds_read_b128 v[200:203], v194 offset:3072
	ds_read_b128 v[208:211], v194 offset:4096
	ds_read_b128 v[212:215], v194 offset:5120
	ds_read_b128 v[216:219], v194 offset:6144
	ds_read_b128 v[220:223], v194 offset:7168
	global_load_lds_dwordx4 v172, s[30:31]
	s_add_i32 m0, s37, 0xe000
	s_nop 0
	global_load_lds_dwordx4 v174, s[30:31]
	s_waitcnt vmcnt(8)
	s_waitcnt lgkmcnt(0)
	s_barrier
	s_setprio 1
	s_waitcnt lgkmcnt(0)
	v_mfma_f32_16x16x32_bf16 v[124:127], v[128:131], v[180:183], v[124:127]
	v_mfma_f32_16x16x32_bf16 v[120:123], v[136:139], v[180:183], v[120:123]
	v_mfma_f32_16x16x32_bf16 v[108:111], v[128:131], v[196:199], v[108:111]
	v_mfma_f32_16x16x32_bf16 v[104:107], v[136:139], v[196:199], v[104:107]
	v_mfma_f32_16x16x32_bf16 v[92:95], v[128:131], v[208:211], v[92:95]
	v_mfma_f32_16x16x32_bf16 v[88:91], v[136:139], v[208:211], v[88:91]
	v_mfma_f32_16x16x32_bf16 v[76:79], v[128:131], v[216:219], v[76:79]
	v_mfma_f32_16x16x32_bf16 v[72:75], v[136:139], v[216:219], v[72:75]
	v_mfma_f32_16x16x32_bf16 v[124:127], v[132:135], v[184:187], v[124:127]
	v_mfma_f32_16x16x32_bf16 v[120:123], v[140:143], v[184:187], v[120:123]
	v_mfma_f32_16x16x32_bf16 v[108:111], v[132:135], v[200:203], v[108:111]
	v_mfma_f32_16x16x32_bf16 v[104:107], v[140:143], v[200:203], v[104:107]
	v_mfma_f32_16x16x32_bf16 v[92:95], v[132:135], v[212:215], v[92:95]
	v_mfma_f32_16x16x32_bf16 v[88:91], v[140:143], v[212:215], v[88:91]
	v_mfma_f32_16x16x32_bf16 v[76:79], v[132:135], v[220:223], v[76:79]
	v_mfma_f32_16x16x32_bf16 v[72:75], v[140:143], v[220:223], v[72:75]
	s_setprio 0
	s_setprio 1
	v_mfma_f32_16x16x32_bf16 v[116:119], v[144:147], v[180:183], v[116:119]
	v_mfma_f32_16x16x32_bf16 v[112:115], v[152:155], v[180:183], v[112:115]
	v_mfma_f32_16x16x32_bf16 v[100:103], v[144:147], v[196:199], v[100:103]
	v_mfma_f32_16x16x32_bf16 v[96:99], v[152:155], v[196:199], v[96:99]
	v_mfma_f32_16x16x32_bf16 v[84:87], v[144:147], v[208:211], v[84:87]
	v_mfma_f32_16x16x32_bf16 v[80:83], v[152:155], v[208:211], v[80:83]
	v_mfma_f32_16x16x32_bf16 v[68:71], v[144:147], v[216:219], v[68:71]
	v_mfma_f32_16x16x32_bf16 v[64:67], v[152:155], v[216:219], v[64:67]
	v_mfma_f32_16x16x32_bf16 v[116:119], v[148:151], v[184:187], v[116:119]
	v_mfma_f32_16x16x32_bf16 v[112:115], v[156:159], v[184:187], v[112:115]
	v_mfma_f32_16x16x32_bf16 v[100:103], v[148:151], v[200:203], v[100:103]
	v_mfma_f32_16x16x32_bf16 v[96:99], v[156:159], v[200:203], v[96:99]
	v_mfma_f32_16x16x32_bf16 v[84:87], v[148:151], v[212:215], v[84:87]
	v_mfma_f32_16x16x32_bf16 v[80:83], v[156:159], v[212:215], v[80:83]
	v_mfma_f32_16x16x32_bf16 v[68:71], v[148:151], v[220:223], v[68:71]
	v_mfma_f32_16x16x32_bf16 v[64:67], v[156:159], v[220:223], v[64:67]
	s_setprio 0
	s_barrier
	s_add_i32 s62, s51, s36
	v_lshl_add_u64 v[204:205], s[60:61], 0, v[162:163]
	s_mov_b32 m0, s62
	ds_read_b128 v[180:183], v194 offset:16384
	ds_read_b128 v[184:187], v194 offset:17408
	ds_read_b128 v[196:199], v194 offset:18432
	ds_read_b128 v[200:203], v194 offset:19456
	ds_read_b128 v[208:211], v194 offset:20480
	ds_read_b128 v[212:215], v194 offset:21504
	ds_read_b128 v[216:219], v194 offset:22528
	ds_read_b128 v[220:223], v194 offset:23552
	global_load_lds_dwordx4 v[204:205], off
	s_add_i32 m0, s62, 0x2000
	v_lshl_add_u64 v[224:225], s[60:61], 0, v[166:167]
	s_add_u32 s60, s60, s10
	s_addc_u32 s61, s61, s11
	s_add_i32 s62, s52, s36
	global_load_lds_dwordx4 v[224:225], off
	v_lshl_add_u64 v[226:227], s[60:61], 0, v[162:163]
	s_mov_b32 m0, s62
	v_lshl_add_u64 v[228:229], s[60:61], 0, v[166:167]
	global_load_lds_dwordx4 v[226:227], off
	s_add_i32 m0, s62, 0x2000
	v_lshl_add_u64 v[230:231], s[34:35], 0, v[160:161]
	global_load_lds_dwordx4 v[228:229], off
	s_mov_b32 m0, s37
	v_lshl_add_u64 v[232:233], s[34:35], 0, v[164:165]
	global_load_lds_dwordx4 v[230:231], off
	s_mov_b32 m0, s38
	s_nop 0
	global_load_lds_dwordx4 v[232:233], off
	s_waitcnt vmcnt(8)
	s_waitcnt lgkmcnt(0)
	s_barrier
; #define PG8_STAGE(bufoff, gbase, voff) do { _Pragma("unroll") for (int _i = 0; _i < 2; ++_i) \
;         __builtin_amdgcn_global_load_lds((const unsigned*)((const char*)(gbase) + (voff)[_i]), (PG8_LAS unsigned*)(lds + (bufoff) + ldsw + _i * 8192), 16, 0, 0); } while (0)
; #define PG8_LDA(dst, b, h) do { _Pragma("unroll") for (int m = 0; m < 4; ++m) _Pragma("unroll") for (int k = 0; k < 2; ++k) dst[m][k] = *(const PG8_LAS bf16x8*)(lds + PG8_SA(b, h) + aoff + m * 2048 + k * 1024); } while (0)
; #define PG8_LDB(dst, b, h) do { _Pragma("unroll") for (int n = 0; n < 2; ++n) _Pragma("unroll") for (int k = 0; k < 2; ++k) dst[n][k] = *(const PG8_LAS bf16x8*)(lds + PG8_SB(b, h) + boff + n * 2048 + k * 1024); } while (0)
; #define PG8_MMA(ai, bj, At, Bt) do { __builtin_amdgcn_s_setprio(1); _Pragma("unroll") for (int m = 0; m < 4; ++m) _Pragma("unroll") for (int n = 0; n < 2; ++n) _Pragma("unroll") for (int k = 0; k < 2; ++k) \
;         acc[ai][bj][m][n] = __builtin_amdgcn_mfma_f32_16x16x32_bf16(Bt[n][k], At[m][k], acc[ai][bj][m][n], 0, 0, 0); __builtin_amdgcn_s_setprio(0); } while (0)
; #define PG8_WAIT_V(n) asm volatile("s_waitcnt vmcnt(" #n ")" ::: "memory")
; #define PG8_WAIT_L(n) asm volatile("s_waitcnt lgkmcnt(" #n ")" ::: "memory")
; #define PG8_BAR __builtin_amdgcn_s_barrier()
; #define PG8_SCHED __builtin_amdgcn_sched_barrier(0)
; template <class Epi, class Sched, bool ALIGN_EPI = false, bool SP2 = false>
; __device__ __forceinline__ void gemm_phase(PG8_LAS unsigned char* lds, const Gemm g, const Sched& S, const Epi& E, int tid_in) {
;     ...
;             PG8_WAIT_V(8); PG8_WAIT_L(0); PG8_BAR; PG8_MMA(1, 0, At, B0); PG8_MMA(1, 1, At, B1); PG8_BAR; PG8_SCHED;
;             PG8_LDB(B0, 1, 0); PG8_LDB(B1, 1, 1); PG8_SCHED; PG8_LDA(At, 1, 0); PG8_STAGE(PG8_SA(0, 1), a2 + hstepA, voffA);
;             PG8_WAIT_V(8); PG8_WAIT_L(0); PG8_BAR; PG8_MMA(0, 0, At, B0); PG8_MMA(0, 1, At, B1); PG8_BAR; PG8_SCHED;
	s_setprio 1
	s_waitcnt lgkmcnt(0)
	v_mfma_f32_16x16x32_bf16 v[60:63], v[128:131], v[180:183], v[60:63]
	v_mfma_f32_16x16x32_bf16 v[56:59], v[136:139], v[180:183], v[56:59]
	v_mfma_f32_16x16x32_bf16 v[44:47], v[128:131], v[196:199], v[44:47]
	v_mfma_f32_16x16x32_bf16 v[40:43], v[136:139], v[196:199], v[40:43]
	v_mfma_f32_16x16x32_bf16 v[28:31], v[128:131], v[208:211], v[28:31]
	v_mfma_f32_16x16x32_bf16 v[24:27], v[136:139], v[208:211], v[24:27]
	v_mfma_f32_16x16x32_bf16 v[12:15], v[128:131], v[216:219], v[12:15]
	v_mfma_f32_16x16x32_bf16 v[8:11], v[136:139], v[216:219], v[8:11]
	v_mfma_f32_16x16x32_bf16 v[60:63], v[132:135], v[184:187], v[60:63]
	v_mfma_f32_16x16x32_bf16 v[56:59], v[140:143], v[184:187], v[56:59]
	v_mfma_f32_16x16x32_bf16 v[44:47], v[132:135], v[200:203], v[44:47]
	v_mfma_f32_16x16x32_bf16 v[40:43], v[140:143], v[200:203], v[40:43]
	v_mfma_f32_16x16x32_bf16 v[28:31], v[132:135], v[212:215], v[28:31]
	v_mfma_f32_16x16x32_bf16 v[24:27], v[140:143], v[212:215], v[24:27]
	v_mfma_f32_16x16x32_bf16 v[12:15], v[132:135], v[220:223], v[12:15]
	v_mfma_f32_16x16x32_bf16 v[8:11], v[140:143], v[220:223], v[8:11]
	s_setprio 0
	s_setprio 1
	v_mfma_f32_16x16x32_bf16 v[52:55], v[144:147], v[180:183], v[52:55]
	v_mfma_f32_16x16x32_bf16 v[48:51], v[152:155], v[180:183], v[48:51]
	v_mfma_f32_16x16x32_bf16 v[36:39], v[144:147], v[196:199], v[36:39]
	v_mfma_f32_16x16x32_bf16 v[32:35], v[152:155], v[196:199], v[32:35]
	v_mfma_f32_16x16x32_bf16 v[20:23], v[144:147], v[208:211], v[20:23]
	v_mfma_f32_16x16x32_bf16 v[16:19], v[152:155], v[208:211], v[16:19]
	v_mfma_f32_16x16x32_bf16 v[4:7], v[144:147], v[216:219], v[4:7]
	v_mfma_f32_16x16x32_bf16 v[0:3], v[152:155], v[216:219], v[0:3]
	v_mfma_f32_16x16x32_bf16 v[52:55], v[148:151], v[184:187], v[52:55]
	v_mfma_f32_16x16x32_bf16 v[48:51], v[156:159], v[184:187], v[48:51]
	v_mfma_f32_16x16x32_bf16 v[36:39], v[148:151], v[200:203], v[36:39]
	v_mfma_f32_16x16x32_bf16 v[32:35], v[156:159], v[200:203], v[32:35]
	v_mfma_f32_16x16x32_bf16 v[20:23], v[148:151], v[212:215], v[20:23]
	v_mfma_f32_16x16x32_bf16 v[16:19], v[156:159], v[212:215], v[16:19]
	v_mfma_f32_16x16x32_bf16 v[4:7], v[148:151], v[220:223], v[4:7]
	v_mfma_f32_16x16x32_bf16 v[0:3], v[156:159], v[220:223], v[0:3]
	s_setprio 0
	s_barrier
	s_add_i32 s60, 0, 0x18000
	s_add_i32 s61, 0, 0x1c000
	v_add_u32_e32 v140, s60, v190
	v_add_u32_e32 v156, s61, v190
	ds_read_b128 v[128:131], v140
	ds_read_b128 v[132:135], v140 offset:1024
	ds_read_b128 v[136:139], v140 offset:2048
	ds_read_b128 v[140:143], v140 offset:3072
	ds_read_b128 v[144:147], v156
	ds_read_b128 v[148:151], v156 offset:1024
	ds_read_b128 v[152:155], v156 offset:2048
	ds_read_b128 v[156:159], v156 offset:3072
	s_add_u32 s34, s34, s10
	s_addc_u32 s35, s35, s11
	s_mov_b32 m0, s39
	ds_read_b128 v[180:183], v194 offset:32768
	ds_read_b128 v[184:187], v194 offset:33792
	ds_read_b128 v[196:199], v194 offset:34816
	ds_read_b128 v[200:203], v194 offset:35840
	ds_read_b128 v[208:211], v194 offset:36864
	ds_read_b128 v[212:215], v194 offset:37888
	ds_read_b128 v[216:219], v194 offset:38912
	ds_read_b128 v[220:223], v194 offset:39936
	global_load_lds_dwordx4 v160, s[34:35]
	s_mov_b32 m0, s40
	s_nop 0
	global_load_lds_dwordx4 v164, s[34:35]
	s_waitcnt vmcnt(8)
	s_waitcnt lgkmcnt(0)
	s_barrier
	s_setprio 1
	s_waitcnt lgkmcnt(0)
	v_mfma_f32_16x16x32_bf16 v[124:127], v[128:131], v[180:183], v[124:127]
	v_mfma_f32_16x16x32_bf16 v[120:123], v[136:139], v[180:183], v[120:123]
	v_mfma_f32_16x16x32_bf16 v[108:111], v[128:131], v[196:199], v[108:111]
	v_mfma_f32_16x16x32_bf16 v[104:107], v[136:139], v[196:199], v[104:107]
	v_mfma_f32_16x16x32_bf16 v[92:95], v[128:131], v[208:211], v[92:95]
	v_mfma_f32_16x16x32_bf16 v[88:91], v[136:139], v[208:211], v[88:91]
	v_mfma_f32_16x16x32_bf16 v[76:79], v[128:131], v[216:219], v[76:79]
	v_mfma_f32_16x16x32_bf16 v[72:75], v[136:139], v[216:219], v[72:75]
	v_mfma_f32_16x16x32_bf16 v[124:127], v[132:135], v[184:187], v[124:127]
	v_mfma_f32_16x16x32_bf16 v[120:123], v[140:143], v[184:187], v[120:123]
	v_mfma_f32_16x16x32_bf16 v[108:111], v[132:135], v[200:203], v[108:111]
	v_mfma_f32_16x16x32_bf16 v[104:107], v[140:143], v[200:203], v[104:107]
	v_mfma_f32_16x16x32_bf16 v[92:95], v[132:135], v[212:215], v[92:95]
	v_mfma_f32_16x16x32_bf16 v[88:91], v[140:143], v[212:215], v[88:91]
	v_mfma_f32_16x16x32_bf16 v[76:79], v[132:135], v[220:223], v[76:79]
	v_mfma_f32_16x16x32_bf16 v[72:75], v[140:143], v[220:223], v[72:75]
	s_setprio 0
	s_setprio 1
	v_mfma_f32_16x16x32_bf16 v[116:119], v[144:147], v[180:183], v[116:119]
	v_mfma_f32_16x16x32_bf16 v[112:115], v[152:155], v[180:183], v[112:115]
	v_mfma_f32_16x16x32_bf16 v[100:103], v[144:147], v[196:199], v[100:103]
	v_mfma_f32_16x16x32_bf16 v[96:99], v[152:155], v[196:199], v[96:99]
	v_mfma_f32_16x16x32_bf16 v[84:87], v[144:147], v[208:211], v[84:87]
	v_mfma_f32_16x16x32_bf16 v[80:83], v[152:155], v[208:211], v[80:83]
	v_mfma_f32_16x16x32_bf16 v[68:71], v[144:147], v[216:219], v[68:71]
	v_mfma_f32_16x16x32_bf16 v[64:67], v[152:155], v[216:219], v[64:67]
	v_mfma_f32_16x16x32_bf16 v[116:119], v[148:151], v[184:187], v[116:119]
	v_mfma_f32_16x16x32_bf16 v[112:115], v[156:159], v[184:187], v[112:115]
	v_mfma_f32_16x16x32_bf16 v[100:103], v[148:151], v[200:203], v[100:103]
	v_mfma_f32_16x16x32_bf16 v[96:99], v[156:159], v[200:203], v[96:99]
	v_mfma_f32_16x16x32_bf16 v[84:87], v[148:151], v[212:215], v[84:87]
	v_mfma_f32_16x16x32_bf16 v[80:83], v[156:159], v[212:215], v[80:83]
	v_mfma_f32_16x16x32_bf16 v[68:71], v[148:151], v[220:223], v[68:71]
	v_mfma_f32_16x16x32_bf16 v[64:67], v[156:159], v[220:223], v[64:67]
	s_setprio 0
	s_barrier
; #define PG8_STAGE(bufoff, gbase, voff) do { _Pragma("unroll") for (int _i = 0; _i < 2; ++_i) \
;         __builtin_amdgcn_global_load_lds((const unsigned*)((const char*)(gbase) + (voff)[_i]), (PG8_LAS unsigned*)(lds + (bufoff) + ldsw + _i * 8192), 16, 0, 0); } while (0)
; #define PG8_LDA(dst, b, h) do { _Pragma("unroll") for (int m = 0; m < 4; ++m) _Pragma("unroll") for (int k = 0; k < 2; ++k) dst[m][k] = *(const PG8_LAS bf16x8*)(lds + PG8_SA(b, h) + aoff + m * 2048 + k * 1024); } while (0)
; #define PG8_MMA(ai, bj, At, Bt) do { __builtin_amdgcn_s_setprio(1); _Pragma("unroll") for (int m = 0; m < 4; ++m) _Pragma("unroll") for (int n = 0; n < 2; ++n) _Pragma("unroll") for (int k = 0; k < 2; ++k) \
;         acc[ai][bj][m][n] = __builtin_amdgcn_mfma_f32_16x16x32_bf16(Bt[n][k], At[m][k], acc[ai][bj][m][n], 0, 0, 0); __builtin_amdgcn_s_setprio(0); } while (0)
; #define PG8_WAIT_V(n) asm volatile("s_waitcnt vmcnt(" #n ")" ::: "memory")
; #define PG8_WAIT_L(n) asm volatile("s_waitcnt lgkmcnt(" #n ")" ::: "memory")
; #define PG8_BAR __builtin_amdgcn_s_barrier()
; #define PG8_SCHED __builtin_amdgcn_sched_barrier(0)
; template <class Epi, class Sched, bool ALIGN_EPI = false, bool SP2 = false>
; __device__ __forceinline__ void gemm_phase(PG8_LAS unsigned char* lds, const Gemm g, const Sched& S, const Epi& E, int tid_in) {
;     ...
;             PG8_WAIT_V(8); PG8_WAIT_L(0); PG8_BAR; PG8_MMA(0, 0, At, B0); PG8_MMA(0, 1, At, B1); PG8_BAR; PG8_SCHED;
;             PG8_LDA(At, 1, 1); PG8_STAGE(PG8_SB(1, 0), b3, voffB); PG8_STAGE(PG8_SB(1, 1), b3 + hstepB, voffB); PG8_STAGE(PG8_SA(1, 0), a3, voffA);
;             PG8_WAIT_V(8); PG8_WAIT_L(0); PG8_BAR; PG8_MMA(1, 0, At, B0); PG8_MMA(1, 1, At, B1); PG8_BAR; PG8_SCHED;
	s_add_i32 s34, s60, s36
	v_lshl_add_u64 v[204:205], v[204:205], 0, s[22:23]
	s_mov_b32 m0, s34
	ds_read_b128 v[180:183], v194 offset:49152
	ds_read_b128 v[184:187], v194 offset:50176
	ds_read_b128 v[196:199], v194 offset:51200
	ds_read_b128 v[200:203], v194 offset:52224
	ds_read_b128 v[208:211], v194 offset:53248
	ds_read_b128 v[212:215], v194 offset:54272
	ds_read_b128 v[216:219], v194 offset:55296
	ds_read_b128 v[220:223], v194 offset:56320
	global_load_lds_dwordx4 v[204:205], off
	v_lshl_add_u64 v[204:205], v[224:225], 0, s[22:23]
	s_add_i32 m0, s34, 0x2000
	s_add_i32 s34, s61, s36
	global_load_lds_dwordx4 v[204:205], off
	v_lshl_add_u64 v[204:205], v[226:227], 0, s[22:23]
	s_mov_b32 m0, s34
	s_nop 0
	global_load_lds_dwordx4 v[204:205], off
	v_lshl_add_u64 v[204:205], v[228:229], 0, s[22:23]
	s_add_i32 m0, s34, 0x2000
	s_nop 0
	global_load_lds_dwordx4 v[204:205], off
	v_lshl_add_u64 v[204:205], v[230:231], 0, s[22:23]
	s_mov_b32 m0, s43
	s_nop 0
	global_load_lds_dwordx4 v[204:205], off
	v_lshl_add_u64 v[204:205], v[232:233], 0, s[22:23]
	s_mov_b32 m0, s44
	s_nop 0
	global_load_lds_dwordx4 v[204:205], off
	s_waitcnt vmcnt(8)
	s_waitcnt lgkmcnt(0)
	s_barrier
	s_setprio 1
	s_waitcnt lgkmcnt(0)
	v_mfma_f32_16x16x32_bf16 v[60:63], v[128:131], v[180:183], v[60:63]
	v_mfma_f32_16x16x32_bf16 v[56:59], v[136:139], v[180:183], v[56:59]
	v_mfma_f32_16x16x32_bf16 v[44:47], v[128:131], v[196:199], v[44:47]
	v_mfma_f32_16x16x32_bf16 v[40:43], v[136:139], v[196:199], v[40:43]
	v_mfma_f32_16x16x32_bf16 v[28:31], v[128:131], v[208:211], v[28:31]
	v_mfma_f32_16x16x32_bf16 v[24:27], v[136:139], v[208:211], v[24:27]
	v_mfma_f32_16x16x32_bf16 v[12:15], v[128:131], v[216:219], v[12:15]
	v_mfma_f32_16x16x32_bf16 v[8:11], v[136:139], v[216:219], v[8:11]
	v_mfma_f32_16x16x32_bf16 v[60:63], v[132:135], v[184:187], v[60:63]
	v_mfma_f32_16x16x32_bf16 v[56:59], v[140:143], v[184:187], v[56:59]
	v_mfma_f32_16x16x32_bf16 v[44:47], v[132:135], v[200:203], v[44:47]
	v_mfma_f32_16x16x32_bf16 v[40:43], v[140:143], v[200:203], v[40:43]
	v_mfma_f32_16x16x32_bf16 v[28:31], v[132:135], v[212:215], v[28:31]
	v_mfma_f32_16x16x32_bf16 v[24:27], v[140:143], v[212:215], v[24:27]
	v_mfma_f32_16x16x32_bf16 v[12:15], v[132:135], v[220:223], v[12:15]
	v_mfma_f32_16x16x32_bf16 v[8:11], v[140:143], v[220:223], v[8:11]
	s_setprio 0
	s_setprio 1
	v_mfma_f32_16x16x32_bf16 v[52:55], v[144:147], v[180:183], v[52:55]
	v_mfma_f32_16x16x32_bf16 v[48:51], v[152:155], v[180:183], v[48:51]
	v_mfma_f32_16x16x32_bf16 v[36:39], v[144:147], v[196:199], v[36:39]
	v_mfma_f32_16x16x32_bf16 v[32:35], v[152:155], v[196:199], v[32:35]
	v_mfma_f32_16x16x32_bf16 v[20:23], v[144:147], v[208:211], v[20:23]
	v_mfma_f32_16x16x32_bf16 v[16:19], v[152:155], v[208:211], v[16:19]
	v_mfma_f32_16x16x32_bf16 v[4:7], v[144:147], v[216:219], v[4:7]
	v_mfma_f32_16x16x32_bf16 v[0:3], v[152:155], v[216:219], v[0:3]
	v_mfma_f32_16x16x32_bf16 v[52:55], v[148:151], v[184:187], v[52:55]
	v_mfma_f32_16x16x32_bf16 v[48:51], v[156:159], v[184:187], v[48:51]
	v_mfma_f32_16x16x32_bf16 v[36:39], v[148:151], v[200:203], v[36:39]
	v_mfma_f32_16x16x32_bf16 v[32:35], v[156:159], v[200:203], v[32:35]
	v_mfma_f32_16x16x32_bf16 v[20:23], v[148:151], v[212:215], v[20:23]
	v_mfma_f32_16x16x32_bf16 v[16:19], v[156:159], v[212:215], v[16:19]
	v_mfma_f32_16x16x32_bf16 v[4:7], v[148:151], v[220:223], v[4:7]
	v_mfma_f32_16x16x32_bf16 v[0:3], v[156:159], v[220:223], v[0:3]
	s_setprio 0
	s_barrier
	s_add_u32 s30, s30, 0x100
	s_addc_u32 s31, s31, 0
	s_add_u32 s57, s57, 0x100
	s_addc_u32 s58, s58, 0
	s_cmp_ge_i32 s59, s45
	s_mov_b32 s34, s59
	s_cbranch_scc0 .LBB0_1172

; #define PG8_STAGE(bufoff, gbase, voff) do { _Pragma("unroll") for (int _i = 0; _i < 2; ++_i) \
;         __builtin_amdgcn_global_load_lds((const unsigned*)((const char*)(gbase) + (voff)[_i]), (PG8_LAS unsigned*)(lds + (bufoff) + ldsw + _i * 8192), 16, 0, 0); } while (0)
; #define PG8_LDA(dst, b, h) do { _Pragma("unroll") for (int m = 0; m < 4; ++m) _Pragma("unroll") for (int k = 0; k < 2; ++k) dst[m][k] = *(const PG8_LAS bf16x8*)(lds + PG8_SA(b, h) + aoff + m * 2048 + k * 1024); } while (0)
; #define PG8_LDB(dst, b, h) do { _Pragma("unroll") for (int n = 0; n < 2; ++n) _Pragma("unroll") for (int k = 0; k < 2; ++k) dst[n][k] = *(const PG8_LAS bf16x8*)(lds + PG8_SB(b, h) + boff + n * 2048 + k * 1024); } while (0)
; #define PG8_MMA(ai, bj, At, Bt) do { __builtin_amdgcn_s_setprio(1); _Pragma("unroll") for (int m = 0; m < 4; ++m) _Pragma("unroll") for (int n = 0; n < 2; ++n) _Pragma("unroll") for (int k = 0; k < 2; ++k) \
;         acc[ai][bj][m][n] = __builtin_amdgcn_mfma_f32_16x16x32_bf16(Bt[n][k], At[m][k], acc[ai][bj][m][n], 0, 0, 0); __builtin_amdgcn_s_setprio(0); } while (0)
; #define PG8_WAIT_V(n) asm volatile("s_waitcnt vmcnt(" #n ")" ::: "memory")
; #define PG8_WAIT_L(n) asm volatile("s_waitcnt lgkmcnt(" #n ")" ::: "memory")
; #define PG8_BAR __builtin_amdgcn_s_barrier()
; #define PG8_SCHED __builtin_amdgcn_sched_barrier(0)
; template <class Epi, class Sched, bool ALIGN_EPI = false, bool SP2 = false>
; __device__ __forceinline__ void gemm_phase(PG8_LAS unsigned char* lds, const Gemm g, const Sched& S, const Epi& E, int tid_in) {
;     ...
;             if constexpr (SP2) {
;             PG8_LDB(B0, 0, 0); PG8_LDB(B1, 0, 1); PG8_SCHED; PG8_LDA(At, 0, 0); PG8_STAGE(PG8_SA(1, 1), a1 + hstepA, voffA);
;             PG8_WAIT_V(8); PG8_WAIT_L(0); PG8_BAR; PG8_MMA(0, 0, At, B0); PG8_MMA(0, 1, At, B1); PG8_BAR; PG8_SCHED;
;             PG8_LDA(At, 0, 1); PG8_STAGE(PG8_SB(0, 0), b2, voffB); PG8_STAGE(PG8_SB(0, 1), b2 + hstepB, voffB); PG8_STAGE(PG8_SA(0, 0), a2, voffA);
;             PG8_WAIT_V(8); PG8_WAIT_L(0); PG8_BAR; PG8_MMA(1, 0, At, B0); PG8_MMA(1, 1, At, B1); PG8_BAR; PG8_SCHED;
.LBB0_1281:
	ds_read_b128 v[144:147], v155
	ds_read_b128 v[148:151], v155 offset:1024
	ds_read_b128 v[160:163], v155 offset:2048
	ds_read_b128 v[164:167], v155 offset:3072
	ds_read_b128 v[168:171], v156
	ds_read_b128 v[172:175], v156 offset:1024
	ds_read_b128 v[176:179], v156 offset:2048
	ds_read_b128 v[180:183], v156 offset:3072
	s_add_i32 s56, s30, 2
	s_add_u32 s57, s28, 0x80
	s_addc_u32 s31, s29, 0
	s_cmp_eq_u32 s44, s30
	s_cselect_b32 s30, s8, s57
	s_cselect_b32 s31, s9, s31
	s_cselect_b32 s59, s27, s55
	s_cselect_b32 s58, s26, s54
	s_add_i32 m0, s36, 0xc000
	ds_read_b128 v[184:187], v157
	ds_read_b128 v[188:191], v157 offset:1024
	ds_read_b128 v[192:195], v157 offset:2048
	ds_read_b128 v[196:199], v157 offset:3072
	ds_read_b128 v[200:203], v157 offset:4096
	ds_read_b128 v[208:211], v157 offset:5120
	ds_read_b128 v[212:215], v157 offset:6144
	ds_read_b128 v[216:219], v157 offset:7168
	global_load_lds_dwordx4 v136, s[28:29]
	s_add_i32 m0, s36, 0xe000
	s_nop 0
	global_load_lds_dwordx4 v138, s[28:29]
	s_waitcnt vmcnt(8)
	s_waitcnt lgkmcnt(0)
	s_barrier
	s_setprio 1
	s_waitcnt lgkmcnt(0)
	v_mfma_f32_16x16x32_bf16 v[116:119], v[144:147], v[184:187], v[116:119]
	v_mfma_f32_16x16x32_bf16 v[124:127], v[160:163], v[184:187], v[124:127]
	v_mfma_f32_16x16x32_bf16 v[104:107], v[144:147], v[192:195], v[104:107]
	v_mfma_f32_16x16x32_bf16 v[108:111], v[160:163], v[192:195], v[108:111]
	v_mfma_f32_16x16x32_bf16 v[88:91], v[144:147], v[200:203], v[88:91]
	v_mfma_f32_16x16x32_bf16 v[92:95], v[160:163], v[200:203], v[92:95]
	v_mfma_f32_16x16x32_bf16 v[72:75], v[144:147], v[212:215], v[72:75]
	v_mfma_f32_16x16x32_bf16 v[76:79], v[160:163], v[212:215], v[76:79]
	v_mfma_f32_16x16x32_bf16 v[116:119], v[148:151], v[188:191], v[116:119]
	v_mfma_f32_16x16x32_bf16 v[124:127], v[164:167], v[188:191], v[124:127]
	v_mfma_f32_16x16x32_bf16 v[104:107], v[148:151], v[196:199], v[104:107]
	v_mfma_f32_16x16x32_bf16 v[108:111], v[164:167], v[196:199], v[108:111]
	v_mfma_f32_16x16x32_bf16 v[88:91], v[148:151], v[208:211], v[88:91]
	v_mfma_f32_16x16x32_bf16 v[92:95], v[164:167], v[208:211], v[92:95]
	v_mfma_f32_16x16x32_bf16 v[72:75], v[148:151], v[216:219], v[72:75]
	v_mfma_f32_16x16x32_bf16 v[76:79], v[164:167], v[216:219], v[76:79]
	s_setprio 0
	s_setprio 1
	v_mfma_f32_16x16x32_bf16 v[112:115], v[168:171], v[184:187], v[112:115]
	v_mfma_f32_16x16x32_bf16 v[120:123], v[176:179], v[184:187], v[120:123]
	v_mfma_f32_16x16x32_bf16 v[96:99], v[168:171], v[192:195], v[96:99]
	v_mfma_f32_16x16x32_bf16 v[100:103], v[176:179], v[192:195], v[100:103]
	v_mfma_f32_16x16x32_bf16 v[80:83], v[168:171], v[200:203], v[80:83]
	v_mfma_f32_16x16x32_bf16 v[84:87], v[176:179], v[200:203], v[84:87]
	v_mfma_f32_16x16x32_bf16 v[64:67], v[168:171], v[212:215], v[64:67]
	v_mfma_f32_16x16x32_bf16 v[68:71], v[176:179], v[212:215], v[68:71]
	v_mfma_f32_16x16x32_bf16 v[112:115], v[172:175], v[188:191], v[112:115]
	v_mfma_f32_16x16x32_bf16 v[120:123], v[180:183], v[188:191], v[120:123]
	v_mfma_f32_16x16x32_bf16 v[96:99], v[172:175], v[196:199], v[96:99]
	v_mfma_f32_16x16x32_bf16 v[100:103], v[180:183], v[196:199], v[100:103]
	v_mfma_f32_16x16x32_bf16 v[80:83], v[172:175], v[208:211], v[80:83]
	v_mfma_f32_16x16x32_bf16 v[84:87], v[180:183], v[208:211], v[84:87]
	v_mfma_f32_16x16x32_bf16 v[64:67], v[172:175], v[216:219], v[64:67]
	v_mfma_f32_16x16x32_bf16 v[68:71], v[180:183], v[216:219], v[68:71]
	s_setprio 0
	s_barrier
	s_add_i32 s57, s47, s33
	v_lshl_add_u64 v[204:205], s[58:59], 0, v[132:133]
	s_mov_b32 m0, s57
	ds_read_b128 v[184:187], v157 offset:16384
	ds_read_b128 v[188:191], v157 offset:17408
	ds_read_b128 v[192:195], v157 offset:18432
	ds_read_b128 v[196:199], v157 offset:19456
	ds_read_b128 v[200:203], v157 offset:20480
	ds_read_b128 v[208:211], v157 offset:21504
	ds_read_b128 v[212:215], v157 offset:22528
	ds_read_b128 v[216:219], v157 offset:23552
	global_load_lds_dwordx4 v[204:205], off
	s_add_i32 m0, s57, 0x2000
	v_lshl_add_u64 v[220:221], s[58:59], 0, v[128:129]
	s_add_u32 s58, s58, s10
	s_addc_u32 s59, s59, s11
	s_add_i32 s57, s48, s33
	global_load_lds_dwordx4 v[220:221], off
	v_lshl_add_u64 v[222:223], s[58:59], 0, v[132:133]
	s_mov_b32 m0, s57
	v_lshl_add_u64 v[224:225], s[58:59], 0, v[128:129]
	global_load_lds_dwordx4 v[222:223], off
	s_add_i32 m0, s57, 0x2000
	v_lshl_add_u64 v[226:227], s[30:31], 0, v[134:135]
	global_load_lds_dwordx4 v[224:225], off
	s_mov_b32 m0, s36
	v_lshl_add_u64 v[228:229], s[30:31], 0, v[130:131]
	global_load_lds_dwordx4 v[226:227], off
	s_mov_b32 m0, s37
	s_nop 0
	global_load_lds_dwordx4 v[228:229], off
	s_waitcnt vmcnt(8)
	s_waitcnt lgkmcnt(0)
	s_barrier
; #define PG8_STAGE(bufoff, gbase, voff) do { _Pragma("unroll") for (int _i = 0; _i < 2; ++_i) \
;         __builtin_amdgcn_global_load_lds((const unsigned*)((const char*)(gbase) + (voff)[_i]), (PG8_LAS unsigned*)(lds + (bufoff) + ldsw + _i * 8192), 16, 0, 0); } while (0)
; #define PG8_LDA(dst, b, h) do { _Pragma("unroll") for (int m = 0; m < 4; ++m) _Pragma("unroll") for (int k = 0; k < 2; ++k) dst[m][k] = *(const PG8_LAS bf16x8*)(lds + PG8_SA(b, h) + aoff + m * 2048 + k * 1024); } while (0)
; #define PG8_LDB(dst, b, h) do { _Pragma("unroll") for (int n = 0; n < 2; ++n) _Pragma("unroll") for (int k = 0; k < 2; ++k) dst[n][k] = *(const PG8_LAS bf16x8*)(lds + PG8_SB(b, h) + boff + n * 2048 + k * 1024); } while (0)
; #define PG8_MMA(ai, bj, At, Bt) do { __builtin_amdgcn_s_setprio(1); _Pragma("unroll") for (int m = 0; m < 4; ++m) _Pragma("unroll") for (int n = 0; n < 2; ++n) _Pragma("unroll") for (int k = 0; k < 2; ++k) \
;         acc[ai][bj][m][n] = __builtin_amdgcn_mfma_f32_16x16x32_bf16(Bt[n][k], At[m][k], acc[ai][bj][m][n], 0, 0, 0); __builtin_amdgcn_s_setprio(0); } while (0)
; #define PG8_WAIT_V(n) asm volatile("s_waitcnt vmcnt(" #n ")" ::: "memory")
; #define PG8_WAIT_L(n) asm volatile("s_waitcnt lgkmcnt(" #n ")" ::: "memory")
; #define PG8_BAR __builtin_amdgcn_s_barrier()
; #define PG8_SCHED __builtin_amdgcn_sched_barrier(0)
; template <class Epi, class Sched, bool ALIGN_EPI = false, bool SP2 = false>
; __device__ __forceinline__ void gemm_phase(PG8_LAS unsigned char* lds, const Gemm g, const Sched& S, const Epi& E, int tid_in) {
;     ...
;             PG8_WAIT_V(8); PG8_WAIT_L(0); PG8_BAR; PG8_MMA(1, 0, At, B0); PG8_MMA(1, 1, At, B1); PG8_BAR; PG8_SCHED;
;             PG8_LDB(B0, 1, 0); PG8_LDB(B1, 1, 1); PG8_SCHED; PG8_LDA(At, 1, 0); PG8_STAGE(PG8_SA(0, 1), a2 + hstepA, voffA);
;             PG8_WAIT_V(8); PG8_WAIT_L(0); PG8_BAR; PG8_MMA(0, 0, At, B0); PG8_MMA(0, 1, At, B1); PG8_BAR; PG8_SCHED;
	s_setprio 1
	s_waitcnt lgkmcnt(0)
	v_mfma_f32_16x16x32_bf16 v[56:59], v[144:147], v[184:187], v[56:59]
	v_mfma_f32_16x16x32_bf16 v[60:63], v[160:163], v[184:187], v[60:63]
	v_mfma_f32_16x16x32_bf16 v[40:43], v[144:147], v[192:195], v[40:43]
	v_mfma_f32_16x16x32_bf16 v[44:47], v[160:163], v[192:195], v[44:47]
	v_mfma_f32_16x16x32_bf16 v[24:27], v[144:147], v[200:203], v[24:27]
	v_mfma_f32_16x16x32_bf16 v[28:31], v[160:163], v[200:203], v[28:31]
	v_mfma_f32_16x16x32_bf16 v[8:11], v[144:147], v[212:215], v[8:11]
	v_mfma_f32_16x16x32_bf16 v[12:15], v[160:163], v[212:215], v[12:15]
	v_mfma_f32_16x16x32_bf16 v[56:59], v[148:151], v[188:191], v[56:59]
	v_mfma_f32_16x16x32_bf16 v[60:63], v[164:167], v[188:191], v[60:63]
	v_mfma_f32_16x16x32_bf16 v[40:43], v[148:151], v[196:199], v[40:43]
	v_mfma_f32_16x16x32_bf16 v[44:47], v[164:167], v[196:199], v[44:47]
	v_mfma_f32_16x16x32_bf16 v[24:27], v[148:151], v[208:211], v[24:27]
	v_mfma_f32_16x16x32_bf16 v[28:31], v[164:167], v[208:211], v[28:31]
	v_mfma_f32_16x16x32_bf16 v[8:11], v[148:151], v[216:219], v[8:11]
	v_mfma_f32_16x16x32_bf16 v[12:15], v[164:167], v[216:219], v[12:15]
	s_setprio 0
	s_setprio 1
	v_mfma_f32_16x16x32_bf16 v[48:51], v[168:171], v[184:187], v[48:51]
	v_mfma_f32_16x16x32_bf16 v[52:55], v[176:179], v[184:187], v[52:55]
	v_mfma_f32_16x16x32_bf16 v[32:35], v[168:171], v[192:195], v[32:35]
	v_mfma_f32_16x16x32_bf16 v[36:39], v[176:179], v[192:195], v[36:39]
	v_mfma_f32_16x16x32_bf16 v[16:19], v[168:171], v[200:203], v[16:19]
	v_mfma_f32_16x16x32_bf16 v[20:23], v[176:179], v[200:203], v[20:23]
	v_mfma_f32_16x16x32_bf16 v[4:7], v[168:171], v[212:215], v[4:7]
	v_mfma_f32_16x16x32_bf16 v[0:3], v[176:179], v[212:215], v[0:3]
	v_mfma_f32_16x16x32_bf16 v[48:51], v[172:175], v[188:191], v[48:51]
	v_mfma_f32_16x16x32_bf16 v[52:55], v[180:183], v[188:191], v[52:55]
	v_mfma_f32_16x16x32_bf16 v[32:35], v[172:175], v[196:199], v[32:35]
	v_mfma_f32_16x16x32_bf16 v[36:39], v[180:183], v[196:199], v[36:39]
	v_mfma_f32_16x16x32_bf16 v[16:19], v[172:175], v[208:211], v[16:19]
	v_mfma_f32_16x16x32_bf16 v[20:23], v[180:183], v[208:211], v[20:23]
	v_mfma_f32_16x16x32_bf16 v[4:7], v[172:175], v[216:219], v[4:7]
	v_mfma_f32_16x16x32_bf16 v[0:3], v[180:183], v[216:219], v[0:3]
	s_setprio 0
	s_barrier
	s_add_i32 s57, 0, 0x18000
	v_add_u32_e32 v159, s57, v153
	s_add_i32 s58, 0, 0x1c000
	ds_read_b128 v[144:147], v159
	ds_read_b128 v[148:151], v159 offset:1024
	ds_read_b128 v[160:163], v159 offset:2048
	ds_read_b128 v[164:167], v159 offset:3072
	v_add_u32_e32 v159, s58, v153
	ds_read_b128 v[168:171], v159
	ds_read_b128 v[172:175], v159 offset:1024
	ds_read_b128 v[176:179], v159 offset:2048
	ds_read_b128 v[180:183], v159 offset:3072
	s_add_u32 s30, s30, s10
	s_addc_u32 s31, s31, s11
	s_mov_b32 m0, s38
	ds_read_b128 v[184:187], v157 offset:32768
	ds_read_b128 v[188:191], v157 offset:33792
	ds_read_b128 v[192:195], v157 offset:34816
	ds_read_b128 v[196:199], v157 offset:35840
	ds_read_b128 v[200:203], v157 offset:36864
	ds_read_b128 v[208:211], v157 offset:37888
	ds_read_b128 v[212:215], v157 offset:38912
	ds_read_b128 v[216:219], v157 offset:39936
	global_load_lds_dwordx4 v134, s[30:31]
	s_mov_b32 m0, s39
	s_nop 0
	global_load_lds_dwordx4 v130, s[30:31]
	s_waitcnt vmcnt(8)
	s_waitcnt lgkmcnt(0)
	s_barrier
	s_setprio 1
	s_waitcnt lgkmcnt(0)
	v_mfma_f32_16x16x32_bf16 v[116:119], v[144:147], v[184:187], v[116:119]
	v_mfma_f32_16x16x32_bf16 v[124:127], v[160:163], v[184:187], v[124:127]
	v_mfma_f32_16x16x32_bf16 v[104:107], v[144:147], v[192:195], v[104:107]
	v_mfma_f32_16x16x32_bf16 v[108:111], v[160:163], v[192:195], v[108:111]
	v_mfma_f32_16x16x32_bf16 v[88:91], v[144:147], v[200:203], v[88:91]
	v_mfma_f32_16x16x32_bf16 v[92:95], v[160:163], v[200:203], v[92:95]
	v_mfma_f32_16x16x32_bf16 v[72:75], v[144:147], v[212:215], v[72:75]
	v_mfma_f32_16x16x32_bf16 v[76:79], v[160:163], v[212:215], v[76:79]
	v_mfma_f32_16x16x32_bf16 v[116:119], v[148:151], v[188:191], v[116:119]
	v_mfma_f32_16x16x32_bf16 v[124:127], v[164:167], v[188:191], v[124:127]
	v_mfma_f32_16x16x32_bf16 v[104:107], v[148:151], v[196:199], v[104:107]
	v_mfma_f32_16x16x32_bf16 v[108:111], v[164:167], v[196:199], v[108:111]
	v_mfma_f32_16x16x32_bf16 v[88:91], v[148:151], v[208:211], v[88:91]
	v_mfma_f32_16x16x32_bf16 v[92:95], v[164:167], v[208:211], v[92:95]
	v_mfma_f32_16x16x32_bf16 v[72:75], v[148:151], v[216:219], v[72:75]
	v_mfma_f32_16x16x32_bf16 v[76:79], v[164:167], v[216:219], v[76:79]
	s_setprio 0
	s_setprio 1
	v_mfma_f32_16x16x32_bf16 v[112:115], v[168:171], v[184:187], v[112:115]
	v_mfma_f32_16x16x32_bf16 v[120:123], v[176:179], v[184:187], v[120:123]
	v_mfma_f32_16x16x32_bf16 v[96:99], v[168:171], v[192:195], v[96:99]
	v_mfma_f32_16x16x32_bf16 v[100:103], v[176:179], v[192:195], v[100:103]
	v_mfma_f32_16x16x32_bf16 v[80:83], v[168:171], v[200:203], v[80:83]
	v_mfma_f32_16x16x32_bf16 v[84:87], v[176:179], v[200:203], v[84:87]
	v_mfma_f32_16x16x32_bf16 v[64:67], v[168:171], v[212:215], v[64:67]
	v_mfma_f32_16x16x32_bf16 v[68:71], v[176:179], v[212:215], v[68:71]
	v_mfma_f32_16x16x32_bf16 v[112:115], v[172:175], v[188:191], v[112:115]
	v_mfma_f32_16x16x32_bf16 v[120:123], v[180:183], v[188:191], v[120:123]
	v_mfma_f32_16x16x32_bf16 v[96:99], v[172:175], v[196:199], v[96:99]
	v_mfma_f32_16x16x32_bf16 v[100:103], v[180:183], v[196:199], v[100:103]
	v_mfma_f32_16x16x32_bf16 v[80:83], v[172:175], v[208:211], v[80:83]
	v_mfma_f32_16x16x32_bf16 v[84:87], v[180:183], v[208:211], v[84:87]
	v_mfma_f32_16x16x32_bf16 v[64:67], v[172:175], v[216:219], v[64:67]
	v_mfma_f32_16x16x32_bf16 v[68:71], v[180:183], v[216:219], v[68:71]
	s_setprio 0
	s_barrier
; #define PG8_STAGE(bufoff, gbase, voff) do { _Pragma("unroll") for (int _i = 0; _i < 2; ++_i) \
;         __builtin_amdgcn_global_load_lds((const unsigned*)((const char*)(gbase) + (voff)[_i]), (PG8_LAS unsigned*)(lds + (bufoff) + ldsw + _i * 8192), 16, 0, 0); } while (0)
; #define PG8_LDA(dst, b, h) do { _Pragma("unroll") for (int m = 0; m < 4; ++m) _Pragma("unroll") for (int k = 0; k < 2; ++k) dst[m][k] = *(const PG8_LAS bf16x8*)(lds + PG8_SA(b, h) + aoff + m * 2048 + k * 1024); } while (0)
; #define PG8_MMA(ai, bj, At, Bt) do { __builtin_amdgcn_s_setprio(1); _Pragma("unroll") for (int m = 0; m < 4; ++m) _Pragma("unroll") for (int n = 0; n < 2; ++n) _Pragma("unroll") for (int k = 0; k < 2; ++k) \
;         acc[ai][bj][m][n] = __builtin_amdgcn_mfma_f32_16x16x32_bf16(Bt[n][k], At[m][k], acc[ai][bj][m][n], 0, 0, 0); __builtin_amdgcn_s_setprio(0); } while (0)
; #define PG8_WAIT_V(n) asm volatile("s_waitcnt vmcnt(" #n ")" ::: "memory")
; #define PG8_WAIT_L(n) asm volatile("s_waitcnt lgkmcnt(" #n ")" ::: "memory")
; #define PG8_BAR __builtin_amdgcn_s_barrier()
; #define PG8_SCHED __builtin_amdgcn_sched_barrier(0)
; template <class Epi, class Sched, bool ALIGN_EPI = false, bool SP2 = false>
; __device__ __forceinline__ void gemm_phase(PG8_LAS unsigned char* lds, const Gemm g, const Sched& S, const Epi& E, int tid_in) {
;     ...
;             PG8_WAIT_V(8); PG8_WAIT_L(0); PG8_BAR; PG8_MMA(0, 0, At, B0); PG8_MMA(0, 1, At, B1); PG8_BAR; PG8_SCHED;
;             PG8_LDA(At, 1, 1); PG8_STAGE(PG8_SB(1, 0), b3, voffB); PG8_STAGE(PG8_SB(1, 1), b3 + hstepB, voffB); PG8_STAGE(PG8_SA(1, 0), a3, voffA);
;             PG8_WAIT_V(8); PG8_WAIT_L(0); PG8_BAR; PG8_MMA(1, 0, At, B0); PG8_MMA(1, 1, At, B1); PG8_BAR; PG8_SCHED;
	s_add_i32 s30, s57, s33
	v_lshl_add_u64 v[204:205], v[204:205], 0, s[20:21]
	s_mov_b32 m0, s30
	ds_read_b128 v[184:187], v157 offset:49152
	ds_read_b128 v[188:191], v157 offset:50176
	ds_read_b128 v[192:195], v157 offset:51200
	ds_read_b128 v[196:199], v157 offset:52224
	ds_read_b128 v[200:203], v157 offset:53248
	ds_read_b128 v[208:211], v157 offset:54272
	ds_read_b128 v[212:215], v157 offset:55296
	ds_read_b128 v[216:219], v157 offset:56320
	global_load_lds_dwordx4 v[204:205], off
	v_lshl_add_u64 v[204:205], v[220:221], 0, s[20:21]
	s_add_i32 m0, s30, 0x2000
	s_add_i32 s30, s58, s33
	global_load_lds_dwordx4 v[204:205], off
	v_lshl_add_u64 v[204:205], v[222:223], 0, s[20:21]
	s_mov_b32 m0, s30
	s_nop 0
	global_load_lds_dwordx4 v[204:205], off
	v_lshl_add_u64 v[204:205], v[224:225], 0, s[20:21]
	s_add_i32 m0, s30, 0x2000
	s_nop 0
	global_load_lds_dwordx4 v[204:205], off
	v_lshl_add_u64 v[204:205], v[226:227], 0, s[20:21]
	s_mov_b32 m0, s41
	s_nop 0
	global_load_lds_dwordx4 v[204:205], off
	v_lshl_add_u64 v[204:205], v[228:229], 0, s[20:21]
	s_mov_b32 m0, s42
	s_nop 0
	global_load_lds_dwordx4 v[204:205], off
	s_waitcnt vmcnt(8)
	s_waitcnt lgkmcnt(0)
	s_barrier
	s_setprio 1
	s_waitcnt lgkmcnt(0)
	v_mfma_f32_16x16x32_bf16 v[56:59], v[144:147], v[184:187], v[56:59]
	v_mfma_f32_16x16x32_bf16 v[60:63], v[160:163], v[184:187], v[60:63]
	v_mfma_f32_16x16x32_bf16 v[40:43], v[144:147], v[192:195], v[40:43]
	v_mfma_f32_16x16x32_bf16 v[44:47], v[160:163], v[192:195], v[44:47]
	v_mfma_f32_16x16x32_bf16 v[24:27], v[144:147], v[200:203], v[24:27]
	v_mfma_f32_16x16x32_bf16 v[28:31], v[160:163], v[200:203], v[28:31]
	v_mfma_f32_16x16x32_bf16 v[8:11], v[144:147], v[212:215], v[8:11]
	v_mfma_f32_16x16x32_bf16 v[12:15], v[160:163], v[212:215], v[12:15]
	v_mfma_f32_16x16x32_bf16 v[56:59], v[148:151], v[188:191], v[56:59]
	v_mfma_f32_16x16x32_bf16 v[60:63], v[164:167], v[188:191], v[60:63]
	v_mfma_f32_16x16x32_bf16 v[40:43], v[148:151], v[196:199], v[40:43]
	v_mfma_f32_16x16x32_bf16 v[44:47], v[164:167], v[196:199], v[44:47]
	v_mfma_f32_16x16x32_bf16 v[24:27], v[148:151], v[208:211], v[24:27]
	v_mfma_f32_16x16x32_bf16 v[28:31], v[164:167], v[208:211], v[28:31]
	v_mfma_f32_16x16x32_bf16 v[8:11], v[148:151], v[216:219], v[8:11]
	v_mfma_f32_16x16x32_bf16 v[12:15], v[164:167], v[216:219], v[12:15]
	s_setprio 0
	s_setprio 1
	v_mfma_f32_16x16x32_bf16 v[48:51], v[168:171], v[184:187], v[48:51]
	v_mfma_f32_16x16x32_bf16 v[52:55], v[176:179], v[184:187], v[52:55]
	v_mfma_f32_16x16x32_bf16 v[32:35], v[168:171], v[192:195], v[32:35]
	v_mfma_f32_16x16x32_bf16 v[36:39], v[176:179], v[192:195], v[36:39]
	v_mfma_f32_16x16x32_bf16 v[16:19], v[168:171], v[200:203], v[16:19]
	v_mfma_f32_16x16x32_bf16 v[20:23], v[176:179], v[200:203], v[20:23]
	v_mfma_f32_16x16x32_bf16 v[4:7], v[168:171], v[212:215], v[4:7]
	v_mfma_f32_16x16x32_bf16 v[0:3], v[176:179], v[212:215], v[0:3]
	v_mfma_f32_16x16x32_bf16 v[48:51], v[172:175], v[188:191], v[48:51]
	v_mfma_f32_16x16x32_bf16 v[52:55], v[180:183], v[188:191], v[52:55]
	v_mfma_f32_16x16x32_bf16 v[32:35], v[172:175], v[196:199], v[32:35]
	v_mfma_f32_16x16x32_bf16 v[36:39], v[180:183], v[196:199], v[36:39]
	v_mfma_f32_16x16x32_bf16 v[16:19], v[172:175], v[208:211], v[16:19]
	v_mfma_f32_16x16x32_bf16 v[20:23], v[180:183], v[208:211], v[20:23]
	v_mfma_f32_16x16x32_bf16 v[4:7], v[172:175], v[216:219], v[4:7]
	v_mfma_f32_16x16x32_bf16 v[0:3], v[180:183], v[216:219], v[0:3]
	s_setprio 0
	s_barrier
	s_add_u32 s28, s28, 0x100
	s_addc_u32 s29, s29, 0
	s_add_u32 s54, s54, 0x100
	s_addc_u32 s55, s55, 0
	s_cmp_ge_i32 s56, s43
	s_mov_b32 s30, s56
	s_cbranch_scc0 .LBB0_1281

; #define PG8_STAGE(bufoff, gbase, voff) do { _Pragma("unroll") for (int _i = 0; _i < 2; ++_i) \
;         __builtin_amdgcn_global_load_lds((const unsigned*)((const char*)(gbase) + (voff)[_i]), (PG8_LAS unsigned*)(lds + (bufoff) + ldsw + _i * 8192), 16, 0, 0); } while (0)
; #define PG8_LDA(dst, b, h) do { _Pragma("unroll") for (int m = 0; m < 4; ++m) _Pragma("unroll") for (int k = 0; k < 2; ++k) dst[m][k] = *(const PG8_LAS bf16x8*)(lds + PG8_SA(b, h) + aoff + m * 2048 + k * 1024); } while (0)
; #define PG8_LDB(dst, b, h) do { _Pragma("unroll") for (int n = 0; n < 2; ++n) _Pragma("unroll") for (int k = 0; k < 2; ++k) dst[n][k] = *(const PG8_LAS bf16x8*)(lds + PG8_SB(b, h) + boff + n * 2048 + k * 1024); } while (0)
; #define PG8_MMA(ai, bj, At, Bt) do { __builtin_amdgcn_s_setprio(1); _Pragma("unroll") for (int m = 0; m < 4; ++m) _Pragma("unroll") for (int n = 0; n < 2; ++n) _Pragma("unroll") for (int k = 0; k < 2; ++k) \
;         acc[ai][bj][m][n] = __builtin_amdgcn_mfma_f32_16x16x32_bf16(Bt[n][k], At[m][k], acc[ai][bj][m][n], 0, 0, 0); __builtin_amdgcn_s_setprio(0); } while (0)
; #define PG8_WAIT_V(n) asm volatile("s_waitcnt vmcnt(" #n ")" ::: "memory")
; #define PG8_WAIT_L(n) asm volatile("s_waitcnt lgkmcnt(" #n ")" ::: "memory")
; #define PG8_BAR __builtin_amdgcn_s_barrier()
; #define PG8_SCHED __builtin_amdgcn_sched_barrier(0)
; template <class Epi, class Sched, bool ALIGN_EPI = false, bool SP2 = false>
; __device__ __forceinline__ void gemm_phase(PG8_LAS unsigned char* lds, const Gemm g, const Sched& S, const Epi& E, int tid_in) {
;     ...
;             if constexpr (SP2) {
;             PG8_LDB(B0, 0, 0); PG8_LDB(B1, 0, 1); PG8_SCHED; PG8_LDA(At, 0, 0); PG8_STAGE(PG8_SA(1, 1), a1 + hstepA, voffA);
;             PG8_WAIT_V(8); PG8_WAIT_L(0); PG8_BAR; PG8_MMA(0, 0, At, B0); PG8_MMA(0, 1, At, B1); PG8_BAR; PG8_SCHED;
;             PG8_LDA(At, 0, 1); PG8_STAGE(PG8_SB(0, 0), b2, voffB); PG8_STAGE(PG8_SB(0, 1), b2 + hstepB, voffB); PG8_STAGE(PG8_SA(0, 0), a2, voffA);
;             PG8_WAIT_V(8); PG8_WAIT_L(0); PG8_BAR; PG8_MMA(1, 0, At, B0); PG8_MMA(1, 1, At, B1); PG8_BAR; PG8_SCHED;
.LBB0_1354:
	ds_read_b128 v[128:131], v176
	ds_read_b128 v[132:135], v176 offset:1024
	ds_read_b128 v[136:139], v176 offset:2048
	ds_read_b128 v[140:143], v176 offset:3072
	ds_read_b128 v[162:165], v177
	ds_read_b128 v[166:169], v177 offset:1024
	ds_read_b128 v[180:183], v177 offset:2048
	ds_read_b128 v[184:187], v177 offset:3072
	s_add_i32 s53, s28, 2
	s_add_u32 s54, s26, 0x80
	s_addc_u32 s29, s27, 0
	s_cmp_eq_u32 s43, s28
	s_cselect_b32 s28, s8, s54
	s_cselect_b32 s29, s9, s29
	s_cselect_b32 s55, s25, s52
	s_cselect_b32 s54, s24, s51
	s_add_i32 m0, s35, 0xc000
	ds_read_b128 v[188:191], v178
	ds_read_b128 v[192:195], v178 offset:1024
	ds_read_b128 v[196:199], v178 offset:2048
	ds_read_b128 v[200:203], v178 offset:3072
	ds_read_b128 v[208:211], v178 offset:4096
	ds_read_b128 v[212:215], v178 offset:5120
	ds_read_b128 v[216:219], v178 offset:6144
	ds_read_b128 v[220:223], v178 offset:7168
	global_load_lds_dwordx4 v154, s[26:27]
	s_add_i32 m0, s35, 0xe000
	s_nop 0
	global_load_lds_dwordx4 v156, s[26:27]
	s_waitcnt vmcnt(8)
	s_waitcnt lgkmcnt(0)
	s_barrier
	s_setprio 1
	s_waitcnt lgkmcnt(0)
	v_mfma_f32_16x16x32_bf16 v[120:123], v[128:131], v[188:191], v[120:123]
	v_mfma_f32_16x16x32_bf16 v[124:127], v[136:139], v[188:191], v[124:127]
	v_mfma_f32_16x16x32_bf16 v[108:111], v[128:131], v[196:199], v[108:111]
	v_mfma_f32_16x16x32_bf16 v[104:107], v[136:139], v[196:199], v[104:107]
	v_mfma_f32_16x16x32_bf16 v[92:95], v[128:131], v[208:211], v[92:95]
	v_mfma_f32_16x16x32_bf16 v[88:91], v[136:139], v[208:211], v[88:91]
	v_mfma_f32_16x16x32_bf16 v[76:79], v[128:131], v[216:219], v[76:79]
	v_mfma_f32_16x16x32_bf16 v[72:75], v[136:139], v[216:219], v[72:75]
	v_mfma_f32_16x16x32_bf16 v[120:123], v[132:135], v[192:195], v[120:123]
	v_mfma_f32_16x16x32_bf16 v[124:127], v[140:143], v[192:195], v[124:127]
	v_mfma_f32_16x16x32_bf16 v[108:111], v[132:135], v[200:203], v[108:111]
	v_mfma_f32_16x16x32_bf16 v[104:107], v[140:143], v[200:203], v[104:107]
	v_mfma_f32_16x16x32_bf16 v[92:95], v[132:135], v[212:215], v[92:95]
	v_mfma_f32_16x16x32_bf16 v[88:91], v[140:143], v[212:215], v[88:91]
	v_mfma_f32_16x16x32_bf16 v[76:79], v[132:135], v[220:223], v[76:79]
	v_mfma_f32_16x16x32_bf16 v[72:75], v[140:143], v[220:223], v[72:75]
	s_setprio 0
	s_setprio 1
	v_mfma_f32_16x16x32_bf16 v[116:119], v[162:165], v[188:191], v[116:119]
	v_mfma_f32_16x16x32_bf16 v[112:115], v[180:183], v[188:191], v[112:115]
	v_mfma_f32_16x16x32_bf16 v[100:103], v[162:165], v[196:199], v[100:103]
	v_mfma_f32_16x16x32_bf16 v[96:99], v[180:183], v[196:199], v[96:99]
	v_mfma_f32_16x16x32_bf16 v[84:87], v[162:165], v[208:211], v[84:87]
	v_mfma_f32_16x16x32_bf16 v[80:83], v[180:183], v[208:211], v[80:83]
	v_mfma_f32_16x16x32_bf16 v[68:71], v[162:165], v[216:219], v[68:71]
	v_mfma_f32_16x16x32_bf16 v[64:67], v[180:183], v[216:219], v[64:67]
	v_mfma_f32_16x16x32_bf16 v[116:119], v[166:169], v[192:195], v[116:119]
	v_mfma_f32_16x16x32_bf16 v[112:115], v[184:187], v[192:195], v[112:115]
	v_mfma_f32_16x16x32_bf16 v[100:103], v[166:169], v[200:203], v[100:103]
	v_mfma_f32_16x16x32_bf16 v[96:99], v[184:187], v[200:203], v[96:99]
	v_mfma_f32_16x16x32_bf16 v[84:87], v[166:169], v[212:215], v[84:87]
	v_mfma_f32_16x16x32_bf16 v[80:83], v[184:187], v[212:215], v[80:83]
	v_mfma_f32_16x16x32_bf16 v[68:71], v[166:169], v[220:223], v[68:71]
	v_mfma_f32_16x16x32_bf16 v[64:67], v[184:187], v[220:223], v[64:67]
	s_setprio 0
	s_barrier
	s_add_i32 s56, s46, s30
	v_lshl_add_u64 v[170:171], s[54:55], 0, v[148:149]
	s_mov_b32 m0, s56
	ds_read_b128 v[188:191], v178 offset:16384
	ds_read_b128 v[192:195], v178 offset:17408
	ds_read_b128 v[196:199], v178 offset:18432
	ds_read_b128 v[200:203], v178 offset:19456
	ds_read_b128 v[208:211], v178 offset:20480
	ds_read_b128 v[212:215], v178 offset:21504
	ds_read_b128 v[216:219], v178 offset:22528
	ds_read_b128 v[220:223], v178 offset:23552
	global_load_lds_dwordx4 v[170:171], off
	s_add_i32 m0, s56, 0x2000
	v_lshl_add_u64 v[204:205], s[54:55], 0, v[144:145]
	s_add_u32 s54, s54, s10
	s_addc_u32 s55, s55, s11
	s_add_i32 s56, s47, s30
	global_load_lds_dwordx4 v[204:205], off
	v_lshl_add_u64 v[224:225], s[54:55], 0, v[148:149]
	s_mov_b32 m0, s56
	v_lshl_add_u64 v[226:227], s[54:55], 0, v[144:145]
	global_load_lds_dwordx4 v[224:225], off
	s_add_i32 m0, s56, 0x2000
	v_lshl_add_u64 v[228:229], s[28:29], 0, v[150:151]
	global_load_lds_dwordx4 v[226:227], off
	s_mov_b32 m0, s35
	v_lshl_add_u64 v[230:231], s[28:29], 0, v[146:147]
	global_load_lds_dwordx4 v[228:229], off
	s_mov_b32 m0, s36
	s_nop 0
	global_load_lds_dwordx4 v[230:231], off
	s_waitcnt vmcnt(8)
	s_waitcnt lgkmcnt(0)
	s_barrier
; #define PG8_STAGE(bufoff, gbase, voff) do { _Pragma("unroll") for (int _i = 0; _i < 2; ++_i) \
;         __builtin_amdgcn_global_load_lds((const unsigned*)((const char*)(gbase) + (voff)[_i]), (PG8_LAS unsigned*)(lds + (bufoff) + ldsw + _i * 8192), 16, 0, 0); } while (0)
; #define PG8_LDA(dst, b, h) do { _Pragma("unroll") for (int m = 0; m < 4; ++m) _Pragma("unroll") for (int k = 0; k < 2; ++k) dst[m][k] = *(const PG8_LAS bf16x8*)(lds + PG8_SA(b, h) + aoff + m * 2048 + k * 1024); } while (0)
; #define PG8_LDB(dst, b, h) do { _Pragma("unroll") for (int n = 0; n < 2; ++n) _Pragma("unroll") for (int k = 0; k < 2; ++k) dst[n][k] = *(const PG8_LAS bf16x8*)(lds + PG8_SB(b, h) + boff + n * 2048 + k * 1024); } while (0)
; #define PG8_MMA(ai, bj, At, Bt) do { __builtin_amdgcn_s_setprio(1); _Pragma("unroll") for (int m = 0; m < 4; ++m) _Pragma("unroll") for (int n = 0; n < 2; ++n) _Pragma("unroll") for (int k = 0; k < 2; ++k) \
;         acc[ai][bj][m][n] = __builtin_amdgcn_mfma_f32_16x16x32_bf16(Bt[n][k], At[m][k], acc[ai][bj][m][n], 0, 0, 0); __builtin_amdgcn_s_setprio(0); } while (0)
; #define PG8_WAIT_V(n) asm volatile("s_waitcnt vmcnt(" #n ")" ::: "memory")
; #define PG8_WAIT_L(n) asm volatile("s_waitcnt lgkmcnt(" #n ")" ::: "memory")
; #define PG8_BAR __builtin_amdgcn_s_barrier()
; #define PG8_SCHED __builtin_amdgcn_sched_barrier(0)
; template <class Epi, class Sched, bool ALIGN_EPI = false, bool SP2 = false>
; __device__ __forceinline__ void gemm_phase(PG8_LAS unsigned char* lds, const Gemm g, const Sched& S, const Epi& E, int tid_in) {
;     ...
;             PG8_WAIT_V(8); PG8_WAIT_L(0); PG8_BAR; PG8_MMA(1, 0, At, B0); PG8_MMA(1, 1, At, B1); PG8_BAR; PG8_SCHED;
;             PG8_LDB(B0, 1, 0); PG8_LDB(B1, 1, 1); PG8_SCHED; PG8_LDA(At, 1, 0); PG8_STAGE(PG8_SA(0, 1), a2 + hstepA, voffA);
;             PG8_WAIT_V(8); PG8_WAIT_L(0); PG8_BAR; PG8_MMA(0, 0, At, B0); PG8_MMA(0, 1, At, B1); PG8_BAR; PG8_SCHED;
	s_setprio 1
	s_waitcnt lgkmcnt(0)
	v_mfma_f32_16x16x32_bf16 v[60:63], v[128:131], v[188:191], v[60:63]
	v_mfma_f32_16x16x32_bf16 v[56:59], v[136:139], v[188:191], v[56:59]
	v_mfma_f32_16x16x32_bf16 v[44:47], v[128:131], v[196:199], v[44:47]
	v_mfma_f32_16x16x32_bf16 v[40:43], v[136:139], v[196:199], v[40:43]
	v_mfma_f32_16x16x32_bf16 v[28:31], v[128:131], v[208:211], v[28:31]
	v_mfma_f32_16x16x32_bf16 v[24:27], v[136:139], v[208:211], v[24:27]
	v_mfma_f32_16x16x32_bf16 v[12:15], v[128:131], v[216:219], v[12:15]
	v_mfma_f32_16x16x32_bf16 v[8:11], v[136:139], v[216:219], v[8:11]
	v_mfma_f32_16x16x32_bf16 v[60:63], v[132:135], v[192:195], v[60:63]
	v_mfma_f32_16x16x32_bf16 v[56:59], v[140:143], v[192:195], v[56:59]
	v_mfma_f32_16x16x32_bf16 v[44:47], v[132:135], v[200:203], v[44:47]
	v_mfma_f32_16x16x32_bf16 v[40:43], v[140:143], v[200:203], v[40:43]
	v_mfma_f32_16x16x32_bf16 v[28:31], v[132:135], v[212:215], v[28:31]
	v_mfma_f32_16x16x32_bf16 v[24:27], v[140:143], v[212:215], v[24:27]
	v_mfma_f32_16x16x32_bf16 v[12:15], v[132:135], v[220:223], v[12:15]
	v_mfma_f32_16x16x32_bf16 v[8:11], v[140:143], v[220:223], v[8:11]
	s_setprio 0
	s_setprio 1
	v_mfma_f32_16x16x32_bf16 v[52:55], v[162:165], v[188:191], v[52:55]
	v_mfma_f32_16x16x32_bf16 v[48:51], v[180:183], v[188:191], v[48:51]
	v_mfma_f32_16x16x32_bf16 v[36:39], v[162:165], v[196:199], v[36:39]
	v_mfma_f32_16x16x32_bf16 v[32:35], v[180:183], v[196:199], v[32:35]
	v_mfma_f32_16x16x32_bf16 v[20:23], v[162:165], v[208:211], v[20:23]
	v_mfma_f32_16x16x32_bf16 v[16:19], v[180:183], v[208:211], v[16:19]
	v_mfma_f32_16x16x32_bf16 v[4:7], v[162:165], v[216:219], v[4:7]
	v_mfma_f32_16x16x32_bf16 v[0:3], v[180:183], v[216:219], v[0:3]
	v_mfma_f32_16x16x32_bf16 v[52:55], v[166:169], v[192:195], v[52:55]
	v_mfma_f32_16x16x32_bf16 v[48:51], v[184:187], v[192:195], v[48:51]
	v_mfma_f32_16x16x32_bf16 v[36:39], v[166:169], v[200:203], v[36:39]
	v_mfma_f32_16x16x32_bf16 v[32:35], v[184:187], v[200:203], v[32:35]
	v_mfma_f32_16x16x32_bf16 v[20:23], v[166:169], v[212:215], v[20:23]
	v_mfma_f32_16x16x32_bf16 v[16:19], v[184:187], v[212:215], v[16:19]
	v_mfma_f32_16x16x32_bf16 v[4:7], v[166:169], v[220:223], v[4:7]
	v_mfma_f32_16x16x32_bf16 v[0:3], v[184:187], v[220:223], v[0:3]
	s_setprio 0
	s_barrier
	s_add_i32 s54, 0, 0x18000
	s_add_i32 s55, 0, 0x1c000
	v_add_u32_e32 v140, s54, v174
	v_add_u32_e32 v184, s55, v174
	ds_read_b128 v[128:131], v140
	ds_read_b128 v[132:135], v140 offset:1024
	ds_read_b128 v[136:139], v140 offset:2048
	ds_read_b128 v[140:143], v140 offset:3072
	ds_read_b128 v[162:165], v184
	ds_read_b128 v[166:169], v184 offset:1024
	ds_read_b128 v[180:183], v184 offset:2048
	ds_read_b128 v[184:187], v184 offset:3072
	s_add_u32 s28, s28, s10
	s_addc_u32 s29, s29, s11
	s_mov_b32 m0, s37
	ds_read_b128 v[188:191], v178 offset:32768
	ds_read_b128 v[192:195], v178 offset:33792
	ds_read_b128 v[196:199], v178 offset:34816
	ds_read_b128 v[200:203], v178 offset:35840
	ds_read_b128 v[208:211], v178 offset:36864
	ds_read_b128 v[212:215], v178 offset:37888
	ds_read_b128 v[216:219], v178 offset:38912
	ds_read_b128 v[220:223], v178 offset:39936
	global_load_lds_dwordx4 v150, s[28:29]
	s_mov_b32 m0, s38
	s_nop 0
	global_load_lds_dwordx4 v146, s[28:29]
	s_waitcnt vmcnt(8)
	s_waitcnt lgkmcnt(0)
	s_barrier
	s_setprio 1
	s_waitcnt lgkmcnt(0)
	v_mfma_f32_16x16x32_bf16 v[120:123], v[128:131], v[188:191], v[120:123]
	v_mfma_f32_16x16x32_bf16 v[124:127], v[136:139], v[188:191], v[124:127]
	v_mfma_f32_16x16x32_bf16 v[108:111], v[128:131], v[196:199], v[108:111]
	v_mfma_f32_16x16x32_bf16 v[104:107], v[136:139], v[196:199], v[104:107]
	v_mfma_f32_16x16x32_bf16 v[92:95], v[128:131], v[208:211], v[92:95]
	v_mfma_f32_16x16x32_bf16 v[88:91], v[136:139], v[208:211], v[88:91]
	v_mfma_f32_16x16x32_bf16 v[76:79], v[128:131], v[216:219], v[76:79]
	v_mfma_f32_16x16x32_bf16 v[72:75], v[136:139], v[216:219], v[72:75]
	v_mfma_f32_16x16x32_bf16 v[120:123], v[132:135], v[192:195], v[120:123]
	v_mfma_f32_16x16x32_bf16 v[124:127], v[140:143], v[192:195], v[124:127]
	v_mfma_f32_16x16x32_bf16 v[108:111], v[132:135], v[200:203], v[108:111]
	v_mfma_f32_16x16x32_bf16 v[104:107], v[140:143], v[200:203], v[104:107]
	v_mfma_f32_16x16x32_bf16 v[92:95], v[132:135], v[212:215], v[92:95]
	v_mfma_f32_16x16x32_bf16 v[88:91], v[140:143], v[212:215], v[88:91]
	v_mfma_f32_16x16x32_bf16 v[76:79], v[132:135], v[220:223], v[76:79]
	v_mfma_f32_16x16x32_bf16 v[72:75], v[140:143], v[220:223], v[72:75]
	s_setprio 0
	s_setprio 1
	v_mfma_f32_16x16x32_bf16 v[116:119], v[162:165], v[188:191], v[116:119]
	v_mfma_f32_16x16x32_bf16 v[112:115], v[180:183], v[188:191], v[112:115]
	v_mfma_f32_16x16x32_bf16 v[100:103], v[162:165], v[196:199], v[100:103]
	v_mfma_f32_16x16x32_bf16 v[96:99], v[180:183], v[196:199], v[96:99]
	v_mfma_f32_16x16x32_bf16 v[84:87], v[162:165], v[208:211], v[84:87]
	v_mfma_f32_16x16x32_bf16 v[80:83], v[180:183], v[208:211], v[80:83]
	v_mfma_f32_16x16x32_bf16 v[68:71], v[162:165], v[216:219], v[68:71]
	v_mfma_f32_16x16x32_bf16 v[64:67], v[180:183], v[216:219], v[64:67]
	v_mfma_f32_16x16x32_bf16 v[116:119], v[166:169], v[192:195], v[116:119]
	v_mfma_f32_16x16x32_bf16 v[112:115], v[184:187], v[192:195], v[112:115]
	v_mfma_f32_16x16x32_bf16 v[100:103], v[166:169], v[200:203], v[100:103]
	v_mfma_f32_16x16x32_bf16 v[96:99], v[184:187], v[200:203], v[96:99]
	v_mfma_f32_16x16x32_bf16 v[84:87], v[166:169], v[212:215], v[84:87]
	v_mfma_f32_16x16x32_bf16 v[80:83], v[184:187], v[212:215], v[80:83]
	v_mfma_f32_16x16x32_bf16 v[68:71], v[166:169], v[220:223], v[68:71]
	v_mfma_f32_16x16x32_bf16 v[64:67], v[184:187], v[220:223], v[64:67]
	s_setprio 0
	s_barrier
; #define PG8_STAGE(bufoff, gbase, voff) do { _Pragma("unroll") for (int _i = 0; _i < 2; ++_i) \
;         __builtin_amdgcn_global_load_lds((const unsigned*)((const char*)(gbase) + (voff)[_i]), (PG8_LAS unsigned*)(lds + (bufoff) + ldsw + _i * 8192), 16, 0, 0); } while (0)
; #define PG8_LDA(dst, b, h) do { _Pragma("unroll") for (int m = 0; m < 4; ++m) _Pragma("unroll") for (int k = 0; k < 2; ++k) dst[m][k] = *(const PG8_LAS bf16x8*)(lds + PG8_SA(b, h) + aoff + m * 2048 + k * 1024); } while (0)
; #define PG8_MMA(ai, bj, At, Bt) do { __builtin_amdgcn_s_setprio(1); _Pragma("unroll") for (int m = 0; m < 4; ++m) _Pragma("unroll") for (int n = 0; n < 2; ++n) _Pragma("unroll") for (int k = 0; k < 2; ++k) \
;         acc[ai][bj][m][n] = __builtin_amdgcn_mfma_f32_16x16x32_bf16(Bt[n][k], At[m][k], acc[ai][bj][m][n], 0, 0, 0); __builtin_amdgcn_s_setprio(0); } while (0)
; #define PG8_WAIT_V(n) asm volatile("s_waitcnt vmcnt(" #n ")" ::: "memory")
; #define PG8_WAIT_L(n) asm volatile("s_waitcnt lgkmcnt(" #n ")" ::: "memory")
; #define PG8_BAR __builtin_amdgcn_s_barrier()
; #define PG8_SCHED __builtin_amdgcn_sched_barrier(0)
; template <class Epi, class Sched, bool ALIGN_EPI = false, bool SP2 = false>
; __device__ __forceinline__ void gemm_phase(PG8_LAS unsigned char* lds, const Gemm g, const Sched& S, const Epi& E, int tid_in) {
;     ...
;             PG8_WAIT_V(8); PG8_WAIT_L(0); PG8_BAR; PG8_MMA(0, 0, At, B0); PG8_MMA(0, 1, At, B1); PG8_BAR; PG8_SCHED;
;             PG8_LDA(At, 1, 1); PG8_STAGE(PG8_SB(1, 0), b3, voffB); PG8_STAGE(PG8_SB(1, 1), b3 + hstepB, voffB); PG8_STAGE(PG8_SA(1, 0), a3, voffA);
;             PG8_WAIT_V(8); PG8_WAIT_L(0); PG8_BAR; PG8_MMA(1, 0, At, B0); PG8_MMA(1, 1, At, B1); PG8_BAR; PG8_SCHED;
	s_add_i32 s28, s54, s30
	v_lshl_add_u64 v[170:171], v[170:171], 0, s[18:19]
	s_mov_b32 m0, s28
	ds_read_b128 v[188:191], v178 offset:49152
	ds_read_b128 v[192:195], v178 offset:50176
	ds_read_b128 v[196:199], v178 offset:51200
	ds_read_b128 v[200:203], v178 offset:52224
	ds_read_b128 v[208:211], v178 offset:53248
	ds_read_b128 v[212:215], v178 offset:54272
	ds_read_b128 v[216:219], v178 offset:55296
	ds_read_b128 v[220:223], v178 offset:56320
	global_load_lds_dwordx4 v[170:171], off
	v_lshl_add_u64 v[170:171], v[204:205], 0, s[18:19]
	s_add_i32 m0, s28, 0x2000
	s_add_i32 s28, s55, s30
	global_load_lds_dwordx4 v[170:171], off
	v_lshl_add_u64 v[170:171], v[224:225], 0, s[18:19]
	s_mov_b32 m0, s28
	s_nop 0
	global_load_lds_dwordx4 v[170:171], off
	v_lshl_add_u64 v[170:171], v[226:227], 0, s[18:19]
	s_add_i32 m0, s28, 0x2000
	s_nop 0
	global_load_lds_dwordx4 v[170:171], off
	v_lshl_add_u64 v[170:171], v[228:229], 0, s[18:19]
	s_mov_b32 m0, s40
	s_nop 0
	global_load_lds_dwordx4 v[170:171], off
	v_lshl_add_u64 v[170:171], v[230:231], 0, s[18:19]
	s_mov_b32 m0, s41
	s_nop 0
	global_load_lds_dwordx4 v[170:171], off
	s_waitcnt vmcnt(8)
	s_waitcnt lgkmcnt(0)
	s_barrier
	s_setprio 1
	s_waitcnt lgkmcnt(0)
	v_mfma_f32_16x16x32_bf16 v[60:63], v[128:131], v[188:191], v[60:63]
	v_mfma_f32_16x16x32_bf16 v[56:59], v[136:139], v[188:191], v[56:59]
	v_mfma_f32_16x16x32_bf16 v[44:47], v[128:131], v[196:199], v[44:47]
	v_mfma_f32_16x16x32_bf16 v[40:43], v[136:139], v[196:199], v[40:43]
	v_mfma_f32_16x16x32_bf16 v[28:31], v[128:131], v[208:211], v[28:31]
	v_mfma_f32_16x16x32_bf16 v[24:27], v[136:139], v[208:211], v[24:27]
	v_mfma_f32_16x16x32_bf16 v[12:15], v[128:131], v[216:219], v[12:15]
	v_mfma_f32_16x16x32_bf16 v[8:11], v[136:139], v[216:219], v[8:11]
	v_mfma_f32_16x16x32_bf16 v[60:63], v[132:135], v[192:195], v[60:63]
	v_mfma_f32_16x16x32_bf16 v[56:59], v[140:143], v[192:195], v[56:59]
	v_mfma_f32_16x16x32_bf16 v[44:47], v[132:135], v[200:203], v[44:47]
	v_mfma_f32_16x16x32_bf16 v[40:43], v[140:143], v[200:203], v[40:43]
	v_mfma_f32_16x16x32_bf16 v[28:31], v[132:135], v[212:215], v[28:31]
	v_mfma_f32_16x16x32_bf16 v[24:27], v[140:143], v[212:215], v[24:27]
	v_mfma_f32_16x16x32_bf16 v[12:15], v[132:135], v[220:223], v[12:15]
	v_mfma_f32_16x16x32_bf16 v[8:11], v[140:143], v[220:223], v[8:11]
	s_setprio 0
	s_setprio 1
	v_mfma_f32_16x16x32_bf16 v[52:55], v[162:165], v[188:191], v[52:55]
	v_mfma_f32_16x16x32_bf16 v[48:51], v[180:183], v[188:191], v[48:51]
	v_mfma_f32_16x16x32_bf16 v[36:39], v[162:165], v[196:199], v[36:39]
	v_mfma_f32_16x16x32_bf16 v[32:35], v[180:183], v[196:199], v[32:35]
	v_mfma_f32_16x16x32_bf16 v[20:23], v[162:165], v[208:211], v[20:23]
	v_mfma_f32_16x16x32_bf16 v[16:19], v[180:183], v[208:211], v[16:19]
	v_mfma_f32_16x16x32_bf16 v[4:7], v[162:165], v[216:219], v[4:7]
	v_mfma_f32_16x16x32_bf16 v[0:3], v[180:183], v[216:219], v[0:3]
	v_mfma_f32_16x16x32_bf16 v[52:55], v[166:169], v[192:195], v[52:55]
	v_mfma_f32_16x16x32_bf16 v[48:51], v[184:187], v[192:195], v[48:51]
	v_mfma_f32_16x16x32_bf16 v[36:39], v[166:169], v[200:203], v[36:39]
	v_mfma_f32_16x16x32_bf16 v[32:35], v[184:187], v[200:203], v[32:35]
	v_mfma_f32_16x16x32_bf16 v[20:23], v[166:169], v[212:215], v[20:23]
	v_mfma_f32_16x16x32_bf16 v[16:19], v[184:187], v[212:215], v[16:19]
	v_mfma_f32_16x16x32_bf16 v[4:7], v[166:169], v[220:223], v[4:7]
	v_mfma_f32_16x16x32_bf16 v[0:3], v[184:187], v[220:223], v[0:3]
	s_setprio 0
	s_barrier
	s_add_u32 s26, s26, 0x100
	s_addc_u32 s27, s27, 0
	s_add_u32 s51, s51, 0x100
	s_addc_u32 s52, s52, 0
	s_cmp_ge_i32 s53, s42
	s_mov_b32 s28, s53
	s_cbranch_scc0 .LBB0_1354

; #define PG8_STAGE(bufoff, gbase, voff) do { _Pragma("unroll") for (int _i = 0; _i < 2; ++_i) \
;         __builtin_amdgcn_global_load_lds((const unsigned*)((const char*)(gbase) + (voff)[_i]), (PG8_LAS unsigned*)(lds + (bufoff) + ldsw + _i * 8192), 16, 0, 0); } while (0)
; #define PG8_LDA(dst, b, h) do { _Pragma("unroll") for (int m = 0; m < 4; ++m) _Pragma("unroll") for (int k = 0; k < 2; ++k) dst[m][k] = *(const PG8_LAS bf16x8*)(lds + PG8_SA(b, h) + aoff + m * 2048 + k * 1024); } while (0)
; #define PG8_LDB(dst, b, h) do { _Pragma("unroll") for (int n = 0; n < 2; ++n) _Pragma("unroll") for (int k = 0; k < 2; ++k) dst[n][k] = *(const PG8_LAS bf16x8*)(lds + PG8_SB(b, h) + boff + n * 2048 + k * 1024); } while (0)
; #define PG8_MMA(ai, bj, At, Bt) do { __builtin_amdgcn_s_setprio(1); _Pragma("unroll") for (int m = 0; m < 4; ++m) _Pragma("unroll") for (int n = 0; n < 2; ++n) _Pragma("unroll") for (int k = 0; k < 2; ++k) \
;         acc[ai][bj][m][n] = __builtin_amdgcn_mfma_f32_16x16x32_bf16(Bt[n][k], At[m][k], acc[ai][bj][m][n], 0, 0, 0); __builtin_amdgcn_s_setprio(0); } while (0)
; #define PG8_WAIT_V(n) asm volatile("s_waitcnt vmcnt(" #n ")" ::: "memory")
; #define PG8_WAIT_L(n) asm volatile("s_waitcnt lgkmcnt(" #n ")" ::: "memory")
; #define PG8_BAR __builtin_amdgcn_s_barrier()
; #define PG8_SCHED __builtin_amdgcn_sched_barrier(0)
; template <class Epi, class Sched, bool ALIGN_EPI = false, bool SP2 = false>
; __device__ __forceinline__ void gemm_phase(PG8_LAS unsigned char* lds, const Gemm g, const Sched& S, const Epi& E, int tid_in) {
;     ...
;             if constexpr (SP2) {
;             PG8_LDB(B0, 0, 0); PG8_LDB(B1, 0, 1); PG8_SCHED; PG8_LDA(At, 0, 0); PG8_STAGE(PG8_SA(1, 1), a1 + hstepA, voffA);
;             PG8_WAIT_V(8); PG8_WAIT_L(0); PG8_BAR; PG8_MMA(0, 0, At, B0); PG8_MMA(0, 1, At, B1); PG8_BAR; PG8_SCHED;
;             PG8_LDA(At, 0, 1); PG8_STAGE(PG8_SB(0, 0), b2, voffB); PG8_STAGE(PG8_SB(0, 1), b2 + hstepB, voffB); PG8_STAGE(PG8_SA(0, 0), a2, voffA);
;             PG8_WAIT_V(8); PG8_WAIT_L(0); PG8_BAR; PG8_MMA(1, 0, At, B0); PG8_MMA(1, 1, At, B1); PG8_BAR; PG8_SCHED;
.LBB0_1447:
	ds_read_b128 v[150:153], v147
	ds_read_b128 v[154:157], v147 offset:1024
	ds_read_b128 v[158:161], v147 offset:2048
	ds_read_b128 v[162:165], v147 offset:3072
	ds_read_b128 v[166:169], v148
	ds_read_b128 v[170:173], v148 offset:1024
	ds_read_b128 v[174:177], v148 offset:2048
	ds_read_b128 v[178:181], v148 offset:3072
	s_add_i32 s55, s30, 2
	s_add_u32 s56, s26, 0x80
	s_addc_u32 s31, s27, 0
	s_cmp_eq_u32 s44, s30
	s_cselect_b32 s30, s10, s56
	s_cselect_b32 s31, s11, s31
	s_cselect_b32 s57, s25, s54
	s_cselect_b32 s56, s24, s53
	s_add_i32 m0, s36, 0xc000
	ds_read_b128 v[182:185], v149
	ds_read_b128 v[186:189], v149 offset:1024
	ds_read_b128 v[190:193], v149 offset:2048
	ds_read_b128 v[194:197], v149 offset:3072
	ds_read_b128 v[198:201], v149 offset:4096
	ds_read_b128 v[202:205], v149 offset:5120
	ds_read_b128 v[208:211], v149 offset:6144
	ds_read_b128 v[212:215], v149 offset:7168
	global_load_lds_dwordx4 v136, s[26:27]
	s_add_i32 m0, s36, 0xe000
	s_nop 0
	global_load_lds_dwordx4 v138, s[26:27]
	s_waitcnt vmcnt(8)
	s_waitcnt lgkmcnt(0)
	s_barrier
	s_setprio 1
	s_waitcnt lgkmcnt(0)
	v_mfma_f32_16x16x32_bf16 v[124:127], v[150:153], v[182:185], v[124:127]
	v_mfma_f32_16x16x32_bf16 v[120:123], v[158:161], v[182:185], v[120:123]
	v_mfma_f32_16x16x32_bf16 v[108:111], v[150:153], v[190:193], v[108:111]
	v_mfma_f32_16x16x32_bf16 v[104:107], v[158:161], v[190:193], v[104:107]
	v_mfma_f32_16x16x32_bf16 v[92:95], v[150:153], v[198:201], v[92:95]
	v_mfma_f32_16x16x32_bf16 v[88:91], v[158:161], v[198:201], v[88:91]
	v_mfma_f32_16x16x32_bf16 v[76:79], v[150:153], v[208:211], v[76:79]
	v_mfma_f32_16x16x32_bf16 v[72:75], v[158:161], v[208:211], v[72:75]
	v_mfma_f32_16x16x32_bf16 v[124:127], v[154:157], v[186:189], v[124:127]
	v_mfma_f32_16x16x32_bf16 v[120:123], v[162:165], v[186:189], v[120:123]
	v_mfma_f32_16x16x32_bf16 v[108:111], v[154:157], v[194:197], v[108:111]
	v_mfma_f32_16x16x32_bf16 v[104:107], v[162:165], v[194:197], v[104:107]
	v_mfma_f32_16x16x32_bf16 v[92:95], v[154:157], v[202:205], v[92:95]
	v_mfma_f32_16x16x32_bf16 v[88:91], v[162:165], v[202:205], v[88:91]
	v_mfma_f32_16x16x32_bf16 v[76:79], v[154:157], v[212:215], v[76:79]
	v_mfma_f32_16x16x32_bf16 v[72:75], v[162:165], v[212:215], v[72:75]
	s_setprio 0
	s_setprio 1
	v_mfma_f32_16x16x32_bf16 v[116:119], v[166:169], v[182:185], v[116:119]
	v_mfma_f32_16x16x32_bf16 v[112:115], v[174:177], v[182:185], v[112:115]
	v_mfma_f32_16x16x32_bf16 v[100:103], v[166:169], v[190:193], v[100:103]
	v_mfma_f32_16x16x32_bf16 v[96:99], v[174:177], v[190:193], v[96:99]
	v_mfma_f32_16x16x32_bf16 v[84:87], v[166:169], v[198:201], v[84:87]
	v_mfma_f32_16x16x32_bf16 v[80:83], v[174:177], v[198:201], v[80:83]
	v_mfma_f32_16x16x32_bf16 v[68:71], v[166:169], v[208:211], v[68:71]
	v_mfma_f32_16x16x32_bf16 v[64:67], v[174:177], v[208:211], v[64:67]
	v_mfma_f32_16x16x32_bf16 v[116:119], v[170:173], v[186:189], v[116:119]
	v_mfma_f32_16x16x32_bf16 v[112:115], v[178:181], v[186:189], v[112:115]
	v_mfma_f32_16x16x32_bf16 v[100:103], v[170:173], v[194:197], v[100:103]
	v_mfma_f32_16x16x32_bf16 v[96:99], v[178:181], v[194:197], v[96:99]
	v_mfma_f32_16x16x32_bf16 v[84:87], v[170:173], v[202:205], v[84:87]
	v_mfma_f32_16x16x32_bf16 v[80:83], v[178:181], v[202:205], v[80:83]
	v_mfma_f32_16x16x32_bf16 v[68:71], v[170:173], v[212:215], v[68:71]
	v_mfma_f32_16x16x32_bf16 v[64:67], v[178:181], v[212:215], v[64:67]
	s_setprio 0
	s_barrier
	s_add_i32 s58, s47, s33
	v_lshl_add_u64 v[216:217], s[56:57], 0, v[132:133]
	s_mov_b32 m0, s58
	ds_read_b128 v[182:185], v149 offset:16384
	ds_read_b128 v[186:189], v149 offset:17408
	ds_read_b128 v[190:193], v149 offset:18432
	ds_read_b128 v[194:197], v149 offset:19456
	ds_read_b128 v[198:201], v149 offset:20480
	ds_read_b128 v[202:205], v149 offset:21504
	ds_read_b128 v[208:211], v149 offset:22528
	ds_read_b128 v[212:215], v149 offset:23552
	global_load_lds_dwordx4 v[216:217], off
	s_add_i32 m0, s58, 0x2000
	v_lshl_add_u64 v[218:219], s[56:57], 0, v[128:129]
	s_add_u32 s56, s56, s14
	s_addc_u32 s57, s57, s15
	s_add_i32 s58, s48, s33
	global_load_lds_dwordx4 v[218:219], off
	v_lshl_add_u64 v[220:221], s[56:57], 0, v[132:133]
	s_mov_b32 m0, s58
	v_lshl_add_u64 v[222:223], s[56:57], 0, v[128:129]
	global_load_lds_dwordx4 v[220:221], off
	s_add_i32 m0, s58, 0x2000
	v_lshl_add_u64 v[224:225], s[30:31], 0, v[134:135]
	global_load_lds_dwordx4 v[222:223], off
	s_mov_b32 m0, s36
	v_lshl_add_u64 v[226:227], s[30:31], 0, v[130:131]
	global_load_lds_dwordx4 v[224:225], off
	s_mov_b32 m0, s37
	s_nop 0
	global_load_lds_dwordx4 v[226:227], off
	s_waitcnt vmcnt(8)
	s_waitcnt lgkmcnt(0)
	s_barrier
; #define PG8_STAGE(bufoff, gbase, voff) do { _Pragma("unroll") for (int _i = 0; _i < 2; ++_i) \
;         __builtin_amdgcn_global_load_lds((const unsigned*)((const char*)(gbase) + (voff)[_i]), (PG8_LAS unsigned*)(lds + (bufoff) + ldsw + _i * 8192), 16, 0, 0); } while (0)
; #define PG8_LDA(dst, b, h) do { _Pragma("unroll") for (int m = 0; m < 4; ++m) _Pragma("unroll") for (int k = 0; k < 2; ++k) dst[m][k] = *(const PG8_LAS bf16x8*)(lds + PG8_SA(b, h) + aoff + m * 2048 + k * 1024); } while (0)
; #define PG8_LDB(dst, b, h) do { _Pragma("unroll") for (int n = 0; n < 2; ++n) _Pragma("unroll") for (int k = 0; k < 2; ++k) dst[n][k] = *(const PG8_LAS bf16x8*)(lds + PG8_SB(b, h) + boff + n * 2048 + k * 1024); } while (0)
; #define PG8_MMA(ai, bj, At, Bt) do { __builtin_amdgcn_s_setprio(1); _Pragma("unroll") for (int m = 0; m < 4; ++m) _Pragma("unroll") for (int n = 0; n < 2; ++n) _Pragma("unroll") for (int k = 0; k < 2; ++k) \
;         acc[ai][bj][m][n] = __builtin_amdgcn_mfma_f32_16x16x32_bf16(Bt[n][k], At[m][k], acc[ai][bj][m][n], 0, 0, 0); __builtin_amdgcn_s_setprio(0); } while (0)
; #define PG8_WAIT_V(n) asm volatile("s_waitcnt vmcnt(" #n ")" ::: "memory")
; #define PG8_WAIT_L(n) asm volatile("s_waitcnt lgkmcnt(" #n ")" ::: "memory")
; #define PG8_BAR __builtin_amdgcn_s_barrier()
; #define PG8_SCHED __builtin_amdgcn_sched_barrier(0)
; template <class Epi, class Sched, bool ALIGN_EPI = false, bool SP2 = false>
; __device__ __forceinline__ void gemm_phase(PG8_LAS unsigned char* lds, const Gemm g, const Sched& S, const Epi& E, int tid_in) {
;     ...
;             PG8_WAIT_V(8); PG8_WAIT_L(0); PG8_BAR; PG8_MMA(1, 0, At, B0); PG8_MMA(1, 1, At, B1); PG8_BAR; PG8_SCHED;
;             PG8_LDB(B0, 1, 0); PG8_LDB(B1, 1, 1); PG8_SCHED; PG8_LDA(At, 1, 0); PG8_STAGE(PG8_SA(0, 1), a2 + hstepA, voffA);
;             PG8_WAIT_V(8); PG8_WAIT_L(0); PG8_BAR; PG8_MMA(0, 0, At, B0); PG8_MMA(0, 1, At, B1); PG8_BAR; PG8_SCHED;
	s_setprio 1
	s_waitcnt lgkmcnt(0)
	v_mfma_f32_16x16x32_bf16 v[60:63], v[150:153], v[182:185], v[60:63]
	v_mfma_f32_16x16x32_bf16 v[56:59], v[158:161], v[182:185], v[56:59]
	v_mfma_f32_16x16x32_bf16 v[44:47], v[150:153], v[190:193], v[44:47]
	v_mfma_f32_16x16x32_bf16 v[40:43], v[158:161], v[190:193], v[40:43]
	v_mfma_f32_16x16x32_bf16 v[28:31], v[150:153], v[198:201], v[28:31]
	v_mfma_f32_16x16x32_bf16 v[24:27], v[158:161], v[198:201], v[24:27]
	v_mfma_f32_16x16x32_bf16 v[12:15], v[150:153], v[208:211], v[12:15]
	v_mfma_f32_16x16x32_bf16 v[8:11], v[158:161], v[208:211], v[8:11]
	v_mfma_f32_16x16x32_bf16 v[60:63], v[154:157], v[186:189], v[60:63]
	v_mfma_f32_16x16x32_bf16 v[56:59], v[162:165], v[186:189], v[56:59]
	v_mfma_f32_16x16x32_bf16 v[44:47], v[154:157], v[194:197], v[44:47]
	v_mfma_f32_16x16x32_bf16 v[40:43], v[162:165], v[194:197], v[40:43]
	v_mfma_f32_16x16x32_bf16 v[28:31], v[154:157], v[202:205], v[28:31]
	v_mfma_f32_16x16x32_bf16 v[24:27], v[162:165], v[202:205], v[24:27]
	v_mfma_f32_16x16x32_bf16 v[12:15], v[154:157], v[212:215], v[12:15]
	v_mfma_f32_16x16x32_bf16 v[8:11], v[162:165], v[212:215], v[8:11]
	s_setprio 0
	s_setprio 1
	v_mfma_f32_16x16x32_bf16 v[52:55], v[166:169], v[182:185], v[52:55]
	v_mfma_f32_16x16x32_bf16 v[48:51], v[174:177], v[182:185], v[48:51]
	v_mfma_f32_16x16x32_bf16 v[36:39], v[166:169], v[190:193], v[36:39]
	v_mfma_f32_16x16x32_bf16 v[32:35], v[174:177], v[190:193], v[32:35]
	v_mfma_f32_16x16x32_bf16 v[20:23], v[166:169], v[198:201], v[20:23]
	v_mfma_f32_16x16x32_bf16 v[16:19], v[174:177], v[198:201], v[16:19]
	v_mfma_f32_16x16x32_bf16 v[4:7], v[166:169], v[208:211], v[4:7]
	v_mfma_f32_16x16x32_bf16 v[0:3], v[174:177], v[208:211], v[0:3]
	v_mfma_f32_16x16x32_bf16 v[52:55], v[170:173], v[186:189], v[52:55]
	v_mfma_f32_16x16x32_bf16 v[48:51], v[178:181], v[186:189], v[48:51]
	v_mfma_f32_16x16x32_bf16 v[36:39], v[170:173], v[194:197], v[36:39]
	v_mfma_f32_16x16x32_bf16 v[32:35], v[178:181], v[194:197], v[32:35]
	v_mfma_f32_16x16x32_bf16 v[20:23], v[170:173], v[202:205], v[20:23]
	v_mfma_f32_16x16x32_bf16 v[16:19], v[178:181], v[202:205], v[16:19]
	v_mfma_f32_16x16x32_bf16 v[4:7], v[170:173], v[212:215], v[4:7]
	v_mfma_f32_16x16x32_bf16 v[0:3], v[178:181], v[212:215], v[0:3]
	s_setprio 0
	s_barrier
	s_add_i32 s56, 0, 0x18000
	s_add_i32 s57, 0, 0x1c000
	v_add_u32_e32 v162, s56, v145
	v_add_u32_e32 v178, s57, v145
	ds_read_b128 v[150:153], v162
	ds_read_b128 v[154:157], v162 offset:1024
	ds_read_b128 v[158:161], v162 offset:2048
	ds_read_b128 v[162:165], v162 offset:3072
	ds_read_b128 v[166:169], v178
	ds_read_b128 v[170:173], v178 offset:1024
	ds_read_b128 v[174:177], v178 offset:2048
	ds_read_b128 v[178:181], v178 offset:3072
	s_add_u32 s30, s30, s14
	s_addc_u32 s31, s31, s15
	s_mov_b32 m0, s38
	ds_read_b128 v[182:185], v149 offset:32768
	ds_read_b128 v[186:189], v149 offset:33792
	ds_read_b128 v[190:193], v149 offset:34816
	ds_read_b128 v[194:197], v149 offset:35840
	ds_read_b128 v[198:201], v149 offset:36864
	ds_read_b128 v[202:205], v149 offset:37888
	ds_read_b128 v[208:211], v149 offset:38912
	ds_read_b128 v[212:215], v149 offset:39936
	global_load_lds_dwordx4 v134, s[30:31]
	s_mov_b32 m0, s39
	s_nop 0
	global_load_lds_dwordx4 v130, s[30:31]
	s_waitcnt vmcnt(8)
	s_waitcnt lgkmcnt(0)
	s_barrier
	s_setprio 1
	s_waitcnt lgkmcnt(0)
	v_mfma_f32_16x16x32_bf16 v[124:127], v[150:153], v[182:185], v[124:127]
	v_mfma_f32_16x16x32_bf16 v[120:123], v[158:161], v[182:185], v[120:123]
	v_mfma_f32_16x16x32_bf16 v[108:111], v[150:153], v[190:193], v[108:111]
	v_mfma_f32_16x16x32_bf16 v[104:107], v[158:161], v[190:193], v[104:107]
	v_mfma_f32_16x16x32_bf16 v[92:95], v[150:153], v[198:201], v[92:95]
	v_mfma_f32_16x16x32_bf16 v[88:91], v[158:161], v[198:201], v[88:91]
	v_mfma_f32_16x16x32_bf16 v[76:79], v[150:153], v[208:211], v[76:79]
	v_mfma_f32_16x16x32_bf16 v[72:75], v[158:161], v[208:211], v[72:75]
	v_mfma_f32_16x16x32_bf16 v[124:127], v[154:157], v[186:189], v[124:127]
	v_mfma_f32_16x16x32_bf16 v[120:123], v[162:165], v[186:189], v[120:123]
	v_mfma_f32_16x16x32_bf16 v[108:111], v[154:157], v[194:197], v[108:111]
	v_mfma_f32_16x16x32_bf16 v[104:107], v[162:165], v[194:197], v[104:107]
	v_mfma_f32_16x16x32_bf16 v[92:95], v[154:157], v[202:205], v[92:95]
	v_mfma_f32_16x16x32_bf16 v[88:91], v[162:165], v[202:205], v[88:91]
	v_mfma_f32_16x16x32_bf16 v[76:79], v[154:157], v[212:215], v[76:79]
	v_mfma_f32_16x16x32_bf16 v[72:75], v[162:165], v[212:215], v[72:75]
	s_setprio 0
	s_setprio 1
	v_mfma_f32_16x16x32_bf16 v[116:119], v[166:169], v[182:185], v[116:119]
	v_mfma_f32_16x16x32_bf16 v[112:115], v[174:177], v[182:185], v[112:115]
	v_mfma_f32_16x16x32_bf16 v[100:103], v[166:169], v[190:193], v[100:103]
	v_mfma_f32_16x16x32_bf16 v[96:99], v[174:177], v[190:193], v[96:99]
	v_mfma_f32_16x16x32_bf16 v[84:87], v[166:169], v[198:201], v[84:87]
	v_mfma_f32_16x16x32_bf16 v[80:83], v[174:177], v[198:201], v[80:83]
	v_mfma_f32_16x16x32_bf16 v[68:71], v[166:169], v[208:211], v[68:71]
	v_mfma_f32_16x16x32_bf16 v[64:67], v[174:177], v[208:211], v[64:67]
	v_mfma_f32_16x16x32_bf16 v[116:119], v[170:173], v[186:189], v[116:119]
	v_mfma_f32_16x16x32_bf16 v[112:115], v[178:181], v[186:189], v[112:115]
	v_mfma_f32_16x16x32_bf16 v[100:103], v[170:173], v[194:197], v[100:103]
	v_mfma_f32_16x16x32_bf16 v[96:99], v[178:181], v[194:197], v[96:99]
	v_mfma_f32_16x16x32_bf16 v[84:87], v[170:173], v[202:205], v[84:87]
	v_mfma_f32_16x16x32_bf16 v[80:83], v[178:181], v[202:205], v[80:83]
	v_mfma_f32_16x16x32_bf16 v[68:71], v[170:173], v[212:215], v[68:71]
	v_mfma_f32_16x16x32_bf16 v[64:67], v[178:181], v[212:215], v[64:67]
	s_setprio 0
	s_barrier
; #define PG8_STAGE(bufoff, gbase, voff) do { _Pragma("unroll") for (int _i = 0; _i < 2; ++_i) \
;         __builtin_amdgcn_global_load_lds((const unsigned*)((const char*)(gbase) + (voff)[_i]), (PG8_LAS unsigned*)(lds + (bufoff) + ldsw + _i * 8192), 16, 0, 0); } while (0)
; #define PG8_LDA(dst, b, h) do { _Pragma("unroll") for (int m = 0; m < 4; ++m) _Pragma("unroll") for (int k = 0; k < 2; ++k) dst[m][k] = *(const PG8_LAS bf16x8*)(lds + PG8_SA(b, h) + aoff + m * 2048 + k * 1024); } while (0)
; #define PG8_MMA(ai, bj, At, Bt) do { __builtin_amdgcn_s_setprio(1); _Pragma("unroll") for (int m = 0; m < 4; ++m) _Pragma("unroll") for (int n = 0; n < 2; ++n) _Pragma("unroll") for (int k = 0; k < 2; ++k) \
;         acc[ai][bj][m][n] = __builtin_amdgcn_mfma_f32_16x16x32_bf16(Bt[n][k], At[m][k], acc[ai][bj][m][n], 0, 0, 0); __builtin_amdgcn_s_setprio(0); } while (0)
; #define PG8_WAIT_V(n) asm volatile("s_waitcnt vmcnt(" #n ")" ::: "memory")
; #define PG8_WAIT_L(n) asm volatile("s_waitcnt lgkmcnt(" #n ")" ::: "memory")
; #define PG8_BAR __builtin_amdgcn_s_barrier()
; #define PG8_SCHED __builtin_amdgcn_sched_barrier(0)
; template <class Epi, class Sched, bool ALIGN_EPI = false, bool SP2 = false>
; __device__ __forceinline__ void gemm_phase(PG8_LAS unsigned char* lds, const Gemm g, const Sched& S, const Epi& E, int tid_in) {
;     ...
;             PG8_WAIT_V(8); PG8_WAIT_L(0); PG8_BAR; PG8_MMA(0, 0, At, B0); PG8_MMA(0, 1, At, B1); PG8_BAR; PG8_SCHED;
;             PG8_LDA(At, 1, 1); PG8_STAGE(PG8_SB(1, 0), b3, voffB); PG8_STAGE(PG8_SB(1, 1), b3 + hstepB, voffB); PG8_STAGE(PG8_SA(1, 0), a3, voffA);
;             PG8_WAIT_V(8); PG8_WAIT_L(0); PG8_BAR; PG8_MMA(1, 0, At, B0); PG8_MMA(1, 1, At, B1); PG8_BAR; PG8_SCHED;
	s_add_i32 s30, s56, s33
	v_lshl_add_u64 v[216:217], v[216:217], 0, s[20:21]
	s_mov_b32 m0, s30
	ds_read_b128 v[182:185], v149 offset:49152
	ds_read_b128 v[186:189], v149 offset:50176
	ds_read_b128 v[190:193], v149 offset:51200
	ds_read_b128 v[194:197], v149 offset:52224
	ds_read_b128 v[198:201], v149 offset:53248
	ds_read_b128 v[202:205], v149 offset:54272
	ds_read_b128 v[208:211], v149 offset:55296
	ds_read_b128 v[212:215], v149 offset:56320
	global_load_lds_dwordx4 v[216:217], off
	v_lshl_add_u64 v[216:217], v[218:219], 0, s[20:21]
	s_add_i32 m0, s30, 0x2000
	s_add_i32 s30, s57, s33
	global_load_lds_dwordx4 v[216:217], off
	v_lshl_add_u64 v[216:217], v[220:221], 0, s[20:21]
	s_mov_b32 m0, s30
	s_nop 0
	global_load_lds_dwordx4 v[216:217], off
	v_lshl_add_u64 v[216:217], v[222:223], 0, s[20:21]
	s_add_i32 m0, s30, 0x2000
	s_nop 0
	global_load_lds_dwordx4 v[216:217], off
	v_lshl_add_u64 v[216:217], v[224:225], 0, s[20:21]
	s_mov_b32 m0, s41
	s_nop 0
	global_load_lds_dwordx4 v[216:217], off
	v_lshl_add_u64 v[216:217], v[226:227], 0, s[20:21]
	s_mov_b32 m0, s42
	s_nop 0
	global_load_lds_dwordx4 v[216:217], off
	s_waitcnt vmcnt(8)
	s_waitcnt lgkmcnt(0)
	s_barrier
	s_setprio 1
	s_waitcnt lgkmcnt(0)
	v_mfma_f32_16x16x32_bf16 v[60:63], v[150:153], v[182:185], v[60:63]
	v_mfma_f32_16x16x32_bf16 v[56:59], v[158:161], v[182:185], v[56:59]
	v_mfma_f32_16x16x32_bf16 v[44:47], v[150:153], v[190:193], v[44:47]
	v_mfma_f32_16x16x32_bf16 v[40:43], v[158:161], v[190:193], v[40:43]
	v_mfma_f32_16x16x32_bf16 v[28:31], v[150:153], v[198:201], v[28:31]
	v_mfma_f32_16x16x32_bf16 v[24:27], v[158:161], v[198:201], v[24:27]
	v_mfma_f32_16x16x32_bf16 v[12:15], v[150:153], v[208:211], v[12:15]
	v_mfma_f32_16x16x32_bf16 v[8:11], v[158:161], v[208:211], v[8:11]
	v_mfma_f32_16x16x32_bf16 v[60:63], v[154:157], v[186:189], v[60:63]
	v_mfma_f32_16x16x32_bf16 v[56:59], v[162:165], v[186:189], v[56:59]
	v_mfma_f32_16x16x32_bf16 v[44:47], v[154:157], v[194:197], v[44:47]
	v_mfma_f32_16x16x32_bf16 v[40:43], v[162:165], v[194:197], v[40:43]
	v_mfma_f32_16x16x32_bf16 v[28:31], v[154:157], v[202:205], v[28:31]
	v_mfma_f32_16x16x32_bf16 v[24:27], v[162:165], v[202:205], v[24:27]
	v_mfma_f32_16x16x32_bf16 v[12:15], v[154:157], v[212:215], v[12:15]
	v_mfma_f32_16x16x32_bf16 v[8:11], v[162:165], v[212:215], v[8:11]
	s_setprio 0
	s_setprio 1
	v_mfma_f32_16x16x32_bf16 v[52:55], v[166:169], v[182:185], v[52:55]
	v_mfma_f32_16x16x32_bf16 v[48:51], v[174:177], v[182:185], v[48:51]
	v_mfma_f32_16x16x32_bf16 v[36:39], v[166:169], v[190:193], v[36:39]
	v_mfma_f32_16x16x32_bf16 v[32:35], v[174:177], v[190:193], v[32:35]
	v_mfma_f32_16x16x32_bf16 v[20:23], v[166:169], v[198:201], v[20:23]
	v_mfma_f32_16x16x32_bf16 v[16:19], v[174:177], v[198:201], v[16:19]
	v_mfma_f32_16x16x32_bf16 v[4:7], v[166:169], v[208:211], v[4:7]
	v_mfma_f32_16x16x32_bf16 v[0:3], v[174:177], v[208:211], v[0:3]
	v_mfma_f32_16x16x32_bf16 v[52:55], v[170:173], v[186:189], v[52:55]
	v_mfma_f32_16x16x32_bf16 v[48:51], v[178:181], v[186:189], v[48:51]
	v_mfma_f32_16x16x32_bf16 v[36:39], v[170:173], v[194:197], v[36:39]
	v_mfma_f32_16x16x32_bf16 v[32:35], v[178:181], v[194:197], v[32:35]
	v_mfma_f32_16x16x32_bf16 v[20:23], v[170:173], v[202:205], v[20:23]
	v_mfma_f32_16x16x32_bf16 v[16:19], v[178:181], v[202:205], v[16:19]
	v_mfma_f32_16x16x32_bf16 v[4:7], v[170:173], v[212:215], v[4:7]
	v_mfma_f32_16x16x32_bf16 v[0:3], v[178:181], v[212:215], v[0:3]
	s_setprio 0
	s_barrier
	s_add_u32 s26, s26, 0x100
	s_addc_u32 s27, s27, 0
	s_add_u32 s53, s53, 0x100
	s_addc_u32 s54, s54, 0
	s_cmp_ge_i32 s55, s43
	s_mov_b32 s30, s55
	s_cbranch_scc0 .LBB0_1447

; #define PG8_STAGE(bufoff, gbase, voff) do { _Pragma("unroll") for (int _i = 0; _i < 2; ++_i) \
;         __builtin_amdgcn_global_load_lds((const unsigned*)((const char*)(gbase) + (voff)[_i]), (PG8_LAS unsigned*)(lds + (bufoff) + ldsw + _i * 8192), 16, 0, 0); } while (0)
; #define PG8_LDA(dst, b, h) do { _Pragma("unroll") for (int m = 0; m < 4; ++m) _Pragma("unroll") for (int k = 0; k < 2; ++k) dst[m][k] = *(const PG8_LAS bf16x8*)(lds + PG8_SA(b, h) + aoff + m * 2048 + k * 1024); } while (0)
; #define PG8_LDB(dst, b, h) do { _Pragma("unroll") for (int n = 0; n < 2; ++n) _Pragma("unroll") for (int k = 0; k < 2; ++k) dst[n][k] = *(const PG8_LAS bf16x8*)(lds + PG8_SB(b, h) + boff + n * 2048 + k * 1024); } while (0)
; #define PG8_MMA(ai, bj, At, Bt) do { __builtin_amdgcn_s_setprio(1); _Pragma("unroll") for (int m = 0; m < 4; ++m) _Pragma("unroll") for (int n = 0; n < 2; ++n) _Pragma("unroll") for (int k = 0; k < 2; ++k) \
;         acc[ai][bj][m][n] = __builtin_amdgcn_mfma_f32_16x16x32_bf16(Bt[n][k], At[m][k], acc[ai][bj][m][n], 0, 0, 0); __builtin_amdgcn_s_setprio(0); } while (0)
; #define PG8_WAIT_V(n) asm volatile("s_waitcnt vmcnt(" #n ")" ::: "memory")
; #define PG8_WAIT_L(n) asm volatile("s_waitcnt lgkmcnt(" #n ")" ::: "memory")
; #define PG8_BAR __builtin_amdgcn_s_barrier()
; #define PG8_SCHED __builtin_amdgcn_sched_barrier(0)
; template <class Epi, class Sched, bool ALIGN_EPI = false, bool SP2 = false>
; __device__ __forceinline__ void gemm_phase(PG8_LAS unsigned char* lds, const Gemm g, const Sched& S, const Epi& E, int tid_in) {
;     ...
;             if constexpr (SP2) {
;             PG8_LDB(B0, 0, 0); PG8_LDB(B1, 0, 1); PG8_SCHED; PG8_LDA(At, 0, 0); PG8_STAGE(PG8_SA(1, 1), a1 + hstepA, voffA);
;             PG8_WAIT_V(8); PG8_WAIT_L(0); PG8_BAR; PG8_MMA(0, 0, At, B0); PG8_MMA(0, 1, At, B1); PG8_BAR; PG8_SCHED;
;             PG8_LDA(At, 0, 1); PG8_STAGE(PG8_SB(0, 0), b2, voffB); PG8_STAGE(PG8_SB(0, 1), b2 + hstepB, voffB); PG8_STAGE(PG8_SA(0, 0), a2, voffA);
;             PG8_WAIT_V(8); PG8_WAIT_L(0); PG8_BAR; PG8_MMA(1, 0, At, B0); PG8_MMA(1, 1, At, B1); PG8_BAR; PG8_SCHED;
.LBB0_1468:
	ds_read_b128 v[128:131], v186
	ds_read_b128 v[132:135], v186 offset:1024
	ds_read_b128 v[136:139], v186 offset:2048
	ds_read_b128 v[140:143], v186 offset:3072
	ds_read_b128 v[162:165], v187
	ds_read_b128 v[166:169], v187 offset:1024
	ds_read_b128 v[170:173], v187 offset:2048
	ds_read_b128 v[174:177], v187 offset:3072
	s_add_i32 s55, s34, 2
	s_add_u32 s56, s30, 0x80
	s_addc_u32 s35, s31, 0
	s_cmp_eq_u32 s47, s34
	s_cselect_b32 s34, s6, s56
	s_cselect_b32 s35, s7, s35
	s_cselect_b32 s57, s29, s54
	s_cselect_b32 s56, s28, s33
	s_add_i32 m0, s39, 0xc000
	ds_read_b128 v[178:181], v188
	ds_read_b128 v[192:195], v188 offset:1024
	ds_read_b128 v[196:199], v188 offset:2048
	ds_read_b128 v[200:203], v188 offset:3072
	ds_read_b128 v[204:207], v188 offset:4096
	ds_read_b128 v[208:211], v188 offset:5120
	ds_read_b128 v[212:215], v188 offset:6144
	ds_read_b128 v[216:219], v188 offset:7168
	global_load_lds_dwordx4 v154, s[30:31]
	s_add_i32 m0, s39, 0xe000
	s_nop 0
	global_load_lds_dwordx4 v156, s[30:31]
	s_waitcnt vmcnt(8)
	s_waitcnt lgkmcnt(0)
	s_barrier
	s_setprio 1
	s_waitcnt lgkmcnt(0)
	v_mfma_f32_16x16x32_bf16 v[124:127], v[128:131], v[178:181], v[124:127]
	v_mfma_f32_16x16x32_bf16 v[120:123], v[136:139], v[178:181], v[120:123]
	v_mfma_f32_16x16x32_bf16 v[108:111], v[128:131], v[196:199], v[108:111]
	v_mfma_f32_16x16x32_bf16 v[104:107], v[136:139], v[196:199], v[104:107]
	v_mfma_f32_16x16x32_bf16 v[92:95], v[128:131], v[204:207], v[92:95]
	v_mfma_f32_16x16x32_bf16 v[88:91], v[136:139], v[204:207], v[88:91]
	v_mfma_f32_16x16x32_bf16 v[76:79], v[128:131], v[212:215], v[76:79]
	v_mfma_f32_16x16x32_bf16 v[72:75], v[136:139], v[212:215], v[72:75]
	v_mfma_f32_16x16x32_bf16 v[124:127], v[132:135], v[192:195], v[124:127]
	v_mfma_f32_16x16x32_bf16 v[120:123], v[140:143], v[192:195], v[120:123]
	v_mfma_f32_16x16x32_bf16 v[108:111], v[132:135], v[200:203], v[108:111]
	v_mfma_f32_16x16x32_bf16 v[104:107], v[140:143], v[200:203], v[104:107]
	v_mfma_f32_16x16x32_bf16 v[92:95], v[132:135], v[208:211], v[92:95]
	v_mfma_f32_16x16x32_bf16 v[88:91], v[140:143], v[208:211], v[88:91]
	v_mfma_f32_16x16x32_bf16 v[76:79], v[132:135], v[216:219], v[76:79]
	v_mfma_f32_16x16x32_bf16 v[72:75], v[140:143], v[216:219], v[72:75]
	s_setprio 0
	s_setprio 1
	v_mfma_f32_16x16x32_bf16 v[116:119], v[162:165], v[178:181], v[116:119]
	v_mfma_f32_16x16x32_bf16 v[112:115], v[170:173], v[178:181], v[112:115]
	v_mfma_f32_16x16x32_bf16 v[100:103], v[162:165], v[196:199], v[100:103]
	v_mfma_f32_16x16x32_bf16 v[96:99], v[170:173], v[196:199], v[96:99]
	v_mfma_f32_16x16x32_bf16 v[84:87], v[162:165], v[204:207], v[84:87]
	v_mfma_f32_16x16x32_bf16 v[80:83], v[170:173], v[204:207], v[80:83]
	v_mfma_f32_16x16x32_bf16 v[68:71], v[162:165], v[212:215], v[68:71]
	v_mfma_f32_16x16x32_bf16 v[64:67], v[170:173], v[212:215], v[64:67]
	v_mfma_f32_16x16x32_bf16 v[116:119], v[166:169], v[192:195], v[116:119]
	v_mfma_f32_16x16x32_bf16 v[112:115], v[174:177], v[192:195], v[112:115]
	v_mfma_f32_16x16x32_bf16 v[100:103], v[166:169], v[200:203], v[100:103]
	v_mfma_f32_16x16x32_bf16 v[96:99], v[174:177], v[200:203], v[96:99]
	v_mfma_f32_16x16x32_bf16 v[84:87], v[166:169], v[208:211], v[84:87]
	v_mfma_f32_16x16x32_bf16 v[80:83], v[174:177], v[208:211], v[80:83]
	v_mfma_f32_16x16x32_bf16 v[68:71], v[166:169], v[216:219], v[68:71]
	v_mfma_f32_16x16x32_bf16 v[64:67], v[174:177], v[216:219], v[64:67]
	s_setprio 0
	s_barrier
	s_add_i32 s58, s50, s36
	v_lshl_add_u64 v[220:221], s[56:57], 0, v[148:149]
	s_mov_b32 m0, s58
	ds_read_b128 v[178:181], v188 offset:16384
	ds_read_b128 v[192:195], v188 offset:17408
	ds_read_b128 v[196:199], v188 offset:18432
	ds_read_b128 v[200:203], v188 offset:19456
	ds_read_b128 v[204:207], v188 offset:20480
	ds_read_b128 v[208:211], v188 offset:21504
	ds_read_b128 v[212:215], v188 offset:22528
	ds_read_b128 v[216:219], v188 offset:23552
	global_load_lds_dwordx4 v[220:221], off
	s_add_i32 m0, s58, 0x2000
	v_lshl_add_u64 v[222:223], s[56:57], 0, v[144:145]
	s_add_u32 s56, s56, s10
	s_addc_u32 s57, s57, s11
	s_add_i32 s58, s51, s36
	global_load_lds_dwordx4 v[222:223], off
	v_lshl_add_u64 v[224:225], s[56:57], 0, v[148:149]
	s_mov_b32 m0, s58
	v_lshl_add_u64 v[226:227], s[56:57], 0, v[144:145]
	global_load_lds_dwordx4 v[224:225], off
	s_add_i32 m0, s58, 0x2000
	v_lshl_add_u64 v[228:229], s[34:35], 0, v[150:151]
	global_load_lds_dwordx4 v[226:227], off
	s_mov_b32 m0, s39
	v_lshl_add_u64 v[230:231], s[34:35], 0, v[146:147]
	global_load_lds_dwordx4 v[228:229], off
	s_mov_b32 m0, s40
	s_nop 0
	global_load_lds_dwordx4 v[230:231], off
	s_waitcnt vmcnt(8)
	s_waitcnt lgkmcnt(0)
	s_barrier
; #define PG8_STAGE(bufoff, gbase, voff) do { _Pragma("unroll") for (int _i = 0; _i < 2; ++_i) \
;         __builtin_amdgcn_global_load_lds((const unsigned*)((const char*)(gbase) + (voff)[_i]), (PG8_LAS unsigned*)(lds + (bufoff) + ldsw + _i * 8192), 16, 0, 0); } while (0)
; #define PG8_LDA(dst, b, h) do { _Pragma("unroll") for (int m = 0; m < 4; ++m) _Pragma("unroll") for (int k = 0; k < 2; ++k) dst[m][k] = *(const PG8_LAS bf16x8*)(lds + PG8_SA(b, h) + aoff + m * 2048 + k * 1024); } while (0)
; #define PG8_LDB(dst, b, h) do { _Pragma("unroll") for (int n = 0; n < 2; ++n) _Pragma("unroll") for (int k = 0; k < 2; ++k) dst[n][k] = *(const PG8_LAS bf16x8*)(lds + PG8_SB(b, h) + boff + n * 2048 + k * 1024); } while (0)
; #define PG8_MMA(ai, bj, At, Bt) do { __builtin_amdgcn_s_setprio(1); _Pragma("unroll") for (int m = 0; m < 4; ++m) _Pragma("unroll") for (int n = 0; n < 2; ++n) _Pragma("unroll") for (int k = 0; k < 2; ++k) \
;         acc[ai][bj][m][n] = __builtin_amdgcn_mfma_f32_16x16x32_bf16(Bt[n][k], At[m][k], acc[ai][bj][m][n], 0, 0, 0); __builtin_amdgcn_s_setprio(0); } while (0)
; #define PG8_WAIT_V(n) asm volatile("s_waitcnt vmcnt(" #n ")" ::: "memory")
; #define PG8_WAIT_L(n) asm volatile("s_waitcnt lgkmcnt(" #n ")" ::: "memory")
; #define PG8_BAR __builtin_amdgcn_s_barrier()
; #define PG8_SCHED __builtin_amdgcn_sched_barrier(0)
; template <class Epi, class Sched, bool ALIGN_EPI = false, bool SP2 = false>
; __device__ __forceinline__ void gemm_phase(PG8_LAS unsigned char* lds, const Gemm g, const Sched& S, const Epi& E, int tid_in) {
;     ...
;             PG8_WAIT_V(8); PG8_WAIT_L(0); PG8_BAR; PG8_MMA(1, 0, At, B0); PG8_MMA(1, 1, At, B1); PG8_BAR; PG8_SCHED;
;             PG8_LDB(B0, 1, 0); PG8_LDB(B1, 1, 1); PG8_SCHED; PG8_LDA(At, 1, 0); PG8_STAGE(PG8_SA(0, 1), a2 + hstepA, voffA);
;             PG8_WAIT_V(8); PG8_WAIT_L(0); PG8_BAR; PG8_MMA(0, 0, At, B0); PG8_MMA(0, 1, At, B1); PG8_BAR; PG8_SCHED;
	s_setprio 1
	s_waitcnt lgkmcnt(0)
	v_mfma_f32_16x16x32_bf16 v[60:63], v[128:131], v[178:181], v[60:63]
	v_mfma_f32_16x16x32_bf16 v[56:59], v[136:139], v[178:181], v[56:59]
	v_mfma_f32_16x16x32_bf16 v[44:47], v[128:131], v[196:199], v[44:47]
	v_mfma_f32_16x16x32_bf16 v[40:43], v[136:139], v[196:199], v[40:43]
	v_mfma_f32_16x16x32_bf16 v[28:31], v[128:131], v[204:207], v[28:31]
	v_mfma_f32_16x16x32_bf16 v[24:27], v[136:139], v[204:207], v[24:27]
	v_mfma_f32_16x16x32_bf16 v[12:15], v[128:131], v[212:215], v[12:15]
	v_mfma_f32_16x16x32_bf16 v[8:11], v[136:139], v[212:215], v[8:11]
	v_mfma_f32_16x16x32_bf16 v[60:63], v[132:135], v[192:195], v[60:63]
	v_mfma_f32_16x16x32_bf16 v[56:59], v[140:143], v[192:195], v[56:59]
	v_mfma_f32_16x16x32_bf16 v[44:47], v[132:135], v[200:203], v[44:47]
	v_mfma_f32_16x16x32_bf16 v[40:43], v[140:143], v[200:203], v[40:43]
	v_mfma_f32_16x16x32_bf16 v[28:31], v[132:135], v[208:211], v[28:31]
	v_mfma_f32_16x16x32_bf16 v[24:27], v[140:143], v[208:211], v[24:27]
	v_mfma_f32_16x16x32_bf16 v[12:15], v[132:135], v[216:219], v[12:15]
	v_mfma_f32_16x16x32_bf16 v[8:11], v[140:143], v[216:219], v[8:11]
	s_setprio 0
	s_setprio 1
	v_mfma_f32_16x16x32_bf16 v[52:55], v[162:165], v[178:181], v[52:55]
	v_mfma_f32_16x16x32_bf16 v[48:51], v[170:173], v[178:181], v[48:51]
	v_mfma_f32_16x16x32_bf16 v[36:39], v[162:165], v[196:199], v[36:39]
	v_mfma_f32_16x16x32_bf16 v[32:35], v[170:173], v[196:199], v[32:35]
	v_mfma_f32_16x16x32_bf16 v[20:23], v[162:165], v[204:207], v[20:23]
	v_mfma_f32_16x16x32_bf16 v[16:19], v[170:173], v[204:207], v[16:19]
	v_mfma_f32_16x16x32_bf16 v[4:7], v[162:165], v[212:215], v[4:7]
	v_mfma_f32_16x16x32_bf16 v[0:3], v[170:173], v[212:215], v[0:3]
	v_mfma_f32_16x16x32_bf16 v[52:55], v[166:169], v[192:195], v[52:55]
	v_mfma_f32_16x16x32_bf16 v[48:51], v[174:177], v[192:195], v[48:51]
	v_mfma_f32_16x16x32_bf16 v[36:39], v[166:169], v[200:203], v[36:39]
	v_mfma_f32_16x16x32_bf16 v[32:35], v[174:177], v[200:203], v[32:35]
	v_mfma_f32_16x16x32_bf16 v[20:23], v[166:169], v[208:211], v[20:23]
	v_mfma_f32_16x16x32_bf16 v[16:19], v[174:177], v[208:211], v[16:19]
	v_mfma_f32_16x16x32_bf16 v[4:7], v[166:169], v[216:219], v[4:7]
	v_mfma_f32_16x16x32_bf16 v[0:3], v[174:177], v[216:219], v[0:3]
	s_setprio 0
	s_barrier
	s_add_i32 s56, 0, 0x18000
	s_add_i32 s57, 0, 0x1c000
	v_add_u32_e32 v140, s56, v184
	v_add_u32_e32 v174, s57, v184
	ds_read_b128 v[128:131], v140
	ds_read_b128 v[132:135], v140 offset:1024
	ds_read_b128 v[136:139], v140 offset:2048
	ds_read_b128 v[140:143], v140 offset:3072
	ds_read_b128 v[162:165], v174
	ds_read_b128 v[166:169], v174 offset:1024
	ds_read_b128 v[170:173], v174 offset:2048
	ds_read_b128 v[174:177], v174 offset:3072
	s_add_u32 s34, s34, s10
	s_addc_u32 s35, s35, s11
	s_mov_b32 m0, s41
	ds_read_b128 v[178:181], v188 offset:32768
	ds_read_b128 v[192:195], v188 offset:33792
	ds_read_b128 v[196:199], v188 offset:34816
	ds_read_b128 v[200:203], v188 offset:35840
	ds_read_b128 v[204:207], v188 offset:36864
	ds_read_b128 v[208:211], v188 offset:37888
	ds_read_b128 v[212:215], v188 offset:38912
	ds_read_b128 v[216:219], v188 offset:39936
	global_load_lds_dwordx4 v150, s[34:35]
	s_mov_b32 m0, s42
	s_nop 0
	global_load_lds_dwordx4 v146, s[34:35]
	s_waitcnt vmcnt(8)
	s_waitcnt lgkmcnt(0)
	s_barrier
	s_setprio 1
	s_waitcnt lgkmcnt(0)
	v_mfma_f32_16x16x32_bf16 v[124:127], v[128:131], v[178:181], v[124:127]
	v_mfma_f32_16x16x32_bf16 v[120:123], v[136:139], v[178:181], v[120:123]
	v_mfma_f32_16x16x32_bf16 v[108:111], v[128:131], v[196:199], v[108:111]
	v_mfma_f32_16x16x32_bf16 v[104:107], v[136:139], v[196:199], v[104:107]
	v_mfma_f32_16x16x32_bf16 v[92:95], v[128:131], v[204:207], v[92:95]
	v_mfma_f32_16x16x32_bf16 v[88:91], v[136:139], v[204:207], v[88:91]
	v_mfma_f32_16x16x32_bf16 v[76:79], v[128:131], v[212:215], v[76:79]
	v_mfma_f32_16x16x32_bf16 v[72:75], v[136:139], v[212:215], v[72:75]
	v_mfma_f32_16x16x32_bf16 v[124:127], v[132:135], v[192:195], v[124:127]
	v_mfma_f32_16x16x32_bf16 v[120:123], v[140:143], v[192:195], v[120:123]
	v_mfma_f32_16x16x32_bf16 v[108:111], v[132:135], v[200:203], v[108:111]
	v_mfma_f32_16x16x32_bf16 v[104:107], v[140:143], v[200:203], v[104:107]
	v_mfma_f32_16x16x32_bf16 v[92:95], v[132:135], v[208:211], v[92:95]
	v_mfma_f32_16x16x32_bf16 v[88:91], v[140:143], v[208:211], v[88:91]
	v_mfma_f32_16x16x32_bf16 v[76:79], v[132:135], v[216:219], v[76:79]
	v_mfma_f32_16x16x32_bf16 v[72:75], v[140:143], v[216:219], v[72:75]
	s_setprio 0
	s_setprio 1
	v_mfma_f32_16x16x32_bf16 v[116:119], v[162:165], v[178:181], v[116:119]
	v_mfma_f32_16x16x32_bf16 v[112:115], v[170:173], v[178:181], v[112:115]
	v_mfma_f32_16x16x32_bf16 v[100:103], v[162:165], v[196:199], v[100:103]
	v_mfma_f32_16x16x32_bf16 v[96:99], v[170:173], v[196:199], v[96:99]
	v_mfma_f32_16x16x32_bf16 v[84:87], v[162:165], v[204:207], v[84:87]
	v_mfma_f32_16x16x32_bf16 v[80:83], v[170:173], v[204:207], v[80:83]
	v_mfma_f32_16x16x32_bf16 v[68:71], v[162:165], v[212:215], v[68:71]
	v_mfma_f32_16x16x32_bf16 v[64:67], v[170:173], v[212:215], v[64:67]
	v_mfma_f32_16x16x32_bf16 v[116:119], v[166:169], v[192:195], v[116:119]
	v_mfma_f32_16x16x32_bf16 v[112:115], v[174:177], v[192:195], v[112:115]
	v_mfma_f32_16x16x32_bf16 v[100:103], v[166:169], v[200:203], v[100:103]
	v_mfma_f32_16x16x32_bf16 v[96:99], v[174:177], v[200:203], v[96:99]
	v_mfma_f32_16x16x32_bf16 v[84:87], v[166:169], v[208:211], v[84:87]
	v_mfma_f32_16x16x32_bf16 v[80:83], v[174:177], v[208:211], v[80:83]
	v_mfma_f32_16x16x32_bf16 v[68:71], v[166:169], v[216:219], v[68:71]
	v_mfma_f32_16x16x32_bf16 v[64:67], v[174:177], v[216:219], v[64:67]
	s_setprio 0
	s_barrier
; #define PG8_STAGE(bufoff, gbase, voff) do { _Pragma("unroll") for (int _i = 0; _i < 2; ++_i) \
;         __builtin_amdgcn_global_load_lds((const unsigned*)((const char*)(gbase) + (voff)[_i]), (PG8_LAS unsigned*)(lds + (bufoff) + ldsw + _i * 8192), 16, 0, 0); } while (0)
; #define PG8_LDA(dst, b, h) do { _Pragma("unroll") for (int m = 0; m < 4; ++m) _Pragma("unroll") for (int k = 0; k < 2; ++k) dst[m][k] = *(const PG8_LAS bf16x8*)(lds + PG8_SA(b, h) + aoff + m * 2048 + k * 1024); } while (0)
; #define PG8_MMA(ai, bj, At, Bt) do { __builtin_amdgcn_s_setprio(1); _Pragma("unroll") for (int m = 0; m < 4; ++m) _Pragma("unroll") for (int n = 0; n < 2; ++n) _Pragma("unroll") for (int k = 0; k < 2; ++k) \
;         acc[ai][bj][m][n] = __builtin_amdgcn_mfma_f32_16x16x32_bf16(Bt[n][k], At[m][k], acc[ai][bj][m][n], 0, 0, 0); __builtin_amdgcn_s_setprio(0); } while (0)
; #define PG8_WAIT_V(n) asm volatile("s_waitcnt vmcnt(" #n ")" ::: "memory")
; #define PG8_WAIT_L(n) asm volatile("s_waitcnt lgkmcnt(" #n ")" ::: "memory")
; #define PG8_BAR __builtin_amdgcn_s_barrier()
; #define PG8_SCHED __builtin_amdgcn_sched_barrier(0)
; template <class Epi, class Sched, bool ALIGN_EPI = false, bool SP2 = false>
; __device__ __forceinline__ void gemm_phase(PG8_LAS unsigned char* lds, const Gemm g, const Sched& S, const Epi& E, int tid_in) {
;     ...
;             PG8_WAIT_V(8); PG8_WAIT_L(0); PG8_BAR; PG8_MMA(0, 0, At, B0); PG8_MMA(0, 1, At, B1); PG8_BAR; PG8_SCHED;
;             PG8_LDA(At, 1, 1); PG8_STAGE(PG8_SB(1, 0), b3, voffB); PG8_STAGE(PG8_SB(1, 1), b3 + hstepB, voffB); PG8_STAGE(PG8_SA(1, 0), a3, voffA);
;             PG8_WAIT_V(8); PG8_WAIT_L(0); PG8_BAR; PG8_MMA(1, 0, At, B0); PG8_MMA(1, 1, At, B1); PG8_BAR; PG8_SCHED;
	s_add_i32 s34, s56, s36
	v_lshl_add_u64 v[220:221], v[220:221], 0, s[22:23]
	s_mov_b32 m0, s34
	ds_read_b128 v[178:181], v188 offset:49152
	ds_read_b128 v[192:195], v188 offset:50176
	ds_read_b128 v[196:199], v188 offset:51200
	ds_read_b128 v[200:203], v188 offset:52224
	ds_read_b128 v[204:207], v188 offset:53248
	ds_read_b128 v[208:211], v188 offset:54272
	ds_read_b128 v[212:215], v188 offset:55296
	ds_read_b128 v[216:219], v188 offset:56320
	global_load_lds_dwordx4 v[220:221], off
	v_lshl_add_u64 v[220:221], v[222:223], 0, s[22:23]
	s_add_i32 m0, s34, 0x2000
	s_add_i32 s34, s57, s36
	global_load_lds_dwordx4 v[220:221], off
	v_lshl_add_u64 v[220:221], v[224:225], 0, s[22:23]
	s_mov_b32 m0, s34
	s_nop 0
	global_load_lds_dwordx4 v[220:221], off
	v_lshl_add_u64 v[220:221], v[226:227], 0, s[22:23]
	s_add_i32 m0, s34, 0x2000
	s_nop 0
	global_load_lds_dwordx4 v[220:221], off
	v_lshl_add_u64 v[220:221], v[228:229], 0, s[22:23]
	s_mov_b32 m0, s44
	s_nop 0
	global_load_lds_dwordx4 v[220:221], off
	v_lshl_add_u64 v[220:221], v[230:231], 0, s[22:23]
	s_mov_b32 m0, s45
	s_nop 0
	global_load_lds_dwordx4 v[220:221], off
	s_waitcnt vmcnt(8)
	s_waitcnt lgkmcnt(0)
	s_barrier
	s_setprio 1
	s_waitcnt lgkmcnt(0)
	v_mfma_f32_16x16x32_bf16 v[60:63], v[128:131], v[178:181], v[60:63]
	v_mfma_f32_16x16x32_bf16 v[56:59], v[136:139], v[178:181], v[56:59]
	v_mfma_f32_16x16x32_bf16 v[44:47], v[128:131], v[196:199], v[44:47]
	v_mfma_f32_16x16x32_bf16 v[40:43], v[136:139], v[196:199], v[40:43]
	v_mfma_f32_16x16x32_bf16 v[28:31], v[128:131], v[204:207], v[28:31]
	v_mfma_f32_16x16x32_bf16 v[24:27], v[136:139], v[204:207], v[24:27]
	v_mfma_f32_16x16x32_bf16 v[12:15], v[128:131], v[212:215], v[12:15]
	v_mfma_f32_16x16x32_bf16 v[8:11], v[136:139], v[212:215], v[8:11]
	v_mfma_f32_16x16x32_bf16 v[60:63], v[132:135], v[192:195], v[60:63]
	v_mfma_f32_16x16x32_bf16 v[56:59], v[140:143], v[192:195], v[56:59]
	v_mfma_f32_16x16x32_bf16 v[44:47], v[132:135], v[200:203], v[44:47]
	v_mfma_f32_16x16x32_bf16 v[40:43], v[140:143], v[200:203], v[40:43]
	v_mfma_f32_16x16x32_bf16 v[28:31], v[132:135], v[208:211], v[28:31]
	v_mfma_f32_16x16x32_bf16 v[24:27], v[140:143], v[208:211], v[24:27]
	v_mfma_f32_16x16x32_bf16 v[12:15], v[132:135], v[216:219], v[12:15]
	v_mfma_f32_16x16x32_bf16 v[8:11], v[140:143], v[216:219], v[8:11]
	s_setprio 0
	s_setprio 1
	v_mfma_f32_16x16x32_bf16 v[52:55], v[162:165], v[178:181], v[52:55]
	v_mfma_f32_16x16x32_bf16 v[48:51], v[170:173], v[178:181], v[48:51]
	v_mfma_f32_16x16x32_bf16 v[36:39], v[162:165], v[196:199], v[36:39]
	v_mfma_f32_16x16x32_bf16 v[32:35], v[170:173], v[196:199], v[32:35]
	v_mfma_f32_16x16x32_bf16 v[20:23], v[162:165], v[204:207], v[20:23]
	v_mfma_f32_16x16x32_bf16 v[16:19], v[170:173], v[204:207], v[16:19]
	v_mfma_f32_16x16x32_bf16 v[4:7], v[162:165], v[212:215], v[4:7]
	v_mfma_f32_16x16x32_bf16 v[0:3], v[170:173], v[212:215], v[0:3]
	v_mfma_f32_16x16x32_bf16 v[52:55], v[166:169], v[192:195], v[52:55]
	v_mfma_f32_16x16x32_bf16 v[48:51], v[174:177], v[192:195], v[48:51]
	v_mfma_f32_16x16x32_bf16 v[36:39], v[166:169], v[200:203], v[36:39]
	v_mfma_f32_16x16x32_bf16 v[32:35], v[174:177], v[200:203], v[32:35]
	v_mfma_f32_16x16x32_bf16 v[20:23], v[166:169], v[208:211], v[20:23]
	v_mfma_f32_16x16x32_bf16 v[16:19], v[174:177], v[208:211], v[16:19]
	v_mfma_f32_16x16x32_bf16 v[4:7], v[166:169], v[216:219], v[4:7]
	v_mfma_f32_16x16x32_bf16 v[0:3], v[174:177], v[216:219], v[0:3]
	s_setprio 0
	s_barrier
	s_add_u32 s30, s30, 0x100
	s_addc_u32 s31, s31, 0
	s_add_u32 s33, s33, 0x100
	s_addc_u32 s54, s54, 0
	s_cmp_ge_i32 s55, s46
	s_mov_b32 s34, s55
	s_cbranch_scc0 .LBB0_1468
